# GEMM epilogues: lane-permute packed outputs with ds_bpermute so adjacent lanes store contiguous 64B (P1/P3/P5/P6 incl f32 K/V); plus table-build and pool LDS read batching
# speedup vs baseline: 1.0198x; 1.0198x over previous
.LBB0_235:
	s_lshl_b32 s12, s12, 5
	v_mov_b32_e32 v133, v3
	s_and_b32 s17, s12, 0x60
	s_add_i32 m0, s35, 0x18000
	v_lshl_add_u64 v[6:7], v[6:7], 0, s[66:67]
	v_lshl_add_u64 v[14:15], s[56:57], 0, v[132:133]
	v_mov_b32_e32 v137, v3
	s_lshl_b32 s16, s1, 13
	s_lshl_b32 s33, s17, 7
	s_waitcnt vmcnt(2)
	s_barrier
	global_load_lds_dwordx4 v[6:7], off
	v_lshl_add_u64 v[4:5], v[4:5], 0, s[66:67]
	s_add_i32 m0, s35, 0x1a000
	s_add_i32 s63, s35, 0x8000
	s_add_i32 s64, s35, 0xa000
	v_lshl_add_u64 v[16:17], s[56:57], 0, v[136:137]
	global_load_lds_dwordx4 v[4:5], off
	v_lshl_add_u64 v[4:5], v[14:15], 0, s[66:67]
	s_mov_b32 m0, s63
	s_add_u32 s12, s88, 0x80080
	global_load_lds_dwordx4 v[4:5], off
	v_lshl_add_u64 v[4:5], v[16:17], 0, s[66:67]
	s_mov_b32 m0, s64
	s_addc_u32 s13, s89, 0
	global_load_lds_dwordx4 v[4:5], off
	s_add_i32 m0, s35, 0x1c000
	v_lshl_add_u64 v[4:5], s[12:13], 0, v[134:135]
	global_load_lds_dwordx4 v[4:5], off
	v_lshl_add_u64 v[4:5], s[12:13], 0, v[138:139]
	s_add_i32 m0, s35, 0x1e000
	s_cmpk_lt_u32 s0, 0x100
	global_load_lds_dwordx4 v[4:5], off
	v_lshrrev_b32_e32 v5, 1, v1
	v_and_b32_e32 v5, 24, v5
	v_and_b32_e32 v4, 15, v1
	v_lshlrev_b32_e32 v6, 1, v5
	v_lshlrev_b32_e32 v1, 2, v1
	v_bfe_u32 v140, v0, 2, 4
	v_lshl_or_b32 v140, s1, 6, v140
	v_bfe_u32 v231, v0, 2, 4
	v_and_b32_e32 v230, 3, v0
	v_lshl_or_b32 v231, v230, 4, v231
	v_lshlrev_b32_e32 v231, 2, v231
	v_lshl_or_b32 v4, v4, 6, v6
	v_and_b32_e32 v1, 32, v1
	v_bitop3_b32 v6, v4, s16, v1 bitop3:0xde
	v_bitop3_b32 v1, v4, s33, v1 bitop3:0xde
	v_lshlrev_b32_e32 v4, 15, v2
	v_and_b32_e32 v4, 0xffff0000, v4
	v_lshl_add_u32 v4, v8, 12, v4
	v_and_b32_e32 v2, 1, v2
	v_lshl_or_b32 v2, v2, 6, v4
	v_lshl_add_u32 v146, v9, 1, v2
	v_lshlrev_b32_e32 v2, 15, v10
	v_readlane_b32 s0, v252, 26
	v_and_b32_e32 v2, 0xffff0000, v2
	v_readlane_b32 s1, v252, 27
	s_waitcnt vmcnt(6)
	v_lshl_add_u32 v2, v11, 12, v2
	v_and_b32_e32 v4, 1, v10
	s_mov_b32 s50, s0
	v_readlane_b32 s0, v252, 24
	v_ashrrev_i32_e32 v141, 31, v140
	v_lshl_or_b32 v2, v4, 6, v2
	v_readlane_b32 s1, v252, 25
	s_mov_b32 s55, 32
	s_cselect_b64 s[58:59], -1, 0
	v_and_b32_e32 v142, 3, v0
	v_lshl_or_b32 v142, v142, 3, s17
	v_lshlrev_b64 v[144:145], 10, v[140:141]
	v_mov_b32_e32 v147, v3
	v_lshl_add_u32 v148, v12, 1, v2
	v_mov_b32_e32 v149, v3
	s_mov_b32 s51, 0
	v_add_u32_e32 v141, 0, v6
	s_mov_b32 s54, s0
	s_mov_b64 s[0:1], s[56:57]
	s_mov_b32 s13, 0
	s_barrier
	s_branch .LBB0_238

.LBB0_251:
	v_sub_co_u32_e64 v2, vcc, s51, 1
	s_lshl_b32 s51, s54, 8
	s_add_i32 s54, s51, 0xffffe000
	s_and_b64 s[0:1], vcc, exec
	v_lshlrev_b64 v[152:153], 23, v[2:3]
	s_cselect_b32 s0, s51, s54
	v_mov_b32_e32 v143, s19
	v_lshl_add_u64 v[152:153], s[20:21], 0, v[152:153]
	v_add_u32_e32 v2, s0, v140
	s_cselect_b32 s0, 0, 0xfffff800
	v_cndmask_b32_e32 v153, v153, v143, vcc
	v_or_b32_e32 v143, s0, v142
	v_lshl_add_u32 v154, s50, 8, v143
	s_movk_i32 s0, 0xc00
	v_mov_b32_e32 v143, s18
	s_cselect_b32 s50, s0, 0x400
	v_cndmask_b32_e32 v152, v152, v143, vcc
	v_ashrrev_i32_e32 v155, 31, v154
	v_lshl_add_u64 v[152:153], v[154:155], 1, v[152:153]
	v_mad_i64_i32 v[154:155], s[54:55], s50, v2, 0
	v_cmp_ne_u64_e64 s[0:1], 0, v[150:151]
	v_lshl_add_u64 v[154:155], v[154:155], 1, v[152:153]
	v_cvt_pk_bf16_f32 v156, v128, v129
	v_cvt_pk_bf16_f32 v157, v130, v131
	v_cvt_pk_bf16_f32 v158, v124, v125
	v_cvt_pk_bf16_f32 v159, v126, v127
	ds_bpermute_b32 v156, v231, v156
	ds_bpermute_b32 v157, v231, v157
	ds_bpermute_b32 v158, v231, v158
	ds_bpermute_b32 v159, v231, v159
	s_waitcnt lgkmcnt(0)
	global_store_dwordx4 v[154:155], v[156:159], off
	s_and_saveexec_b64 s[88:89], s[0:1]
	s_cbranch_execz .LBB0_253
	ds_bpermute_b32 v128, v231, v128
	ds_bpermute_b32 v129, v231, v129
	ds_bpermute_b32 v130, v231, v130
	ds_bpermute_b32 v131, v231, v131
	s_waitcnt lgkmcnt(0)
	global_store_dwordx4 v[150:151], v[128:131], off
	ds_bpermute_b32 v124, v231, v124
	ds_bpermute_b32 v125, v231, v125
	ds_bpermute_b32 v126, v231, v126
	ds_bpermute_b32 v127, v231, v127
	s_waitcnt lgkmcnt(0)
	global_store_dwordx4 v[150:151], v[124:127], off offset:16
.LBB0_253:
	s_or_b64 exec, exec, s[88:89]
	s_nop 0
	v_cvt_pk_bf16_f32 v124, v120, v121
	v_cvt_pk_bf16_f32 v125, v122, v123
	v_cvt_pk_bf16_f32 v126, v112, v113
	v_cvt_pk_bf16_f32 v127, v114, v115
	ds_bpermute_b32 v124, v231, v124
	ds_bpermute_b32 v125, v231, v125
	ds_bpermute_b32 v126, v231, v126
	ds_bpermute_b32 v127, v231, v127
	s_waitcnt lgkmcnt(0)
	global_store_dwordx4 v[154:155], v[124:127], off offset:256
	s_and_saveexec_b64 s[88:89], s[0:1]
	s_cbranch_execz .LBB0_255
	ds_bpermute_b32 v120, v231, v120
	ds_bpermute_b32 v121, v231, v121
	ds_bpermute_b32 v122, v231, v122
	ds_bpermute_b32 v123, v231, v123
	s_waitcnt lgkmcnt(0)
	global_store_dwordx4 v[150:151], v[120:123], off offset:512
	ds_bpermute_b32 v112, v231, v112
	ds_bpermute_b32 v113, v231, v113
	ds_bpermute_b32 v114, v231, v114
	ds_bpermute_b32 v115, v231, v115
	s_waitcnt lgkmcnt(0)
	global_store_dwordx4 v[150:151], v[112:115], off offset:528
.LBB0_255:
	s_or_b64 exec, exec, s[88:89]
	s_nop 0
	v_or_b32_e32 v112, 16, v2
	v_mad_i64_i32 v[112:113], s[54:55], s50, v112, 0
	v_lshl_add_u64 v[112:113], v[112:113], 1, v[152:153]
	v_cvt_pk_bf16_f32 v120, v116, v117
	v_cvt_pk_bf16_f32 v121, v118, v119
	v_cvt_pk_bf16_f32 v122, v108, v109
	v_cvt_pk_bf16_f32 v123, v110, v111
	ds_bpermute_b32 v120, v231, v120
	ds_bpermute_b32 v121, v231, v121
	ds_bpermute_b32 v122, v231, v122
	ds_bpermute_b32 v123, v231, v123
	s_waitcnt lgkmcnt(0)
	global_store_dwordx4 v[112:113], v[120:123], off
	s_and_saveexec_b64 s[88:89], s[0:1]
	s_cbranch_execz .LBB0_257
	v_add_co_u32_e32 v114, vcc, 0x4000, v150
	s_nop 1
	v_addc_co_u32_e32 v115, vcc, 0, v151, vcc
	ds_bpermute_b32 v116, v231, v116
	ds_bpermute_b32 v117, v231, v117
	ds_bpermute_b32 v118, v231, v118
	ds_bpermute_b32 v119, v231, v119
	s_waitcnt lgkmcnt(0)
	global_store_dwordx4 v[114:115], v[116:119], off
	ds_bpermute_b32 v108, v231, v108
	ds_bpermute_b32 v109, v231, v109
	ds_bpermute_b32 v110, v231, v110
	ds_bpermute_b32 v111, v231, v111
	s_waitcnt lgkmcnt(0)
	global_store_dwordx4 v[114:115], v[108:111], off offset:16
.LBB0_257:
	s_or_b64 exec, exec, s[88:89]
	s_nop 0
	v_cvt_pk_bf16_f32 v108, v104, v105
	v_cvt_pk_bf16_f32 v109, v106, v107
	v_cvt_pk_bf16_f32 v110, v96, v97
	v_cvt_pk_bf16_f32 v111, v98, v99
	ds_bpermute_b32 v108, v231, v108
	ds_bpermute_b32 v109, v231, v109
	ds_bpermute_b32 v110, v231, v110
	ds_bpermute_b32 v111, v231, v111
	s_waitcnt lgkmcnt(0)
	global_store_dwordx4 v[112:113], v[108:111], off offset:256
	s_and_saveexec_b64 s[88:89], s[0:1]
	s_cbranch_execz .LBB0_259
	v_add_co_u32_e32 v108, vcc, 0x4000, v150
	s_nop 1
	v_addc_co_u32_e32 v109, vcc, 0, v151, vcc
	ds_bpermute_b32 v104, v231, v104
	ds_bpermute_b32 v105, v231, v105
	ds_bpermute_b32 v106, v231, v106
	ds_bpermute_b32 v107, v231, v107
	s_waitcnt lgkmcnt(0)
	global_store_dwordx4 v[108:109], v[104:107], off offset:512
	ds_bpermute_b32 v96, v231, v96
	ds_bpermute_b32 v97, v231, v97
	ds_bpermute_b32 v98, v231, v98
	ds_bpermute_b32 v99, v231, v99
	s_waitcnt lgkmcnt(0)
	global_store_dwordx4 v[108:109], v[96:99], off offset:528
.LBB0_259:
	s_or_b64 exec, exec, s[88:89]
	s_nop 0
	v_or_b32_e32 v96, 32, v2
	v_mad_i64_i32 v[96:97], s[54:55], s50, v96, 0
	v_lshl_add_u64 v[96:97], v[96:97], 1, v[152:153]
	v_cvt_pk_bf16_f32 v104, v100, v101
	v_cvt_pk_bf16_f32 v105, v102, v103
	v_cvt_pk_bf16_f32 v106, v92, v93
	v_cvt_pk_bf16_f32 v107, v94, v95
	ds_bpermute_b32 v104, v231, v104
	ds_bpermute_b32 v105, v231, v105
	ds_bpermute_b32 v106, v231, v106
	ds_bpermute_b32 v107, v231, v107
	s_waitcnt lgkmcnt(0)
	global_store_dwordx4 v[96:97], v[104:107], off
	s_and_saveexec_b64 s[88:89], s[0:1]
	s_cbranch_execz .LBB0_261
	v_add_co_u32_e32 v98, vcc, 0x8000, v150
	s_nop 1
	v_addc_co_u32_e32 v99, vcc, 0, v151, vcc
	ds_bpermute_b32 v100, v231, v100
	ds_bpermute_b32 v101, v231, v101
	ds_bpermute_b32 v102, v231, v102
	ds_bpermute_b32 v103, v231, v103
	s_waitcnt lgkmcnt(0)
	global_store_dwordx4 v[98:99], v[100:103], off
	ds_bpermute_b32 v92, v231, v92
	ds_bpermute_b32 v93, v231, v93
	ds_bpermute_b32 v94, v231, v94
	ds_bpermute_b32 v95, v231, v95
	s_waitcnt lgkmcnt(0)
	global_store_dwordx4 v[98:99], v[92:95], off offset:16
.LBB0_261:
	s_or_b64 exec, exec, s[88:89]
	s_nop 0
	v_cvt_pk_bf16_f32 v92, v88, v89
	v_cvt_pk_bf16_f32 v93, v90, v91
	v_cvt_pk_bf16_f32 v94, v80, v81
	v_cvt_pk_bf16_f32 v95, v82, v83
	ds_bpermute_b32 v92, v231, v92
	ds_bpermute_b32 v93, v231, v93
	ds_bpermute_b32 v94, v231, v94
	ds_bpermute_b32 v95, v231, v95
	s_waitcnt lgkmcnt(0)
	global_store_dwordx4 v[96:97], v[92:95], off offset:256
	s_and_saveexec_b64 s[88:89], s[0:1]
	s_cbranch_execz .LBB0_263
	v_add_co_u32_e32 v92, vcc, 0x8000, v150
	s_nop 1
	v_addc_co_u32_e32 v93, vcc, 0, v151, vcc
	ds_bpermute_b32 v88, v231, v88
	ds_bpermute_b32 v89, v231, v89
	ds_bpermute_b32 v90, v231, v90
	ds_bpermute_b32 v91, v231, v91
	s_waitcnt lgkmcnt(0)
	global_store_dwordx4 v[92:93], v[88:91], off offset:512
	ds_bpermute_b32 v80, v231, v80
	ds_bpermute_b32 v81, v231, v81
	ds_bpermute_b32 v82, v231, v82
	ds_bpermute_b32 v83, v231, v83
	s_waitcnt lgkmcnt(0)
	global_store_dwordx4 v[92:93], v[80:83], off offset:528
.LBB0_263:
	s_or_b64 exec, exec, s[88:89]
	s_nop 0
	v_or_b32_e32 v80, 48, v2
	v_mad_i64_i32 v[80:81], s[54:55], s50, v80, 0
	v_lshl_add_u64 v[80:81], v[80:81], 1, v[152:153]
	v_cvt_pk_bf16_f32 v88, v84, v85
	v_cvt_pk_bf16_f32 v89, v86, v87
	v_cvt_pk_bf16_f32 v90, v76, v77
	v_cvt_pk_bf16_f32 v91, v78, v79
	ds_bpermute_b32 v88, v231, v88
	ds_bpermute_b32 v89, v231, v89
	ds_bpermute_b32 v90, v231, v90
	ds_bpermute_b32 v91, v231, v91
	s_waitcnt lgkmcnt(0)
	global_store_dwordx4 v[80:81], v[88:91], off
	s_and_saveexec_b64 s[88:89], s[0:1]
	s_cbranch_execz .LBB0_265
	v_add_co_u32_e32 v82, vcc, 0xc000, v150
	s_nop 1
	v_addc_co_u32_e32 v83, vcc, 0, v151, vcc
	ds_bpermute_b32 v84, v231, v84
	ds_bpermute_b32 v85, v231, v85
	ds_bpermute_b32 v86, v231, v86
	ds_bpermute_b32 v87, v231, v87
	s_waitcnt lgkmcnt(0)
	global_store_dwordx4 v[82:83], v[84:87], off
	ds_bpermute_b32 v76, v231, v76
	ds_bpermute_b32 v77, v231, v77
	ds_bpermute_b32 v78, v231, v78
	ds_bpermute_b32 v79, v231, v79
	s_waitcnt lgkmcnt(0)
	global_store_dwordx4 v[82:83], v[76:79], off offset:16
.LBB0_265:
	s_or_b64 exec, exec, s[88:89]
	s_nop 0
	v_cvt_pk_bf16_f32 v76, v72, v73
	v_cvt_pk_bf16_f32 v77, v74, v75
	v_cvt_pk_bf16_f32 v78, v68, v69
	v_cvt_pk_bf16_f32 v79, v70, v71
	ds_bpermute_b32 v76, v231, v76
	ds_bpermute_b32 v77, v231, v77
	ds_bpermute_b32 v78, v231, v78
	ds_bpermute_b32 v79, v231, v79
	s_waitcnt lgkmcnt(0)
	global_store_dwordx4 v[80:81], v[76:79], off offset:256
	s_and_saveexec_b64 s[88:89], s[0:1]
	s_cbranch_execz .LBB0_267
	v_add_co_u32_e32 v76, vcc, 0xc000, v150
	s_nop 1
	v_addc_co_u32_e32 v77, vcc, 0, v151, vcc
	ds_bpermute_b32 v72, v231, v72
	ds_bpermute_b32 v73, v231, v73
	ds_bpermute_b32 v74, v231, v74
	ds_bpermute_b32 v75, v231, v75
	s_waitcnt lgkmcnt(0)
	global_store_dwordx4 v[76:77], v[72:75], off offset:512
	ds_bpermute_b32 v68, v231, v68
	ds_bpermute_b32 v69, v231, v69
	ds_bpermute_b32 v70, v231, v70
	ds_bpermute_b32 v71, v231, v71
	s_waitcnt lgkmcnt(0)
	global_store_dwordx4 v[76:77], v[68:71], off offset:528
.LBB0_267:
	s_or_b64 exec, exec, s[88:89]
	s_nop 0
	v_add_u32_e32 v68, 0x80, v2
	v_mad_i64_i32 v[68:69], s[54:55], s50, v68, 0
	v_lshl_add_u64 v[68:69], v[68:69], 1, v[152:153]
	v_cvt_pk_bf16_f32 v70, v64, v65
	v_cvt_pk_bf16_f32 v71, v66, v67
	v_cvt_pk_bf16_f32 v72, v60, v61
	v_cvt_pk_bf16_f32 v73, v62, v63
	ds_bpermute_b32 v70, v231, v70
	ds_bpermute_b32 v71, v231, v71
	ds_bpermute_b32 v72, v231, v72
	ds_bpermute_b32 v73, v231, v73
	s_waitcnt lgkmcnt(0)
	global_store_dwordx4 v[68:69], v[70:73], off
	s_and_saveexec_b64 s[88:89], s[0:1]
	s_cbranch_execz .LBB0_269
	v_add_co_u32_e32 v70, vcc, 0x20000, v150
	s_nop 1
	v_addc_co_u32_e32 v71, vcc, 0, v151, vcc
	ds_bpermute_b32 v64, v231, v64
	ds_bpermute_b32 v65, v231, v65
	ds_bpermute_b32 v66, v231, v66
	ds_bpermute_b32 v67, v231, v67
	s_waitcnt lgkmcnt(0)
	global_store_dwordx4 v[70:71], v[64:67], off
	ds_bpermute_b32 v60, v231, v60
	ds_bpermute_b32 v61, v231, v61
	ds_bpermute_b32 v62, v231, v62
	ds_bpermute_b32 v63, v231, v63
	s_waitcnt lgkmcnt(0)
	global_store_dwordx4 v[70:71], v[60:63], off offset:16
.LBB0_269:
	s_or_b64 exec, exec, s[88:89]
	s_nop 0
	v_cvt_pk_bf16_f32 v60, v56, v57
	v_cvt_pk_bf16_f32 v61, v58, v59
	v_cvt_pk_bf16_f32 v62, v48, v49
	v_cvt_pk_bf16_f32 v63, v50, v51
	ds_bpermute_b32 v60, v231, v60
	ds_bpermute_b32 v61, v231, v61
	ds_bpermute_b32 v62, v231, v62
	ds_bpermute_b32 v63, v231, v63
	s_waitcnt lgkmcnt(0)
	global_store_dwordx4 v[68:69], v[60:63], off offset:256
	s_and_saveexec_b64 s[88:89], s[0:1]
	s_cbranch_execz .LBB0_271
	v_add_co_u32_e32 v60, vcc, 0x20000, v150
	s_nop 1
	v_addc_co_u32_e32 v61, vcc, 0, v151, vcc
	ds_bpermute_b32 v56, v231, v56
	ds_bpermute_b32 v57, v231, v57
	ds_bpermute_b32 v58, v231, v58
	ds_bpermute_b32 v59, v231, v59
	s_waitcnt lgkmcnt(0)
	global_store_dwordx4 v[60:61], v[56:59], off offset:512
	ds_bpermute_b32 v48, v231, v48
	ds_bpermute_b32 v49, v231, v49
	ds_bpermute_b32 v50, v231, v50
	ds_bpermute_b32 v51, v231, v51
	s_waitcnt lgkmcnt(0)
	global_store_dwordx4 v[60:61], v[48:51], off offset:528
.LBB0_271:
	s_or_b64 exec, exec, s[88:89]
	s_nop 0
	v_add_u32_e32 v48, 0x90, v2
	v_mad_i64_i32 v[48:49], s[54:55], s50, v48, 0
	v_lshl_add_u64 v[48:49], v[48:49], 1, v[152:153]
	v_cvt_pk_bf16_f32 v56, v52, v53
	v_cvt_pk_bf16_f32 v57, v54, v55
	v_cvt_pk_bf16_f32 v58, v44, v45
	v_cvt_pk_bf16_f32 v59, v46, v47
	ds_bpermute_b32 v56, v231, v56
	ds_bpermute_b32 v57, v231, v57
	ds_bpermute_b32 v58, v231, v58
	ds_bpermute_b32 v59, v231, v59
	s_waitcnt lgkmcnt(0)
	global_store_dwordx4 v[48:49], v[56:59], off
	s_and_saveexec_b64 s[88:89], s[0:1]
	s_cbranch_execz .LBB0_273
	v_add_co_u32_e32 v50, vcc, 0x24000, v150
	s_nop 1
	v_addc_co_u32_e32 v51, vcc, 0, v151, vcc
	ds_bpermute_b32 v52, v231, v52
	ds_bpermute_b32 v53, v231, v53
	ds_bpermute_b32 v54, v231, v54
	ds_bpermute_b32 v55, v231, v55
	s_waitcnt lgkmcnt(0)
	global_store_dwordx4 v[50:51], v[52:55], off
	ds_bpermute_b32 v44, v231, v44
	ds_bpermute_b32 v45, v231, v45
	ds_bpermute_b32 v46, v231, v46
	ds_bpermute_b32 v47, v231, v47
	s_waitcnt lgkmcnt(0)
	global_store_dwordx4 v[50:51], v[44:47], off offset:16
.LBB0_273:
	s_or_b64 exec, exec, s[88:89]
	s_nop 0
	v_cvt_pk_bf16_f32 v44, v40, v41
	v_cvt_pk_bf16_f32 v45, v42, v43
	v_cvt_pk_bf16_f32 v46, v32, v33
	v_cvt_pk_bf16_f32 v47, v34, v35
	ds_bpermute_b32 v44, v231, v44
	ds_bpermute_b32 v45, v231, v45
	ds_bpermute_b32 v46, v231, v46
	ds_bpermute_b32 v47, v231, v47
	s_waitcnt lgkmcnt(0)
	global_store_dwordx4 v[48:49], v[44:47], off offset:256
	s_and_saveexec_b64 s[88:89], s[0:1]
	s_cbranch_execz .LBB0_275
	v_add_co_u32_e32 v44, vcc, 0x24000, v150
	s_nop 1
	v_addc_co_u32_e32 v45, vcc, 0, v151, vcc
	ds_bpermute_b32 v40, v231, v40
	ds_bpermute_b32 v41, v231, v41
	ds_bpermute_b32 v42, v231, v42
	ds_bpermute_b32 v43, v231, v43
	s_waitcnt lgkmcnt(0)
	global_store_dwordx4 v[44:45], v[40:43], off offset:512
	ds_bpermute_b32 v32, v231, v32
	ds_bpermute_b32 v33, v231, v33
	ds_bpermute_b32 v34, v231, v34
	ds_bpermute_b32 v35, v231, v35
	s_waitcnt lgkmcnt(0)
	global_store_dwordx4 v[44:45], v[32:35], off offset:528
.LBB0_275:
	s_or_b64 exec, exec, s[88:89]
	s_nop 0
	v_add_u32_e32 v32, 0xa0, v2
	v_mad_i64_i32 v[32:33], s[54:55], s50, v32, 0
	v_lshl_add_u64 v[32:33], v[32:33], 1, v[152:153]
	v_cvt_pk_bf16_f32 v40, v36, v37
	v_cvt_pk_bf16_f32 v41, v38, v39
	v_cvt_pk_bf16_f32 v42, v28, v29
	v_cvt_pk_bf16_f32 v43, v30, v31
	ds_bpermute_b32 v40, v231, v40
	ds_bpermute_b32 v41, v231, v41
	ds_bpermute_b32 v42, v231, v42
	ds_bpermute_b32 v43, v231, v43
	s_waitcnt lgkmcnt(0)
	global_store_dwordx4 v[32:33], v[40:43], off
	s_and_saveexec_b64 s[88:89], s[0:1]
	s_cbranch_execz .LBB0_277
	v_add_co_u32_e32 v34, vcc, 0x28000, v150
	s_nop 1
	v_addc_co_u32_e32 v35, vcc, 0, v151, vcc
	ds_bpermute_b32 v36, v231, v36
	ds_bpermute_b32 v37, v231, v37
	ds_bpermute_b32 v38, v231, v38
	ds_bpermute_b32 v39, v231, v39
	s_waitcnt lgkmcnt(0)
	global_store_dwordx4 v[34:35], v[36:39], off
	ds_bpermute_b32 v28, v231, v28
	ds_bpermute_b32 v29, v231, v29
	ds_bpermute_b32 v30, v231, v30
	ds_bpermute_b32 v31, v231, v31
	s_waitcnt lgkmcnt(0)
	global_store_dwordx4 v[34:35], v[28:31], off offset:16
.LBB0_277:
	s_or_b64 exec, exec, s[88:89]
	s_nop 0
	v_cvt_pk_bf16_f32 v28, v24, v25
	v_cvt_pk_bf16_f32 v29, v26, v27
	v_cvt_pk_bf16_f32 v30, v16, v17
	v_cvt_pk_bf16_f32 v31, v18, v19
	ds_bpermute_b32 v28, v231, v28
	ds_bpermute_b32 v29, v231, v29
	ds_bpermute_b32 v30, v231, v30
	ds_bpermute_b32 v31, v231, v31
	s_waitcnt lgkmcnt(0)
	global_store_dwordx4 v[32:33], v[28:31], off offset:256
	s_and_saveexec_b64 s[88:89], s[0:1]
	s_cbranch_execz .LBB0_279
	v_add_co_u32_e32 v28, vcc, 0x28000, v150
	s_nop 1
	v_addc_co_u32_e32 v29, vcc, 0, v151, vcc
	ds_bpermute_b32 v24, v231, v24
	ds_bpermute_b32 v25, v231, v25
	ds_bpermute_b32 v26, v231, v26
	ds_bpermute_b32 v27, v231, v27
	s_waitcnt lgkmcnt(0)
	global_store_dwordx4 v[28:29], v[24:27], off offset:512
	ds_bpermute_b32 v16, v231, v16
	ds_bpermute_b32 v17, v231, v17
	ds_bpermute_b32 v18, v231, v18
	ds_bpermute_b32 v19, v231, v19
	s_waitcnt lgkmcnt(0)
	global_store_dwordx4 v[28:29], v[16:19], off offset:528
.LBB0_279:
	s_or_b64 exec, exec, s[88:89]
	v_add_u32_e32 v2, 0xb0, v2
	v_mad_i64_i32 v[16:17], s[50:51], s50, v2, 0
	v_lshl_add_u64 v[16:17], v[16:17], 1, v[152:153]
	v_cvt_pk_bf16_f32 v24, v20, v21
	v_cvt_pk_bf16_f32 v25, v22, v23
	v_cvt_pk_bf16_f32 v26, v12, v13
	v_cvt_pk_bf16_f32 v27, v14, v15
	ds_bpermute_b32 v24, v231, v24
	ds_bpermute_b32 v25, v231, v25
	ds_bpermute_b32 v26, v231, v26
	ds_bpermute_b32 v27, v231, v27
	s_waitcnt lgkmcnt(0)
	global_store_dwordx4 v[16:17], v[24:27], off
	s_and_saveexec_b64 s[88:89], s[0:1]
	s_cbranch_execz .LBB0_281
	v_add_co_u32_e32 v18, vcc, 0x2c000, v150
	s_nop 1
	v_addc_co_u32_e32 v19, vcc, 0, v151, vcc
	ds_bpermute_b32 v20, v231, v20
	ds_bpermute_b32 v21, v231, v21
	ds_bpermute_b32 v22, v231, v22
	ds_bpermute_b32 v23, v231, v23
	s_waitcnt lgkmcnt(0)
	global_store_dwordx4 v[18:19], v[20:23], off
	ds_bpermute_b32 v12, v231, v12
	ds_bpermute_b32 v13, v231, v13
	ds_bpermute_b32 v14, v231, v14
	ds_bpermute_b32 v15, v231, v15
	s_waitcnt lgkmcnt(0)
	global_store_dwordx4 v[18:19], v[12:15], off offset:16
.LBB0_281:
	s_or_b64 exec, exec, s[88:89]
	s_nop 0
	v_cvt_pk_bf16_f32 v12, v8, v9
	v_cvt_pk_bf16_f32 v13, v10, v11
	v_cvt_pk_bf16_f32 v14, v4, v5
	v_cvt_pk_bf16_f32 v15, v6, v7
	ds_bpermute_b32 v12, v231, v12
	ds_bpermute_b32 v13, v231, v13
	ds_bpermute_b32 v14, v231, v14
	ds_bpermute_b32 v15, v231, v15
	s_waitcnt lgkmcnt(0)
	global_store_dwordx4 v[16:17], v[12:15], off offset:256
	s_and_saveexec_b64 s[88:89], s[0:1]
	s_cbranch_execz .LBB0_283
	v_add_co_u32_e32 v12, vcc, 0x2c000, v150
	s_nop 1
	v_addc_co_u32_e32 v13, vcc, 0, v151, vcc
	ds_bpermute_b32 v8, v231, v8
	ds_bpermute_b32 v9, v231, v9
	ds_bpermute_b32 v10, v231, v10
	ds_bpermute_b32 v11, v231, v11
	s_waitcnt lgkmcnt(0)
	global_store_dwordx4 v[12:13], v[8:11], off offset:512
	ds_bpermute_b32 v4, v231, v4
	ds_bpermute_b32 v5, v231, v5
	ds_bpermute_b32 v6, v231, v6
	ds_bpermute_b32 v7, v231, v7
	s_waitcnt lgkmcnt(0)
	global_store_dwordx4 v[12:13], v[4:7], off offset:528

.LBB0_390:
	global_load_dwordx4 v[4:7], v[4:5], off
	s_nop 0
	global_load_dwordx4 v[8:11], v[8:9], off
	s_nop 0
	global_load_dwordx4 v[12:15], v[12:13], off
	s_nop 0
	global_load_dwordx4 v[16:19], v[16:17], off
	s_nop 0
	global_load_dwordx4 v[20:23], v[20:21], off
	s_nop 0
	global_load_dwordx4 v[24:27], v[24:25], off
	s_nop 0
	global_load_dwordx4 v[28:31], v[28:29], off
	s_nop 0
	global_load_dwordx4 v[32:35], v[32:33], off
	s_nop 0
	global_load_dwordx4 v[36:39], v[36:37], off
	s_nop 0
	global_load_dwordx4 v[40:43], v[40:41], off
	s_nop 0
	global_load_dwordx4 v[44:47], v[44:45], off
	s_nop 0
	global_load_dwordx4 v[48:51], v[48:49], off
	s_nop 0
	global_load_dwordx4 v[52:55], v[52:53], off
	s_nop 0
	global_load_dwordx4 v[56:59], v[56:57], off
	s_nop 0
	global_load_dwordx4 v[60:63], v[60:61], off
	s_nop 0
	global_load_dwordx4 v[64:67], v[64:65], off
	v_cmp_lt_i32_e32 vcc, 0, v180
	s_mov_b64 s[84:85], 0
	s_mov_b64 s[0:1], 0
	s_waitcnt lgkmcnt(0)
	s_barrier
	s_and_saveexec_b64 s[12:13], vcc
	s_xor_b64 s[86:87], exec, s[12:13]
	s_cbranch_execz .LBB0_398
	v_cmp_lt_i32_e32 vcc, 1, v180
	s_mov_b64 s[90:91], 0
	s_and_saveexec_b64 s[0:1], vcc
	s_xor_b64 s[88:89], exec, s[0:1]
	s_cbranch_execz .LBB0_395
	v_cmp_eq_u32_e32 vcc, 2, v180
	s_mov_b64 s[0:1], -1
	s_and_saveexec_b64 s[90:91], vcc
	s_cbranch_execz .LBB0_394
	v_lshl_add_u32 v92, v96, 1, 0
	ds_read_u16 v140, v92 offset:4096
	ds_read_u16 v137, v92 offset:5120
	ds_read_u16 v136, v92 offset:6144
	ds_read_u16 v135, v92 offset:7168
	ds_read_u16 v134, v92 offset:8192
	ds_read_u16 v133, v92 offset:9216
	ds_read_u16 v132, v92 offset:10240
	ds_read_u16 v131, v92 offset:11264
	ds_read_u16 v130, v92 offset:12288
	ds_read_u16 v129, v92 offset:13312
	ds_read_u16 v128, v92 offset:14336
	ds_read_u16 v127, v92 offset:15360
	ds_read_u16 v126, v92 offset:16384
	ds_read_u16 v125, v92 offset:17408
	ds_read_u16 v124, v92 offset:18432
	ds_read_u16 v123, v92 offset:19456
	ds_read_u16 v122, v92 offset:20480
	ds_read_u16 v95, v92 offset:21504
	ds_read_u16 v94, v92 offset:22528
	ds_read_u16 v93, v92 offset:23552
	ds_read_u16 v91, v92 offset:24576
	ds_read_u16 v87, v92 offset:25600
	ds_read_u16 v79, v92 offset:26624
	ds_read_u16 v84, v92 offset:27648
	ds_read_u16 v78, v92 offset:35840
	ds_read_u16 v83, v92 offset:28672
	ds_read_u16 v77, v92 offset:36864
	ds_read_u16 v82, v92 offset:29696
	ds_read_u16 v76, v92 offset:37888
	ds_read_u16 v81, v92 offset:30720
	ds_read_u16 v75, v92 offset:38912
	ds_read_u16 v80, v92 offset:31744
	ds_read_u16 v85, v92 offset:32768
	ds_read_u16 v89, v92 offset:40960
	ds_read_u16 v86, v92 offset:33792
	ds_read_u16 v90, v92 offset:41984
	s_cmp_gt_i32 s62, 3
	s_cselect_b64 s[0:1], -1, 0
	s_add_i32 s63, s62, 35
	s_cmp_le_i32 s63, s35
	s_waitcnt lgkmcnt(0)
	v_lshlrev_b32_e32 v140, 16, v140
	s_cselect_b64 s[12:13], -1, 0
	s_ashr_i32 s75, s74, 31
	s_and_b64 vcc, s[0:1], s[12:13]
	s_lshl_b64 s[0:1], s[74:75], 12
	s_waitcnt lgkmcnt(0)
	v_lshlrev_b32_e32 v137, 16, v137
	s_add_u32 s0, s94, s0
	s_addc_u32 s1, s95, s1
	v_ashrrev_i32_e32 v97, 31, v96
	v_lshl_add_u64 v[72:73], v[96:97], 1, s[0:1]
	s_waitcnt lgkmcnt(0)
	v_lshlrev_b32_e32 v136, 16, v136
	s_mov_b64 s[0:1], 0x1ec00800
	s_waitcnt lgkmcnt(0)
	v_lshlrev_b32_e32 v135, 16, v135
	s_waitcnt lgkmcnt(0)
	v_lshlrev_b32_e32 v134, 16, v134
	s_waitcnt lgkmcnt(0)
	v_lshlrev_b32_e32 v133, 16, v133
	s_waitcnt lgkmcnt(0)
	v_lshlrev_b32_e32 v132, 16, v132
	s_waitcnt lgkmcnt(0)
	v_lshlrev_b32_e32 v131, 16, v131
	s_waitcnt lgkmcnt(0)
	v_lshlrev_b32_e32 v130, 16, v130
	s_waitcnt lgkmcnt(0)
	v_lshlrev_b32_e32 v129, 16, v129
	s_waitcnt lgkmcnt(0)
	v_lshlrev_b32_e32 v128, 16, v128
	s_waitcnt lgkmcnt(0)
	v_lshlrev_b32_e32 v127, 16, v127
	s_waitcnt lgkmcnt(0)
	v_lshlrev_b32_e32 v126, 16, v126
	s_waitcnt lgkmcnt(0)
	v_lshlrev_b32_e32 v125, 16, v125
	s_waitcnt lgkmcnt(0)
	v_lshlrev_b32_e32 v124, 16, v124
	s_waitcnt lgkmcnt(0)
	v_lshlrev_b32_e32 v123, 16, v123
	s_waitcnt lgkmcnt(0)
	v_lshlrev_b32_e32 v122, 16, v122
	s_waitcnt lgkmcnt(0)
	v_lshlrev_b32_e32 v95, 16, v95
	s_waitcnt lgkmcnt(0)
	v_lshlrev_b32_e32 v94, 16, v94
	s_waitcnt lgkmcnt(0)
	v_lshlrev_b32_e32 v93, 16, v93
	s_waitcnt lgkmcnt(0)
	v_lshlrev_b32_e32 v91, 16, v91
	s_waitcnt lgkmcnt(0)
	v_lshlrev_b32_e32 v87, 16, v87
	s_waitcnt lgkmcnt(0)
	v_lshlrev_b32_e32 v79, 16, v79
	s_waitcnt lgkmcnt(0)
	v_lshlrev_b32_e32 v84, 16, v84
	s_waitcnt lgkmcnt(0)
	v_lshlrev_b32_e32 v78, 16, v78
	s_waitcnt lgkmcnt(0)
	v_lshlrev_b32_e32 v83, 16, v83
	s_waitcnt lgkmcnt(0)
	v_lshlrev_b32_e32 v77, 16, v77
	s_waitcnt lgkmcnt(0)
	v_lshlrev_b32_e32 v82, 16, v82
	s_waitcnt lgkmcnt(0)
	v_lshlrev_b32_e32 v76, 16, v76
	s_waitcnt lgkmcnt(0)
	v_lshlrev_b32_e32 v81, 16, v81
	s_waitcnt lgkmcnt(0)
	v_lshlrev_b32_e32 v75, 16, v75
	ds_read_u16 v69, v92 offset:39936
	s_waitcnt lgkmcnt(0)
	v_lshlrev_b32_e32 v80, 16, v80
	s_waitcnt lgkmcnt(0)
	v_lshlrev_b32_e32 v69, 16, v69
	s_waitcnt lgkmcnt(0)
	v_lshlrev_b32_e32 v85, 16, v85
	s_waitcnt lgkmcnt(0)
	v_lshlrev_b32_e32 v89, 16, v89
	v_sub_f32_e32 v89, v89, v85
	s_waitcnt lgkmcnt(0)
	v_lshlrev_b32_e32 v86, 16, v86
	v_add_f32_e32 v70, 0, v140
	v_add_f32_e32 v70, v70, v137
	v_add_f32_e32 v70, v70, v136
	v_add_f32_e32 v70, v70, v135
	v_add_f32_e32 v70, v70, v134
	v_add_f32_e32 v70, v70, v133
	v_add_f32_e32 v70, v70, v132
	s_waitcnt lgkmcnt(0)
	v_lshlrev_b32_e32 v90, 16, v90
	v_add_f32_e32 v141, v70, v131
	v_lshl_add_u64 v[70:71], v[72:73], 0, s[0:1]
	s_or_b32 s1, s62, 4
	s_max_i32 s0, s62, 4
	s_min_i32 s1, s1, s35
	s_sub_i32 s0, s1, s0
	s_add_i32 s0, s0, 4
	v_cvt_f32_i32_e32 v88, s0
	v_sub_f32_e32 v137, v129, v137
	v_sub_f32_e32 v136, v128, v136
	v_sub_f32_e32 v135, v127, v135
	v_rcp_iflag_f32_e32 v88, v88
	v_sub_f32_e32 v90, v90, v86
	v_cndmask_b32_e32 v88, v88, v240, vcc
	v_fma_f32 v88, v141, v88, -v134
	v_cvt_pk_bf16_f32 v97, v88, s0
	s_mov_b32 s0, 0x1ec00000
	v_add_co_u32_e64 v138, s[0:1], s0, v72
	ds_read_u16 v88, v92 offset:34816
	ds_read_u16 v92, v92 offset:43008
	v_addc_co_u32_e64 v139, s[0:1], 0, v73, s[0:1]
	s_or_b32 s1, s62, 5
	s_max_i32 s0, s62, 3
	s_min_i32 s1, s1, s35
	s_sub_i32 s0, s1, s0
	s_add_i32 s0, s0, 3
	global_store_short v[138:139], v97, off offset:2048
	v_cvt_f32_i32_e32 v138, s0
	v_sub_f32_e32 v97, v130, v140
	v_add_f32_e32 v97, v141, v97
	v_sub_f32_e32 v134, v126, v134
	v_rcp_iflag_f32_e32 v138, v138
	s_waitcnt lgkmcnt(1)
	v_lshlrev_b32_e32 v88, 16, v88
	s_waitcnt lgkmcnt(0)
	v_lshlrev_b32_e32 v92, 16, v92
	v_cndmask_b32_e32 v138, v138, v240, vcc
	v_fma_f32 v138, v97, v138, -v133
	v_cvt_pk_bf16_f32 v140, v138, s0
	s_mov_b32 s0, 0x1ec01000
	v_add_co_u32_e64 v138, s[0:1], s0, v72
	v_add_f32_e32 v97, v97, v137
	s_nop 0
	v_addc_co_u32_e64 v139, s[0:1], 0, v73, s[0:1]
	s_or_b32 s1, s62, 6
	s_max_i32 s0, s62, 2
	s_min_i32 s1, s1, s35
	s_sub_i32 s0, s1, s0
	s_add_i32 s0, s0, 2
	v_cvt_f32_i32_e32 v137, s0
	global_store_short v[138:139], v140, off offset:2048
	v_sub_f32_e32 v133, v125, v133
	v_rcp_iflag_f32_e32 v137, v137
	s_nop 0
	v_cndmask_b32_e32 v137, v137, v240, vcc
	v_fma_f32 v137, v97, v137, -v132
	v_cvt_pk_bf16_f32 v137, v137, s0
	s_mov_b32 s0, 0x1ec02000
	v_add_co_u32_e64 v138, s[0:1], s0, v72
	v_add_f32_e32 v97, v97, v136
	s_nop 0
	v_addc_co_u32_e64 v139, s[0:1], 0, v73, s[0:1]
	s_or_b32 s1, s62, 7
	s_max_i32 s0, s62, 1
	s_min_i32 s1, s1, s35
	s_sub_i32 s0, s1, s0
	s_add_i32 s0, s0, 1
	v_cvt_f32_i32_e32 v136, s0
	global_store_short v[138:139], v137, off offset:2048
	v_sub_f32_e32 v132, v124, v132
	v_rcp_iflag_f32_e32 v136, v136
	s_nop 0
	v_cndmask_b32_e32 v136, v136, v240, vcc
	v_fma_f32 v136, v97, v136, -v131
	v_cvt_pk_bf16_f32 v138, v136, s0
	s_mov_b32 s0, 0x1ec03000
	v_add_co_u32_e64 v136, s[0:1], s0, v72
	v_add_f32_e32 v97, v97, v135
	s_nop 0
	v_addc_co_u32_e64 v137, s[0:1], 0, v73, s[0:1]
	s_or_b32 s1, s62, 8
	s_max_i32 s0, s62, 0
	s_min_i32 s1, s1, s35
	s_sub_i32 s0, s1, s0
	v_cvt_f32_i32_e32 v135, s0
	global_store_short v[136:137], v138, off offset:2048
	v_sub_f32_e32 v131, v123, v131
	v_rcp_iflag_f32_e32 v135, v135
	s_nop 0
	v_cndmask_b32_e32 v135, v135, v240, vcc
	v_fma_f32 v135, v97, v135, -v130
	v_cvt_pk_bf16_f32 v135, v135, s0
	s_mov_b32 s0, 0x1ec04000
	v_add_co_u32_e64 v136, s[0:1], s0, v72
	v_add_f32_e32 v97, v97, v134
	s_nop 0
	v_addc_co_u32_e64 v137, s[0:1], 0, v73, s[0:1]
	s_or_b32 s0, s62, 9
	s_min_i32 s0, s0, s35
	s_not_b32 s1, s62
	s_cmp_gt_i32 s62, -1
	s_cselect_b32 s1, s1, 0
	s_add_i32 s0, s0, s1
	v_cvt_f32_i32_e32 v134, s0
	global_store_short v[136:137], v135, off offset:2048
	v_sub_f32_e32 v130, v122, v130
	v_rcp_iflag_f32_e32 v134, v134
	s_nop 0
	v_cndmask_b32_e32 v134, v134, v240, vcc
	v_fma_f32 v134, v97, v134, -v129
	v_cvt_pk_bf16_f32 v136, v134, s0
	s_mov_b32 s0, 0x1ec05000
	v_add_co_u32_e64 v134, s[0:1], s0, v72
	v_add_f32_e32 v97, v97, v133
	s_nop 0
	v_addc_co_u32_e64 v135, s[0:1], 0, v73, s[0:1]
	s_or_b32 s1, s62, 10
	s_max_i32 s0, s62, -2
	s_min_i32 s1, s1, s35
	s_sub_i32 s0, s1, s0
	s_add_i32 s0, s0, -2
	v_cvt_f32_i32_e32 v133, s0
	global_store_short v[134:135], v136, off offset:2048
	v_sub_f32_e32 v129, v95, v129
	v_rcp_iflag_f32_e32 v133, v133
	s_nop 0
	v_cndmask_b32_e32 v133, v133, v240, vcc
	v_fma_f32 v133, v97, v133, -v128
	v_cvt_pk_bf16_f32 v133, v133, s0
	s_mov_b32 s0, 0x1ec06000
	v_add_co_u32_e64 v134, s[0:1], s0, v72
	v_add_f32_e32 v97, v97, v132
	s_nop 0
	v_addc_co_u32_e64 v135, s[0:1], 0, v73, s[0:1]
	s_or_b32 s1, s62, 11
	s_max_i32 s0, s62, -3
	s_min_i32 s1, s1, s35
	s_sub_i32 s0, s1, s0
	s_add_i32 s0, s0, -3
	v_cvt_f32_i32_e32 v132, s0
	global_store_short v[134:135], v133, off offset:2048
	v_sub_f32_e32 v128, v94, v128
	v_rcp_iflag_f32_e32 v132, v132
	s_nop 0
	v_cndmask_b32_e32 v132, v132, v240, vcc
	v_fma_f32 v132, v97, v132, -v127
	v_cvt_pk_bf16_f32 v134, v132, s0
	s_mov_b32 s0, 0x1ec07000
	v_add_co_u32_e64 v132, s[0:1], s0, v72
	v_add_f32_e32 v97, v97, v131
	s_nop 0
	v_addc_co_u32_e64 v133, s[0:1], 0, v73, s[0:1]
	s_or_b32 s1, s62, 12
	s_max_i32 s0, s62, -4
	s_min_i32 s1, s1, s35
	s_sub_i32 s0, s1, s0
	s_add_i32 s0, s0, -4
	v_cvt_f32_i32_e32 v131, s0
	global_store_short v[132:133], v134, off offset:2048
	v_sub_f32_e32 v127, v93, v127
	v_rcp_iflag_f32_e32 v131, v131
	s_nop 0
	v_cndmask_b32_e32 v131, v131, v240, vcc
	v_fma_f32 v131, v97, v131, -v126
	v_cvt_pk_bf16_f32 v131, v131, s0
	s_mov_b32 s0, 0x1ec08000
	v_add_co_u32_e64 v132, s[0:1], s0, v72
	v_add_f32_e32 v97, v97, v130
	s_nop 0
	v_addc_co_u32_e64 v133, s[0:1], 0, v73, s[0:1]
	s_or_b32 s1, s62, 13
	s_max_i32 s0, s62, -5
	s_min_i32 s1, s1, s35
	s_sub_i32 s0, s1, s0
	s_add_i32 s0, s0, -5
	v_cvt_f32_i32_e32 v130, s0
	global_store_short v[132:133], v131, off offset:2048
	v_sub_f32_e32 v126, v91, v126
	v_rcp_iflag_f32_e32 v130, v130
	s_nop 0
	v_cndmask_b32_e32 v130, v130, v240, vcc
	v_fma_f32 v130, v97, v130, -v125
	v_cvt_pk_bf16_f32 v132, v130, s0
	s_mov_b32 s0, 0x1ec09000
	v_add_co_u32_e64 v130, s[0:1], s0, v72
	v_add_f32_e32 v97, v97, v129
	s_nop 0
	v_addc_co_u32_e64 v131, s[0:1], 0, v73, s[0:1]
	s_or_b32 s1, s62, 14
	s_max_i32 s0, s62, -6
	s_min_i32 s1, s1, s35
	s_sub_i32 s0, s1, s0
	s_add_i32 s0, s0, -6
	v_cvt_f32_i32_e32 v129, s0
	global_store_short v[130:131], v132, off offset:2048
	v_sub_f32_e32 v125, v87, v125
	v_rcp_iflag_f32_e32 v129, v129
	s_nop 0
	v_cndmask_b32_e32 v129, v129, v240, vcc
	v_fma_f32 v129, v97, v129, -v124
	v_cvt_pk_bf16_f32 v129, v129, s0
	s_mov_b32 s0, 0x1ec0a000
	v_add_co_u32_e64 v130, s[0:1], s0, v72
	v_add_f32_e32 v97, v97, v128
	s_nop 0
	v_addc_co_u32_e64 v131, s[0:1], 0, v73, s[0:1]
	s_or_b32 s1, s62, 15
	s_max_i32 s0, s62, -7
	s_min_i32 s1, s1, s35
	s_sub_i32 s0, s1, s0
	s_add_i32 s0, s0, -7
	v_cvt_f32_i32_e32 v128, s0
	global_store_short v[130:131], v129, off offset:2048
	v_sub_f32_e32 v124, v79, v124
	v_rcp_iflag_f32_e32 v128, v128
	s_nop 0
	v_cndmask_b32_e32 v128, v128, v240, vcc
	v_fma_f32 v128, v97, v128, -v123
	v_cvt_pk_bf16_f32 v130, v128, s0
	s_mov_b32 s0, 0x1ec0b000
	v_add_co_u32_e64 v128, s[0:1], s0, v72
	v_add_f32_e32 v97, v97, v127
	s_nop 0
	v_addc_co_u32_e64 v129, s[0:1], 0, v73, s[0:1]
	s_or_b32 s1, s62, 16
	s_max_i32 s0, s62, -8
	s_min_i32 s1, s1, s35
	s_sub_i32 s0, s1, s0
	s_add_i32 s0, s0, -8
	v_cvt_f32_i32_e32 v127, s0
	global_store_short v[128:129], v130, off offset:2048
	v_sub_f32_e32 v123, v84, v123
	v_rcp_iflag_f32_e32 v127, v127
	s_nop 0
	v_cndmask_b32_e32 v127, v127, v240, vcc
	v_fma_f32 v127, v97, v127, -v122
	v_cvt_pk_bf16_f32 v127, v127, s0
	s_mov_b32 s0, 0x1ec0c000
	v_add_co_u32_e64 v128, s[0:1], s0, v72
	v_add_f32_e32 v97, v97, v126
	s_nop 0
	v_addc_co_u32_e64 v129, s[0:1], 0, v73, s[0:1]
	s_or_b32 s1, s62, 17
	s_max_i32 s0, s62, -9
	s_min_i32 s1, s1, s35
	s_sub_i32 s0, s1, s0
	s_add_i32 s0, s0, -9
	v_cvt_f32_i32_e32 v126, s0
	global_store_short v[128:129], v127, off offset:2048
	v_sub_f32_e32 v122, v83, v122
	v_rcp_iflag_f32_e32 v126, v126
	s_nop 0
	v_cndmask_b32_e32 v126, v126, v240, vcc
	v_fma_f32 v126, v97, v126, -v95
	v_cvt_pk_bf16_f32 v128, v126, s0
	s_mov_b32 s0, 0x1ec0d000
	v_add_co_u32_e64 v126, s[0:1], s0, v72
	v_add_f32_e32 v97, v97, v125
	s_nop 0
	v_addc_co_u32_e64 v127, s[0:1], 0, v73, s[0:1]
	s_or_b32 s1, s62, 18
	s_max_i32 s0, s62, -10
	s_min_i32 s1, s1, s35
	s_sub_i32 s0, s1, s0
	s_add_i32 s0, s0, -10
	v_cvt_f32_i32_e32 v125, s0
	global_store_short v[126:127], v128, off offset:2048
	v_sub_f32_e32 v95, v82, v95
	v_rcp_iflag_f32_e32 v125, v125
	s_nop 0
	v_cndmask_b32_e32 v125, v125, v240, vcc
	v_fma_f32 v125, v97, v125, -v94
	v_cvt_pk_bf16_f32 v125, v125, s0
	s_mov_b32 s0, 0x1ec0e000
	v_add_co_u32_e64 v126, s[0:1], s0, v72
	v_add_f32_e32 v97, v97, v124
	s_nop 0
	v_addc_co_u32_e64 v127, s[0:1], 0, v73, s[0:1]
	s_or_b32 s1, s62, 19
	s_max_i32 s0, s62, -11
	s_min_i32 s1, s1, s35
	s_sub_i32 s0, s1, s0
	s_add_i32 s0, s0, -11
	v_cvt_f32_i32_e32 v124, s0
	global_store_short v[126:127], v125, off offset:2048
	v_sub_f32_e32 v94, v81, v94
	v_rcp_iflag_f32_e32 v124, v124
	s_nop 0
	v_cndmask_b32_e32 v124, v124, v240, vcc
	v_fma_f32 v124, v97, v124, -v93
	v_cvt_pk_bf16_f32 v126, v124, s0
	s_mov_b32 s0, 0x1ec0f000
	v_add_co_u32_e64 v124, s[0:1], s0, v72
	v_add_f32_e32 v97, v97, v123
	s_nop 0
	v_addc_co_u32_e64 v125, s[0:1], 0, v73, s[0:1]
	s_or_b32 s1, s62, 20
	s_max_i32 s0, s62, -12
	s_min_i32 s1, s1, s35
	s_sub_i32 s0, s1, s0
	s_add_i32 s0, s0, -12
	v_cvt_f32_i32_e32 v123, s0
	global_store_short v[124:125], v126, off offset:2048
	v_sub_f32_e32 v93, v80, v93
	v_rcp_iflag_f32_e32 v123, v123
	s_nop 0
	v_cndmask_b32_e32 v123, v123, v240, vcc
	v_fma_f32 v123, v97, v123, -v91
	v_cvt_pk_bf16_f32 v123, v123, s0
	s_mov_b32 s0, 0x1ec10000
	v_add_co_u32_e64 v124, s[0:1], s0, v72
	v_add_f32_e32 v97, v97, v122
	s_nop 0
	v_addc_co_u32_e64 v125, s[0:1], 0, v73, s[0:1]
	s_or_b32 s1, s62, 21
	s_max_i32 s0, s62, -13
	s_min_i32 s1, s1, s35
	s_sub_i32 s0, s1, s0
	s_add_i32 s0, s0, -13
	v_cvt_f32_i32_e32 v122, s0
	global_store_short v[124:125], v123, off offset:2048
	v_add_f32_e32 v95, v97, v95
	v_sub_f32_e32 v91, v85, v91
	v_rcp_iflag_f32_e32 v122, v122
	s_nop 0
	v_cndmask_b32_e32 v122, v122, v240, vcc
	v_fma_f32 v122, v97, v122, -v87
	v_cvt_pk_bf16_f32 v124, v122, s0
	s_mov_b32 s0, 0x1ec11000
	v_add_co_u32_e64 v122, s[0:1], s0, v72
	v_sub_f32_e32 v87, v86, v87
	s_nop 0
	v_addc_co_u32_e64 v123, s[0:1], 0, v73, s[0:1]
	s_or_b32 s1, s62, 22
	s_max_i32 s0, s62, -14
	s_min_i32 s1, s1, s35
	s_sub_i32 s0, s1, s0
	s_add_i32 s0, s0, -14
	v_cvt_f32_i32_e32 v97, s0
	global_store_short v[122:123], v124, off offset:2048
	v_rcp_iflag_f32_e32 v97, v97
	s_nop 0
	v_cndmask_b32_e32 v97, v97, v240, vcc
	v_fma_f32 v97, v95, v97, -v79
	v_cvt_pk_bf16_f32 v97, v97, s0
	s_mov_b32 s0, 0x1ec12000
	v_add_co_u32_e64 v122, s[0:1], s0, v72
	v_sub_f32_e32 v79, v88, v79
	s_nop 0
	v_addc_co_u32_e64 v123, s[0:1], 0, v73, s[0:1]
	s_or_b32 s1, s62, 23
	s_max_i32 s0, s62, -15
	s_min_i32 s1, s1, s35
	s_sub_i32 s0, s1, s0
	s_add_i32 s0, s0, -15
	global_store_short v[122:123], v97, off offset:2048
	v_add_f32_e32 v97, v95, v94
	v_cvt_f32_i32_e32 v94, s0
	v_add_f32_e32 v93, v97, v93
	v_add_f32_e32 v91, v93, v91
	v_add_f32_e32 v87, v91, v87
	v_rcp_iflag_f32_e32 v94, v94
	v_add_f32_e32 v79, v87, v79
	v_sub_f32_e32 v123, v69, v80
	v_cndmask_b32_e32 v94, v94, v240, vcc
	v_fma_f32 v94, v97, v94, -v84
	v_cvt_pk_bf16_f32 v122, v94, s0
	s_mov_b32 s0, 0x1ec13000
	v_add_co_u32_e64 v94, s[0:1], s0, v72
	v_sub_f32_e32 v84, v78, v84
	s_nop 0
	v_addc_co_u32_e64 v95, s[0:1], 0, v73, s[0:1]
	s_or_b32 s1, s62, 24
	s_max_i32 s0, s62, -16
	s_min_i32 s1, s1, s35
	s_sub_i32 s0, s1, s0
	s_add_i32 s0, s0, -16
	global_store_short v[94:95], v122, off offset:2048
	v_cvt_f32_i32_e32 v94, s0
	v_rcp_iflag_f32_e32 v94, v94
	s_nop 0
	v_cndmask_b32_e32 v94, v94, v240, vcc
	v_fma_f32 v94, v93, v94, -v83
	v_cvt_pk_bf16_f32 v97, v94, s0
	s_mov_b32 s0, 0x1ec14000
	v_add_co_u32_e64 v94, s[0:1], s0, v72
	v_sub_f32_e32 v83, v77, v83
	s_nop 0
	v_addc_co_u32_e64 v95, s[0:1], 0, v73, s[0:1]
	s_or_b32 s1, s62, 25
	s_max_i32 s0, s62, 0xffffffef
	s_min_i32 s1, s1, s35
	s_sub_i32 s0, s1, s0
	s_sub_i32 s0, s0, 17
	v_cvt_f32_i32_e32 v93, s0
	global_store_short v[94:95], v97, off offset:2048
	v_sub_f32_e32 v97, v75, v81
	v_rcp_iflag_f32_e32 v93, v93
	s_nop 0
	v_cndmask_b32_e32 v93, v93, v240, vcc
	v_fma_f32 v93, v91, v93, -v82
	v_cvt_pk_bf16_f32 v93, v93, s0
	s_mov_b32 s0, 0x1ec15000
	v_add_co_u32_e64 v94, s[0:1], s0, v72
	v_sub_f32_e32 v82, v76, v82
	s_nop 0
	v_addc_co_u32_e64 v95, s[0:1], 0, v73, s[0:1]
	s_or_b32 s1, s62, 26
	s_max_i32 s0, s62, 0xffffffee
	s_min_i32 s1, s1, s35
	s_sub_i32 s0, s1, s0
	s_sub_i32 s0, s0, 18
	v_cvt_f32_i32_e32 v91, s0
	global_store_short v[94:95], v93, off offset:2048
	v_rcp_iflag_f32_e32 v91, v91
	s_nop 0
	v_cndmask_b32_e32 v91, v91, v240, vcc
	v_fma_f32 v91, v87, v91, -v81
	v_cvt_pk_bf16_f32 v91, v91, s0
	s_mov_b32 s0, 0x1ec16000
	v_add_co_u32_e64 v94, s[0:1], s0, v72
	s_nop 1
	v_addc_co_u32_e64 v95, s[0:1], 0, v73, s[0:1]
	s_or_b32 s1, s62, 27
	s_max_i32 s0, s62, 0xffffffed
	s_min_i32 s1, s1, s35
	s_sub_i32 s0, s1, s0
	s_sub_i32 s0, s0, 19
	s_or_b32 s1, s62, 28
	global_store_short v[94:95], v91, off offset:2048
	v_cvt_f32_i32_e32 v91, s0
	s_max_i32 s0, s62, 0xffffffec
	s_min_i32 s1, s1, s35
	s_sub_i32 s0, s1, s0
	s_sub_i32 s0, s0, 20
	s_or_b32 s1, s62, 29
	v_cvt_f32_i32_e32 v93, s0
	s_max_i32 s0, s62, 0xffffffeb
	s_min_i32 s1, s1, s35
	s_sub_i32 s0, s1, s0
	s_sub_i32 s0, s0, 21
	s_or_b32 s1, s62, 30
	v_cvt_f32_i32_e32 v94, s0
	s_max_i32 s0, s62, 0xffffffea
	s_min_i32 s1, s1, s35
	s_sub_i32 s0, s1, s0
	s_sub_i32 s0, s0, 22
	s_or_b32 s1, s62, 31
	v_cvt_f32_i32_e32 v95, s0
	s_max_i32 s0, s62, 0xffffffe9
	s_min_i32 s1, s1, s35
	s_sub_i32 s0, s1, s0
	s_sub_i32 s0, s0, 23
	v_cvt_f32_i32_e32 v81, s0
	s_add_i32 s1, s62, 32
	s_max_i32 s0, s62, 0xffffffe8
	s_min_i32 s1, s1, s35
	v_rcp_iflag_f32_e32 v81, v81
	s_sub_i32 s0, s1, s0
	s_sub_i32 s0, s0, 24
	s_add_i32 s1, s62, 33
	v_cndmask_b32_e32 v122, v81, v240, vcc
	v_cvt_f32_i32_e32 v81, s0
	s_max_i32 s0, s62, 0xffffffe7
	s_min_i32 s1, s1, s35
	s_sub_i32 s0, s1, s0
	v_rcp_iflag_f32_e32 v81, v81
	s_sub_i32 s0, s0, 25
	s_add_i32 s1, s62, 34
	s_min_i32 s1, s1, s35
	v_cndmask_b32_e32 v124, v81, v240, vcc
	v_cvt_f32_i32_e32 v81, s0
	s_max_i32 s0, s62, 0xffffffe6
	s_sub_i32 s0, s1, s0
	s_sub_i32 s0, s0, 26
	v_rcp_iflag_f32_e32 v81, v81
	s_min_i32 s1, s63, s35
	v_rcp_iflag_f32_e32 v91, v91
	v_rcp_iflag_f32_e32 v93, v93
	v_cndmask_b32_e32 v125, v81, v240, vcc
	v_cvt_f32_i32_e32 v81, s0
	s_max_i32 s0, s62, 0xffffffe5
	s_sub_i32 s0, s1, s0
	s_sub_i32 s0, s0, 27
	v_rcp_iflag_f32_e32 v81, v81
	v_rcp_iflag_f32_e32 v94, v94
	v_rcp_iflag_f32_e32 v95, v95
	v_cndmask_b32_e32 v91, v91, v240, vcc
	v_cndmask_b32_e32 v126, v81, v240, vcc
	v_cvt_f32_i32_e32 v81, s0
	v_fma_f32 v80, v79, v91, -v80
	v_cvt_pk_bf16_f32 v87, v80, s0
	s_mov_b32 s0, 0x1ec17000
	v_rcp_iflag_f32_e32 v81, v81
	v_cndmask_b32_e32 v93, v93, v240, vcc
	v_cndmask_b32_e32 v94, v94, v240, vcc
	v_cndmask_b32_e32 v95, v95, v240, vcc
	v_cndmask_b32_e32 v127, v81, v240, vcc
	v_add_co_u32_e32 v80, vcc, s0, v72
	v_add_f32_e32 v79, v79, v84
	s_nop 0
	v_addc_co_u32_e32 v81, vcc, 0, v73, vcc
	global_store_short v[80:81], v87, off offset:2048
	v_fma_f32 v80, v79, v93, -v85
	v_cvt_pk_bf16_f32 v84, v80, s0
	s_mov_b32 s0, 0x1ec18000
	v_add_co_u32_e32 v80, vcc, s0, v72
	v_add_f32_e32 v79, v79, v83
	s_nop 0
	v_addc_co_u32_e32 v81, vcc, 0, v73, vcc
	global_store_short v[80:81], v84, off offset:2048
	v_fma_f32 v80, v79, v94, -v86
	v_cvt_pk_bf16_f32 v83, v80, s0
	s_mov_b32 s0, 0x1ec19000
	v_add_co_u32_e32 v80, vcc, s0, v72
	v_add_f32_e32 v79, v79, v82
	s_nop 0
	v_addc_co_u32_e32 v81, vcc, 0, v73, vcc
	global_store_short v[80:81], v83, off offset:2048
	v_fma_f32 v80, v79, v95, -v88
	v_cvt_pk_bf16_f32 v82, v80, s0
	s_mov_b32 s0, 0x1ec1a000
	v_add_co_u32_e32 v80, vcc, s0, v72
	s_nop 1
	v_addc_co_u32_e32 v81, vcc, 0, v73, vcc
	global_store_short v[80:81], v82, off offset:2048
	v_add_f32_e32 v80, v79, v97
	v_fma_f32 v78, v80, v122, -v78
	v_cvt_pk_bf16_f32 v81, v78, s0
	s_mov_b32 s0, 0x1ec1b000
	v_add_f32_e32 v80, v80, v123
	v_add_co_u32_e32 v78, vcc, s0, v72
	v_fma_f32 v77, v80, v124, -v77
	s_nop 0
	v_addc_co_u32_e32 v79, vcc, 0, v73, vcc
	v_cvt_pk_bf16_f32 v77, v77, s0
	s_mov_b32 s0, 0x1ec1c000
	global_store_short v[78:79], v81, off offset:2048
	v_add_co_u32_e32 v78, vcc, s0, v72
	s_nop 1
	v_addc_co_u32_e32 v79, vcc, 0, v73, vcc
	global_store_short v[78:79], v77, off offset:2048
	v_add_f32_e32 v78, v80, v89
	v_fma_f32 v76, v78, v125, -v76
	v_cvt_pk_bf16_f32 v79, v76, s0
	v_add_co_u32_e32 v76, vcc, 0x1ec1d000, v72
	s_nop 1
	v_addc_co_u32_e32 v77, vcc, 0, v73, vcc
	global_store_short v[76:77], v79, off offset:2048
	v_add_f32_e32 v76, v78, v90
	v_fma_f32 v75, v76, v126, -v75
	v_add_co_u32_e32 v72, vcc, 0x1ec1e000, v72
	v_cvt_pk_bf16_f32 v75, v75, s0
	s_nop 0
	v_addc_co_u32_e32 v73, vcc, 0, v73, vcc
	global_store_short v[72:73], v75, off offset:2048
	v_sub_f32_e32 v72, v92, v88
	v_add_f32_e32 v72, v76, v72
	v_fma_f32 v69, v72, v127, -v69
	s_xor_b64 s[0:1], exec, -1

.LBB0_395:
	s_andn2_saveexec_b64 s[88:89], s[88:89]
	s_cbranch_execz .LBB0_397
	v_lshl_add_u32 v84, v96, 1, 0
	ds_read_u16 v136, v84 offset:6144
	ds_read_u16 v133, v84 offset:7168
	ds_read_u16 v132, v84 offset:8192
	ds_read_u16 v131, v84 offset:9216
	ds_read_u16 v130, v84 offset:10240
	ds_read_u16 v129, v84 offset:11264
	ds_read_u16 v128, v84 offset:12288
	ds_read_u16 v127, v84 offset:13312
	ds_read_u16 v126, v84 offset:14336
	ds_read_u16 v125, v84 offset:15360
	ds_read_u16 v124, v84 offset:16384
	ds_read_u16 v123, v84 offset:17408
	ds_read_u16 v122, v84 offset:18432
	ds_read_u16 v95, v84 offset:19456
	ds_read_u16 v94, v84 offset:20480
	ds_read_u16 v93, v84 offset:21504
	ds_read_u16 v92, v84 offset:22528
	ds_read_u16 v91, v84 offset:23552
	ds_read_u16 v90, v84 offset:24576
	ds_read_u16 v89, v84 offset:25600
	ds_read_u16 v88, v84 offset:26624
	ds_read_u16 v85, v84 offset:29696
	ds_read_u16 v83, v84 offset:30720
	ds_read_u16 v87, v84 offset:27648
	ds_read_u16 v82, v84 offset:31744
	ds_read_u16 v86, v84 offset:28672
	ds_read_u16 v77, v84 offset:32768
	ds_read_u16 v81, v84 offset:33792
	ds_read_u16 v76, v84 offset:37888
	ds_read_u16 v80, v84 offset:34816
	ds_read_u16 v75, v84 offset:38912
	ds_read_u16 v78, v84 offset:35840
	s_cmp_gt_i32 s62, 1
	s_cselect_b64 s[0:1], -1, 0
	s_add_i32 s63, s62, 33
	s_cmp_le_i32 s63, s35
	s_waitcnt lgkmcnt(0)
	v_lshlrev_b32_e32 v136, 16, v136
	s_cselect_b64 s[12:13], -1, 0
	s_ashr_i32 s75, s74, 31
	s_and_b64 vcc, s[0:1], s[12:13]
	s_lshl_b64 s[0:1], s[74:75], 12
	s_waitcnt lgkmcnt(0)
	v_lshlrev_b32_e32 v133, 16, v133
	s_add_u32 s0, s94, s0
	s_addc_u32 s1, s95, s1
	v_ashrrev_i32_e32 v97, 31, v96
	v_lshl_add_u64 v[72:73], v[96:97], 1, s[0:1]
	s_waitcnt lgkmcnt(0)
	v_lshlrev_b32_e32 v132, 16, v132
	s_mov_b64 s[0:1], 0x1ec00800
	s_waitcnt lgkmcnt(0)
	v_lshlrev_b32_e32 v131, 16, v131
	s_waitcnt lgkmcnt(0)
	v_lshlrev_b32_e32 v130, 16, v130
	s_waitcnt lgkmcnt(0)
	v_lshlrev_b32_e32 v129, 16, v129
	s_waitcnt lgkmcnt(0)
	v_lshlrev_b32_e32 v128, 16, v128
	s_waitcnt lgkmcnt(0)
	v_lshlrev_b32_e32 v127, 16, v127
	s_waitcnt lgkmcnt(0)
	v_lshlrev_b32_e32 v126, 16, v126
	s_waitcnt lgkmcnt(0)
	v_lshlrev_b32_e32 v125, 16, v125
	s_waitcnt lgkmcnt(0)
	v_lshlrev_b32_e32 v124, 16, v124
	s_waitcnt lgkmcnt(0)
	v_lshlrev_b32_e32 v123, 16, v123
	s_waitcnt lgkmcnt(0)
	v_lshlrev_b32_e32 v122, 16, v122
	s_waitcnt lgkmcnt(0)
	v_lshlrev_b32_e32 v95, 16, v95
	s_waitcnt lgkmcnt(0)
	v_lshlrev_b32_e32 v94, 16, v94
	s_waitcnt lgkmcnt(0)
	v_lshlrev_b32_e32 v93, 16, v93
	s_waitcnt lgkmcnt(0)
	v_lshlrev_b32_e32 v92, 16, v92
	s_waitcnt lgkmcnt(0)
	v_lshlrev_b32_e32 v91, 16, v91
	s_waitcnt lgkmcnt(0)
	v_lshlrev_b32_e32 v90, 16, v90
	s_waitcnt lgkmcnt(0)
	v_lshlrev_b32_e32 v89, 16, v89
	s_waitcnt lgkmcnt(0)
	v_lshlrev_b32_e32 v88, 16, v88
	s_waitcnt lgkmcnt(0)
	v_lshlrev_b32_e32 v85, 16, v85
	s_waitcnt lgkmcnt(0)
	v_lshlrev_b32_e32 v83, 16, v83
	s_waitcnt lgkmcnt(0)
	v_lshlrev_b32_e32 v87, 16, v87
	s_waitcnt lgkmcnt(0)
	v_lshlrev_b32_e32 v82, 16, v82
	s_waitcnt lgkmcnt(0)
	v_lshlrev_b32_e32 v86, 16, v86
	s_waitcnt lgkmcnt(0)
	v_lshlrev_b32_e32 v77, 16, v77
	s_waitcnt lgkmcnt(0)
	v_lshlrev_b32_e32 v81, 16, v81
	s_waitcnt lgkmcnt(0)
	v_lshlrev_b32_e32 v76, 16, v76
	s_waitcnt lgkmcnt(0)
	v_lshlrev_b32_e32 v80, 16, v80
	s_waitcnt lgkmcnt(0)
	v_lshlrev_b32_e32 v75, 16, v75
	ds_read_u16 v69, v84 offset:39936
	s_waitcnt lgkmcnt(0)
	v_lshlrev_b32_e32 v78, 16, v78
	v_add_f32_e32 v70, 0, v136
	v_add_f32_e32 v70, v70, v133
	v_add_f32_e32 v70, v70, v132
	v_add_f32_e32 v137, v70, v131
	v_lshl_add_u64 v[70:71], v[72:73], 0, s[0:1]
	s_or_b32 s1, s62, 2
	s_max_i32 s0, s62, 2
	s_min_i32 s1, s1, s35
	s_sub_i32 s0, s1, s0
	s_add_i32 s0, s0, 2
	v_cvt_f32_i32_e32 v79, s0
	v_sub_f32_e32 v133, v129, v133
	s_waitcnt lgkmcnt(0)
	v_lshlrev_b32_e32 v69, 16, v69
	v_rcp_iflag_f32_e32 v79, v79
	s_nop 0
	v_cndmask_b32_e32 v79, v79, v241, vcc
	v_fma_f32 v79, v137, v79, -v132
	v_cvt_pk_bf16_f32 v97, v79, s0
	s_mov_b32 s0, 0x1ec00000
	v_add_co_u32_e64 v134, s[0:1], s0, v72
	ds_read_u16 v79, v84 offset:36864
	ds_read_u16 v84, v84 offset:40960
	v_addc_co_u32_e64 v135, s[0:1], 0, v73, s[0:1]
	s_or_b32 s1, s62, 3
	s_max_i32 s0, s62, 1
	s_min_i32 s1, s1, s35
	s_sub_i32 s0, s1, s0
	s_add_i32 s0, s0, 1
	global_store_short v[134:135], v97, off offset:2048
	v_cvt_f32_i32_e32 v134, s0
	v_sub_f32_e32 v97, v130, v136
	v_add_f32_e32 v97, v137, v97
	v_sub_f32_e32 v132, v128, v132
	v_rcp_iflag_f32_e32 v134, v134
	s_waitcnt lgkmcnt(0)
	v_lshlrev_b32_e32 v84, 16, v84
	v_cndmask_b32_e32 v134, v134, v241, vcc
	v_fma_f32 v134, v97, v134, -v131
	v_cvt_pk_bf16_f32 v136, v134, s0
	s_mov_b32 s0, 0x1ec01000
	v_add_co_u32_e64 v134, s[0:1], s0, v72
	v_add_f32_e32 v97, v97, v133
	s_nop 0
	v_addc_co_u32_e64 v135, s[0:1], 0, v73, s[0:1]
	s_or_b32 s1, s62, 4
	s_max_i32 s0, s62, 0
	s_min_i32 s1, s1, s35
	s_sub_i32 s0, s1, s0
	v_cvt_f32_i32_e32 v133, s0
	global_store_short v[134:135], v136, off offset:2048
	v_sub_f32_e32 v131, v127, v131
	v_rcp_iflag_f32_e32 v133, v133
	s_nop 0
	v_cndmask_b32_e32 v133, v133, v241, vcc
	v_fma_f32 v133, v97, v133, -v130
	v_cvt_pk_bf16_f32 v133, v133, s0
	s_mov_b32 s0, 0x1ec02000
	v_add_co_u32_e64 v134, s[0:1], s0, v72
	v_add_f32_e32 v97, v97, v132
	s_nop 0
	v_addc_co_u32_e64 v135, s[0:1], 0, v73, s[0:1]
	s_or_b32 s0, s62, 5
	s_min_i32 s0, s0, s35
	s_not_b32 s1, s62
	s_cmp_gt_i32 s62, -1
	s_cselect_b32 s1, s1, 0
	s_add_i32 s0, s0, s1
	v_cvt_f32_i32_e32 v132, s0
	global_store_short v[134:135], v133, off offset:2048
	v_sub_f32_e32 v130, v126, v130
	v_rcp_iflag_f32_e32 v132, v132
	s_nop 0
	v_cndmask_b32_e32 v132, v132, v241, vcc
	v_fma_f32 v132, v97, v132, -v129
	v_cvt_pk_bf16_f32 v134, v132, s0
	s_mov_b32 s0, 0x1ec03000
	v_add_co_u32_e64 v132, s[0:1], s0, v72
	v_add_f32_e32 v97, v97, v131
	s_nop 0
	v_addc_co_u32_e64 v133, s[0:1], 0, v73, s[0:1]
	s_or_b32 s1, s62, 6
	s_max_i32 s0, s62, -2
	s_min_i32 s1, s1, s35
	s_sub_i32 s0, s1, s0
	s_add_i32 s0, s0, -2
	v_cvt_f32_i32_e32 v131, s0
	global_store_short v[132:133], v134, off offset:2048
	v_sub_f32_e32 v129, v125, v129
	v_rcp_iflag_f32_e32 v131, v131
	s_nop 0
	v_cndmask_b32_e32 v131, v131, v241, vcc
	v_fma_f32 v131, v97, v131, -v128
	v_cvt_pk_bf16_f32 v131, v131, s0
	s_mov_b32 s0, 0x1ec04000
	v_add_co_u32_e64 v132, s[0:1], s0, v72
	v_add_f32_e32 v97, v97, v130
	s_nop 0
	v_addc_co_u32_e64 v133, s[0:1], 0, v73, s[0:1]
	s_or_b32 s1, s62, 7
	s_max_i32 s0, s62, -3
	s_min_i32 s1, s1, s35
	s_sub_i32 s0, s1, s0
	s_add_i32 s0, s0, -3
	v_cvt_f32_i32_e32 v130, s0
	global_store_short v[132:133], v131, off offset:2048
	v_sub_f32_e32 v128, v124, v128
	v_rcp_iflag_f32_e32 v130, v130
	s_nop 0
	v_cndmask_b32_e32 v130, v130, v241, vcc
	v_fma_f32 v130, v97, v130, -v127
	v_cvt_pk_bf16_f32 v132, v130, s0
	s_mov_b32 s0, 0x1ec05000
	v_add_co_u32_e64 v130, s[0:1], s0, v72
	v_add_f32_e32 v97, v97, v129
	s_nop 0
	v_addc_co_u32_e64 v131, s[0:1], 0, v73, s[0:1]
	s_or_b32 s1, s62, 8
	s_max_i32 s0, s62, -4
	s_min_i32 s1, s1, s35
	s_sub_i32 s0, s1, s0
	s_add_i32 s0, s0, -4
	v_cvt_f32_i32_e32 v129, s0
	global_store_short v[130:131], v132, off offset:2048
	v_sub_f32_e32 v127, v123, v127
	v_rcp_iflag_f32_e32 v129, v129
	s_nop 0
	v_cndmask_b32_e32 v129, v129, v241, vcc
	v_fma_f32 v129, v97, v129, -v126
	v_cvt_pk_bf16_f32 v129, v129, s0
	s_mov_b32 s0, 0x1ec06000
	v_add_co_u32_e64 v130, s[0:1], s0, v72
	v_add_f32_e32 v97, v97, v128
	s_nop 0
	v_addc_co_u32_e64 v131, s[0:1], 0, v73, s[0:1]
	s_or_b32 s1, s62, 9
	s_max_i32 s0, s62, -5
	s_min_i32 s1, s1, s35
	s_sub_i32 s0, s1, s0
	s_add_i32 s0, s0, -5
	v_cvt_f32_i32_e32 v128, s0
	global_store_short v[130:131], v129, off offset:2048
	v_sub_f32_e32 v126, v122, v126
	v_rcp_iflag_f32_e32 v128, v128
	s_nop 0
	v_cndmask_b32_e32 v128, v128, v241, vcc
	v_fma_f32 v128, v97, v128, -v125
	v_cvt_pk_bf16_f32 v130, v128, s0
	s_mov_b32 s0, 0x1ec07000
	v_add_co_u32_e64 v128, s[0:1], s0, v72
	v_add_f32_e32 v97, v97, v127
	s_nop 0
	v_addc_co_u32_e64 v129, s[0:1], 0, v73, s[0:1]
	s_or_b32 s1, s62, 10
	s_max_i32 s0, s62, -6
	s_min_i32 s1, s1, s35
	s_sub_i32 s0, s1, s0
	s_add_i32 s0, s0, -6
	v_cvt_f32_i32_e32 v127, s0
	global_store_short v[128:129], v130, off offset:2048
	v_sub_f32_e32 v125, v95, v125
	v_rcp_iflag_f32_e32 v127, v127
	s_nop 0
	v_cndmask_b32_e32 v127, v127, v241, vcc
	v_fma_f32 v127, v97, v127, -v124
	v_cvt_pk_bf16_f32 v127, v127, s0
	s_mov_b32 s0, 0x1ec08000
	v_add_co_u32_e64 v128, s[0:1], s0, v72
	v_add_f32_e32 v97, v97, v126
	s_nop 0
	v_addc_co_u32_e64 v129, s[0:1], 0, v73, s[0:1]
	s_or_b32 s1, s62, 11
	s_max_i32 s0, s62, -7
	s_min_i32 s1, s1, s35
	s_sub_i32 s0, s1, s0
	s_add_i32 s0, s0, -7
	v_cvt_f32_i32_e32 v126, s0
	global_store_short v[128:129], v127, off offset:2048
	v_sub_f32_e32 v124, v94, v124
	v_rcp_iflag_f32_e32 v126, v126
	s_nop 0
	v_cndmask_b32_e32 v126, v126, v241, vcc
	v_fma_f32 v126, v97, v126, -v123
	v_cvt_pk_bf16_f32 v128, v126, s0
	s_mov_b32 s0, 0x1ec09000
	v_add_co_u32_e64 v126, s[0:1], s0, v72
	v_add_f32_e32 v97, v97, v125
	s_nop 0
	v_addc_co_u32_e64 v127, s[0:1], 0, v73, s[0:1]
	s_or_b32 s1, s62, 12
	s_max_i32 s0, s62, -8
	s_min_i32 s1, s1, s35
	s_sub_i32 s0, s1, s0
	s_add_i32 s0, s0, -8
	v_cvt_f32_i32_e32 v125, s0
	global_store_short v[126:127], v128, off offset:2048
	v_sub_f32_e32 v123, v93, v123
	v_rcp_iflag_f32_e32 v125, v125
	s_nop 0
	v_cndmask_b32_e32 v125, v125, v241, vcc
	v_fma_f32 v125, v97, v125, -v122
	v_cvt_pk_bf16_f32 v125, v125, s0
	s_mov_b32 s0, 0x1ec0a000
	v_add_co_u32_e64 v126, s[0:1], s0, v72
	v_add_f32_e32 v97, v97, v124
	s_nop 0
	v_addc_co_u32_e64 v127, s[0:1], 0, v73, s[0:1]
	s_or_b32 s1, s62, 13
	s_max_i32 s0, s62, -9
	s_min_i32 s1, s1, s35
	s_sub_i32 s0, s1, s0
	s_add_i32 s0, s0, -9
	v_cvt_f32_i32_e32 v124, s0
	global_store_short v[126:127], v125, off offset:2048
	v_sub_f32_e32 v122, v92, v122
	v_rcp_iflag_f32_e32 v124, v124
	s_nop 0
	v_cndmask_b32_e32 v124, v124, v241, vcc
	v_fma_f32 v124, v97, v124, -v95
	v_cvt_pk_bf16_f32 v126, v124, s0
	s_mov_b32 s0, 0x1ec0b000
	v_add_co_u32_e64 v124, s[0:1], s0, v72
	v_add_f32_e32 v97, v97, v123
	s_nop 0
	v_addc_co_u32_e64 v125, s[0:1], 0, v73, s[0:1]
	s_or_b32 s1, s62, 14
	s_max_i32 s0, s62, -10
	s_min_i32 s1, s1, s35
	s_sub_i32 s0, s1, s0
	s_add_i32 s0, s0, -10
	v_cvt_f32_i32_e32 v123, s0
	global_store_short v[124:125], v126, off offset:2048
	v_sub_f32_e32 v95, v91, v95
	v_rcp_iflag_f32_e32 v123, v123
	s_nop 0
	v_cndmask_b32_e32 v123, v123, v241, vcc
	v_fma_f32 v123, v97, v123, -v94
	v_cvt_pk_bf16_f32 v123, v123, s0
	s_mov_b32 s0, 0x1ec0c000
	v_add_co_u32_e64 v124, s[0:1], s0, v72
	v_add_f32_e32 v97, v97, v122
	s_nop 0
	v_addc_co_u32_e64 v125, s[0:1], 0, v73, s[0:1]
	s_or_b32 s1, s62, 15
	s_max_i32 s0, s62, -11
	s_min_i32 s1, s1, s35
	s_sub_i32 s0, s1, s0
	s_add_i32 s0, s0, -11
	v_cvt_f32_i32_e32 v122, s0
	global_store_short v[124:125], v123, off offset:2048
	v_add_f32_e32 v95, v97, v95
	v_sub_f32_e32 v94, v90, v94
	v_rcp_iflag_f32_e32 v122, v122
	s_nop 0
	v_cndmask_b32_e32 v122, v122, v241, vcc
	v_fma_f32 v122, v97, v122, -v93
	v_cvt_pk_bf16_f32 v124, v122, s0
	s_mov_b32 s0, 0x1ec0d000
	v_add_co_u32_e64 v122, s[0:1], s0, v72
	v_sub_f32_e32 v93, v89, v93
	s_nop 0
	v_addc_co_u32_e64 v123, s[0:1], 0, v73, s[0:1]
	s_or_b32 s1, s62, 16
	s_max_i32 s0, s62, -12
	s_min_i32 s1, s1, s35
	s_sub_i32 s0, s1, s0
	s_add_i32 s0, s0, -12
	v_cvt_f32_i32_e32 v97, s0
	global_store_short v[122:123], v124, off offset:2048
	v_rcp_iflag_f32_e32 v97, v97
	s_nop 0
	v_cndmask_b32_e32 v97, v97, v241, vcc
	v_fma_f32 v97, v95, v97, -v92
	v_cvt_pk_bf16_f32 v97, v97, s0
	s_mov_b32 s0, 0x1ec0e000
	v_add_co_u32_e64 v122, s[0:1], s0, v72
	v_sub_f32_e32 v92, v88, v92
	s_nop 0
	v_addc_co_u32_e64 v123, s[0:1], 0, v73, s[0:1]
	s_or_b32 s1, s62, 17
	s_max_i32 s0, s62, -13
	s_min_i32 s1, s1, s35
	s_sub_i32 s0, s1, s0
	s_add_i32 s0, s0, -13
	global_store_short v[122:123], v97, off offset:2048
	v_add_f32_e32 v97, v95, v94
	v_cvt_f32_i32_e32 v94, s0
	v_add_f32_e32 v93, v97, v93
	v_rcp_iflag_f32_e32 v94, v94
	s_nop 0
	v_cndmask_b32_e32 v94, v94, v241, vcc
	v_fma_f32 v94, v97, v94, -v91
	v_cvt_pk_bf16_f32 v122, v94, s0
	s_mov_b32 s0, 0x1ec0f000
	v_add_co_u32_e64 v94, s[0:1], s0, v72
	v_sub_f32_e32 v91, v87, v91
	s_nop 0
	v_addc_co_u32_e64 v95, s[0:1], 0, v73, s[0:1]
	s_or_b32 s1, s62, 18
	s_max_i32 s0, s62, -14
	s_min_i32 s1, s1, s35
	s_sub_i32 s0, s1, s0
	s_add_i32 s0, s0, -14
	global_store_short v[94:95], v122, off offset:2048
	v_cvt_f32_i32_e32 v94, s0
	v_rcp_iflag_f32_e32 v94, v94
	s_nop 0
	v_cndmask_b32_e32 v94, v94, v241, vcc
	v_fma_f32 v94, v93, v94, -v90
	v_cvt_pk_bf16_f32 v97, v94, s0
	s_mov_b32 s0, 0x1ec10000
	v_add_co_u32_e64 v94, s[0:1], s0, v72
	v_sub_f32_e32 v90, v86, v90
	s_nop 0
	v_addc_co_u32_e64 v95, s[0:1], 0, v73, s[0:1]
	s_or_b32 s1, s62, 19
	s_max_i32 s0, s62, -15
	s_min_i32 s1, s1, s35
	s_sub_i32 s0, s1, s0
	s_add_i32 s0, s0, -15
	global_store_short v[94:95], v97, off offset:2048
	v_add_f32_e32 v94, v93, v92
	v_cvt_f32_i32_e32 v92, s0
	v_add_f32_e32 v91, v94, v91
	v_rcp_iflag_f32_e32 v92, v92
	s_nop 0
	v_cndmask_b32_e32 v92, v92, v241, vcc
	v_fma_f32 v92, v94, v92, -v89
	v_cvt_pk_bf16_f32 v95, v92, s0
	s_mov_b32 s0, 0x1ec11000
	v_add_co_u32_e64 v92, s[0:1], s0, v72
	v_sub_f32_e32 v89, v85, v89
	s_nop 0
	v_addc_co_u32_e64 v93, s[0:1], 0, v73, s[0:1]
	s_or_b32 s1, s62, 20
	s_max_i32 s0, s62, -16
	s_min_i32 s1, s1, s35
	s_sub_i32 s0, s1, s0
	s_add_i32 s0, s0, -16
	global_store_short v[92:93], v95, off offset:2048
	v_cvt_f32_i32_e32 v92, s0
	v_rcp_iflag_f32_e32 v92, v92
	s_nop 0
	v_cndmask_b32_e32 v92, v92, v241, vcc
	v_fma_f32 v92, v91, v92, -v88
	v_cvt_pk_bf16_f32 v94, v92, s0
	s_mov_b32 s0, 0x1ec12000
	v_add_co_u32_e64 v92, s[0:1], s0, v72
	v_sub_f32_e32 v88, v83, v88
	s_nop 0
	v_addc_co_u32_e64 v93, s[0:1], 0, v73, s[0:1]
	s_or_b32 s1, s62, 21
	s_max_i32 s0, s62, 0xffffffef
	s_min_i32 s1, s1, s35
	s_sub_i32 s0, s1, s0
	s_sub_i32 s0, s0, 17
	global_store_short v[92:93], v94, off offset:2048
	v_add_f32_e32 v92, v91, v90
	v_cvt_f32_i32_e32 v90, s0
	v_add_f32_e32 v89, v92, v89
	v_rcp_iflag_f32_e32 v90, v90
	s_nop 0
	v_cndmask_b32_e32 v90, v90, v241, vcc
	v_fma_f32 v90, v92, v90, -v87
	v_cvt_pk_bf16_f32 v93, v90, s0
	s_mov_b32 s0, 0x1ec13000
	v_add_co_u32_e64 v90, s[0:1], s0, v72
	v_sub_f32_e32 v87, v82, v87
	s_nop 0
	v_addc_co_u32_e64 v91, s[0:1], 0, v73, s[0:1]
	s_or_b32 s1, s62, 22
	s_max_i32 s0, s62, 0xffffffee
	s_min_i32 s1, s1, s35
	s_sub_i32 s0, s1, s0
	s_sub_i32 s0, s0, 18
	global_store_short v[90:91], v93, off offset:2048
	v_cvt_f32_i32_e32 v90, s0
	v_rcp_iflag_f32_e32 v90, v90
	s_nop 0
	v_cndmask_b32_e32 v90, v90, v241, vcc
	v_fma_f32 v90, v89, v90, -v86
	v_cvt_pk_bf16_f32 v92, v90, s0
	s_mov_b32 s0, 0x1ec14000
	v_add_co_u32_e64 v90, s[0:1], s0, v72
	v_sub_f32_e32 v86, v77, v86
	s_nop 0
	v_addc_co_u32_e64 v91, s[0:1], 0, v73, s[0:1]
	s_or_b32 s1, s62, 23
	s_max_i32 s0, s62, 0xffffffed
	s_min_i32 s1, s1, s35
	s_sub_i32 s0, s1, s0
	s_sub_i32 s0, s0, 19
	global_store_short v[90:91], v92, off offset:2048
	v_add_f32_e32 v90, v89, v88
	v_cvt_f32_i32_e32 v88, s0
	v_add_f32_e32 v87, v90, v87
	v_rcp_iflag_f32_e32 v88, v88
	s_nop 0
	v_cndmask_b32_e32 v88, v88, v241, vcc
	v_fma_f32 v88, v90, v88, -v85
	v_cvt_pk_bf16_f32 v91, v88, s0
	s_mov_b32 s0, 0x1ec15000
	v_add_co_u32_e64 v88, s[0:1], s0, v72
	v_sub_f32_e32 v85, v81, v85
	s_nop 0
	v_addc_co_u32_e64 v89, s[0:1], 0, v73, s[0:1]
	s_or_b32 s1, s62, 24
	s_max_i32 s0, s62, 0xffffffec
	s_min_i32 s1, s1, s35
	s_sub_i32 s0, s1, s0
	s_sub_i32 s0, s0, 20
	global_store_short v[88:89], v91, off offset:2048
	v_cvt_f32_i32_e32 v88, s0
	v_rcp_iflag_f32_e32 v88, v88
	s_nop 0
	v_cndmask_b32_e32 v88, v88, v241, vcc
	v_fma_f32 v88, v87, v88, -v83
	v_cvt_pk_bf16_f32 v90, v88, s0
	s_mov_b32 s0, 0x1ec16000
	v_add_co_u32_e64 v88, s[0:1], s0, v72
	v_sub_f32_e32 v83, v80, v83
	s_nop 0
	v_addc_co_u32_e64 v89, s[0:1], 0, v73, s[0:1]
	s_or_b32 s1, s62, 25
	s_max_i32 s0, s62, 0xffffffeb
	s_min_i32 s1, s1, s35
	s_sub_i32 s0, s1, s0
	s_sub_i32 s0, s0, 21
	global_store_short v[88:89], v90, off offset:2048
	v_add_f32_e32 v88, v87, v86
	v_cvt_f32_i32_e32 v86, s0
	v_add_f32_e32 v85, v88, v85
	v_add_f32_e32 v83, v85, v83
	v_lshlrev_b32_e32 v90, 16, v79
	v_rcp_iflag_f32_e32 v86, v86
	s_nop 0
	v_cndmask_b32_e32 v86, v86, v241, vcc
	v_fma_f32 v86, v88, v86, -v82
	v_cvt_pk_bf16_f32 v89, v86, s0
	s_mov_b32 s0, 0x1ec17000
	v_add_co_u32_e64 v86, s[0:1], s0, v72
	v_sub_f32_e32 v82, v78, v82
	s_nop 0
	v_addc_co_u32_e64 v87, s[0:1], 0, v73, s[0:1]
	s_or_b32 s1, s62, 26
	s_max_i32 s0, s62, 0xffffffea
	s_min_i32 s1, s1, s35
	s_sub_i32 s0, s1, s0
	s_sub_i32 s0, s0, 22
	global_store_short v[86:87], v89, off offset:2048
	v_cvt_f32_i32_e32 v86, s0
	v_rcp_iflag_f32_e32 v86, v86
	s_nop 0
	v_cndmask_b32_e32 v86, v86, v241, vcc
	v_fma_f32 v86, v85, v86, -v77
	v_cvt_pk_bf16_f32 v88, v86, s0
	s_mov_b32 s0, 0x1ec18000
	v_add_co_u32_e64 v86, s[0:1], s0, v72
	v_sub_f32_e32 v77, v90, v77
	s_nop 0
	v_addc_co_u32_e64 v87, s[0:1], 0, v73, s[0:1]
	s_or_b32 s1, s62, 27
	s_max_i32 s0, s62, 0xffffffe9
	s_min_i32 s1, s1, s35
	s_sub_i32 s0, s1, s0
	s_sub_i32 s0, s0, 23
	v_cvt_f32_i32_e32 v85, s0
	global_store_short v[86:87], v88, off offset:2048
	v_rcp_iflag_f32_e32 v85, v85
	s_nop 0
	v_cndmask_b32_e32 v85, v85, v241, vcc
	v_fma_f32 v85, v83, v85, -v81
	v_cvt_pk_bf16_f32 v85, v85, s0
	s_mov_b32 s0, 0x1ec19000
	v_add_co_u32_e64 v86, s[0:1], s0, v72
	v_sub_f32_e32 v81, v76, v81
	s_nop 0
	v_addc_co_u32_e64 v87, s[0:1], 0, v73, s[0:1]
	s_or_b32 s1, s62, 28
	s_max_i32 s0, s62, 0xffffffe8
	s_min_i32 s1, s1, s35
	s_sub_i32 s0, s1, s0
	s_sub_i32 s0, s0, 24
	global_store_short v[86:87], v85, off offset:2048
	v_add_f32_e32 v85, v83, v82
	v_cvt_f32_i32_e32 v82, s0
	v_add_f32_e32 v77, v85, v77
	v_sub_f32_e32 v87, v69, v78
	v_rcp_iflag_f32_e32 v82, v82
	s_nop 0
	v_cndmask_b32_e32 v82, v82, v241, vcc
	v_fma_f32 v82, v85, v82, -v80
	v_cvt_pk_bf16_f32 v86, v82, s0
	s_mov_b32 s0, 0x1ec1a000
	v_add_co_u32_e64 v82, s[0:1], s0, v72
	v_sub_f32_e32 v80, v75, v80
	s_nop 0
	v_addc_co_u32_e64 v83, s[0:1], 0, v73, s[0:1]
	s_or_b32 s1, s62, 29
	s_max_i32 s0, s62, 0xffffffe7
	s_min_i32 s1, s1, s35
	s_sub_i32 s0, s1, s0
	s_sub_i32 s0, s0, 25
	s_or_b32 s1, s62, 30
	global_store_short v[82:83], v86, off offset:2048
	v_cvt_f32_i32_e32 v82, s0
	s_max_i32 s0, s62, 0xffffffe6
	s_min_i32 s1, s1, s35
	s_sub_i32 s0, s1, s0
	s_sub_i32 s0, s0, 26
	s_or_b32 s1, s62, 31
	v_cvt_f32_i32_e32 v83, s0
	s_max_i32 s0, s62, 0xffffffe5
	s_min_i32 s1, s1, s35
	s_sub_i32 s0, s1, s0
	s_sub_i32 s0, s0, 27
	s_add_i32 s1, s62, 32
	v_cvt_f32_i32_e32 v86, s0
	s_max_i32 s0, s62, 0xffffffe4
	s_min_i32 s1, s1, s35
	s_sub_i32 s0, s1, s0
	s_sub_i32 s0, s0, 28
	v_cvt_f32_i32_e32 v88, s0
	s_max_i32 s0, s62, 0xffffffe3
	s_min_i32 s1, s63, s35
	s_sub_i32 s0, s1, s0
	s_sub_i32 s0, s0, 29
	v_cvt_f32_i32_e32 v89, s0
	v_rcp_iflag_f32_e32 v82, v82
	v_rcp_iflag_f32_e32 v83, v83
	v_rcp_iflag_f32_e32 v86, v86
	v_rcp_iflag_f32_e32 v88, v88
	v_rcp_iflag_f32_e32 v89, v89
	v_cndmask_b32_e32 v82, v82, v241, vcc
	v_fma_f32 v78, v77, v82, -v78
	v_cvt_pk_bf16_f32 v82, v78, s0
	s_mov_b32 s0, 0x1ec1b000
	v_cndmask_b32_e32 v83, v83, v241, vcc
	v_cndmask_b32_e32 v86, v86, v241, vcc
	v_cndmask_b32_e32 v88, v88, v241, vcc
	v_cndmask_b32_e32 v89, v89, v241, vcc
	v_add_co_u32_e32 v78, vcc, s0, v72
	v_add_f32_e32 v77, v77, v81
	s_nop 0
	v_addc_co_u32_e32 v79, vcc, 0, v73, vcc
	global_store_short v[78:79], v82, off offset:2048
	v_fma_f32 v78, v77, v83, -v90
	v_cvt_pk_bf16_f32 v81, v78, s0
	s_mov_b32 s0, 0x1ec1c000
	v_add_co_u32_e32 v78, vcc, s0, v72
	s_nop 1
	v_addc_co_u32_e32 v79, vcc, 0, v73, vcc
	global_store_short v[78:79], v81, off offset:2048
	v_add_f32_e32 v78, v77, v80
	v_fma_f32 v76, v78, v86, -v76
	v_cvt_pk_bf16_f32 v79, v76, s0
	v_add_co_u32_e32 v76, vcc, 0x1ec1d000, v72
	s_nop 1
	v_addc_co_u32_e32 v77, vcc, 0, v73, vcc
	global_store_short v[76:77], v79, off offset:2048
	v_add_f32_e32 v76, v78, v87
	v_fma_f32 v75, v76, v88, -v75
	v_add_co_u32_e32 v72, vcc, 0x1ec1e000, v72
	v_cvt_pk_bf16_f32 v75, v75, s0
	s_nop 0
	v_addc_co_u32_e32 v73, vcc, 0, v73, vcc
	global_store_short v[72:73], v75, off offset:2048
	v_sub_f32_e32 v72, v84, v90
	v_add_f32_e32 v72, v76, v72
	v_fma_f32 v69, v72, v89, -v69

.LBB0_398:
	s_andn2_saveexec_b64 s[86:87], s[86:87]
	v_cmp_ne_u32_e32 vcc, 0, v180
	s_andn2_b64 s[0:1], s[0:1], exec
	s_and_b64 s[12:13], vcc, exec
	s_or_b64 s[0:1], s[0:1], s[12:13]
	s_mov_b64 s[84:85], exec
	s_or_b64 exec, exec, s[86:87]
	v_ashrrev_i32_e32 v97, 31, v96
	v_lshl_add_u32 v182, v96, 1, 0
	s_and_saveexec_b64 s[12:13], s[0:1]
	s_xor_b64 s[86:87], exec, s[12:13]
	s_cbranch_execz .LBB0_402
	ds_read_u16 v146, v182
	ds_read_u16 v145, v182 offset:1024
	ds_read_u16 v144, v182 offset:2048
	ds_read_u16 v143, v182 offset:3072
	ds_read_u16 v142, v182 offset:4096
	ds_read_u16 v141, v182 offset:5120
	ds_read_u16 v140, v182 offset:6144
	ds_read_u16 v139, v182 offset:7168
	ds_read_u16 v138, v182 offset:8192
	ds_read_u16 v137, v182 offset:9216
	ds_read_u16 v136, v182 offset:10240
	ds_read_u16 v135, v182 offset:11264
	ds_read_u16 v134, v182 offset:12288
	ds_read_u16 v132, v182 offset:13312
	ds_read_u16 v83, v182 offset:14336
	ds_read_u16 v124, v182 offset:15360
	ds_read_u16 v123, v182 offset:16384
	ds_read_u16 v122, v182 offset:17408
	ds_read_u16 v95, v182 offset:18432
	ds_read_u16 v93, v182 offset:19456
	ds_read_u16 v90, v182 offset:20480
	ds_read_u16 v82, v182 offset:31744
	ds_read_u16 v81, v182 offset:32768
	ds_read_u16 v80, v182 offset:33792
	ds_read_u16 v79, v182 offset:34816
	ds_read_u16 v78, v182 offset:35840
	ds_read_u16 v77, v182 offset:36864
	ds_read_u16 v87, v182 offset:21504
	ds_read_u16 v76, v182 offset:37888
	ds_read_u16 v85, v182 offset:22528
	ds_read_u16 v75, v182 offset:38912
	ds_read_u16 v84, v182 offset:23552
	ds_read_u16 v86, v182 offset:24576
	ds_read_u16 v131, v182 offset:40960
	ds_read_u16 v88, v182 offset:25600
	ds_read_u16 v130, v182 offset:41984
	ds_read_u16 v89, v182 offset:26624
	ds_read_u16 v128, v182 offset:43008
	ds_read_u16 v91, v182 offset:27648
	ds_read_u16 v129, v182 offset:44032
	ds_read_u16 v92, v182 offset:28672
	ds_read_u16 v126, v182 offset:45056
	ds_read_u16 v94, v182 offset:29696
	ds_read_u16 v127, v182 offset:46080
	s_cmp_gt_i32 s62, 7
	s_cselect_b64 s[0:1], -1, 0
	s_add_i32 s63, s62, 39
	s_cmp_le_i32 s63, s35
	s_waitcnt lgkmcnt(0)
	v_lshlrev_b32_e32 v146, 16, v146
	s_cselect_b64 s[12:13], -1, 0
	s_ashr_i32 s75, s74, 31
	s_and_b64 vcc, s[0:1], s[12:13]
	s_lshl_b64 s[0:1], s[74:75], 12
	s_waitcnt lgkmcnt(0)
	v_lshlrev_b32_e32 v145, 16, v145
	s_add_u32 s0, s94, s0
	s_addc_u32 s1, s95, s1
	v_lshl_add_u64 v[72:73], v[96:97], 1, s[0:1]
	s_mov_b64 s[0:1], 0x1ec00800
	s_waitcnt lgkmcnt(0)
	v_lshlrev_b32_e32 v144, 16, v144
	s_waitcnt lgkmcnt(0)
	v_lshlrev_b32_e32 v143, 16, v143
	s_waitcnt lgkmcnt(0)
	v_lshlrev_b32_e32 v142, 16, v142
	s_waitcnt lgkmcnt(0)
	v_lshlrev_b32_e32 v141, 16, v141
	s_waitcnt lgkmcnt(0)
	v_lshlrev_b32_e32 v140, 16, v140
	s_waitcnt lgkmcnt(0)
	v_lshlrev_b32_e32 v139, 16, v139
	s_waitcnt lgkmcnt(0)
	v_lshlrev_b32_e32 v138, 16, v138
	s_waitcnt lgkmcnt(0)
	v_lshlrev_b32_e32 v137, 16, v137
	s_waitcnt lgkmcnt(0)
	v_lshlrev_b32_e32 v136, 16, v136
	s_waitcnt lgkmcnt(0)
	v_lshlrev_b32_e32 v135, 16, v135
	s_waitcnt lgkmcnt(0)
	v_lshlrev_b32_e32 v134, 16, v134
	s_waitcnt lgkmcnt(0)
	v_lshlrev_b32_e32 v132, 16, v132
	s_waitcnt lgkmcnt(0)
	v_lshlrev_b32_e32 v83, 16, v83
	s_waitcnt lgkmcnt(0)
	v_lshlrev_b32_e32 v124, 16, v124
	s_waitcnt lgkmcnt(0)
	v_lshlrev_b32_e32 v123, 16, v123
	s_waitcnt lgkmcnt(0)
	v_lshlrev_b32_e32 v122, 16, v122
	s_waitcnt lgkmcnt(0)
	v_lshlrev_b32_e32 v95, 16, v95
	s_waitcnt lgkmcnt(0)
	v_lshlrev_b32_e32 v93, 16, v93
	s_waitcnt lgkmcnt(0)
	v_lshlrev_b32_e32 v90, 16, v90
	s_waitcnt lgkmcnt(0)
	v_lshlrev_b32_e32 v82, 16, v82
	s_waitcnt lgkmcnt(0)
	v_lshlrev_b32_e32 v81, 16, v81
	s_waitcnt lgkmcnt(0)
	v_lshlrev_b32_e32 v80, 16, v80
	s_waitcnt lgkmcnt(0)
	v_lshlrev_b32_e32 v79, 16, v79
	s_waitcnt lgkmcnt(0)
	v_lshlrev_b32_e32 v78, 16, v78
	s_waitcnt lgkmcnt(0)
	v_lshlrev_b32_e32 v77, 16, v77
	s_waitcnt lgkmcnt(0)
	v_lshlrev_b32_e32 v87, 16, v87
	s_waitcnt lgkmcnt(0)
	v_lshlrev_b32_e32 v76, 16, v76
	s_waitcnt lgkmcnt(0)
	v_lshlrev_b32_e32 v85, 16, v85
	s_waitcnt lgkmcnt(0)
	v_lshlrev_b32_e32 v75, 16, v75
	ds_read_u16 v69, v182 offset:39936
	s_waitcnt lgkmcnt(0)
	v_lshlrev_b32_e32 v84, 16, v84
	s_waitcnt lgkmcnt(0)
	v_lshlrev_b32_e32 v69, 16, v69
	s_waitcnt lgkmcnt(0)
	v_lshlrev_b32_e32 v86, 16, v86
	s_waitcnt lgkmcnt(0)
	v_lshlrev_b32_e32 v131, 16, v131
	v_sub_f32_e32 v131, v131, v86
	s_waitcnt lgkmcnt(0)
	v_lshlrev_b32_e32 v88, 16, v88
	s_waitcnt lgkmcnt(0)
	v_lshlrev_b32_e32 v130, 16, v130
	v_sub_f32_e32 v130, v130, v88
	s_waitcnt lgkmcnt(0)
	v_lshlrev_b32_e32 v89, 16, v89
	s_waitcnt lgkmcnt(0)
	v_lshlrev_b32_e32 v128, 16, v128
	v_sub_f32_e32 v128, v128, v89
	s_waitcnt lgkmcnt(0)
	v_lshlrev_b32_e32 v91, 16, v91
	s_waitcnt lgkmcnt(0)
	v_lshlrev_b32_e32 v129, 16, v129
	v_sub_f32_e32 v129, v129, v91
	s_waitcnt lgkmcnt(0)
	v_lshlrev_b32_e32 v92, 16, v92
	s_waitcnt lgkmcnt(0)
	v_lshlrev_b32_e32 v126, 16, v126
	v_sub_f32_e32 v126, v126, v92
	s_waitcnt lgkmcnt(0)
	v_lshlrev_b32_e32 v94, 16, v94
	v_add_f32_e32 v70, 0, v146
	v_add_f32_e32 v70, v70, v145
	v_add_f32_e32 v70, v70, v144
	v_add_f32_e32 v70, v70, v143
	v_add_f32_e32 v70, v70, v142
	v_add_f32_e32 v70, v70, v141
	v_add_f32_e32 v70, v70, v140
	v_add_f32_e32 v70, v70, v139
	v_add_f32_e32 v70, v70, v138
	v_add_f32_e32 v70, v70, v137
	v_add_f32_e32 v70, v70, v136
	v_add_f32_e32 v70, v70, v135
	v_add_f32_e32 v70, v70, v134
	v_add_f32_e32 v70, v70, v132
	v_add_f32_e32 v70, v70, v83
	s_waitcnt lgkmcnt(0)
	v_lshlrev_b32_e32 v127, 16, v127
	v_add_f32_e32 v147, v70, v124
	v_lshl_add_u64 v[70:71], v[72:73], 0, s[0:1]
	s_or_b32 s1, s62, 8
	s_max_i32 s0, s62, 8
	s_min_i32 s1, s1, s35
	s_sub_i32 s0, s1, s0
	s_add_i32 s0, s0, 8
	v_cvt_f32_i32_e32 v125, s0
	v_sub_f32_e32 v146, v123, v146
	v_sub_f32_e32 v145, v122, v145
	v_sub_f32_e32 v144, v95, v144
	v_rcp_iflag_f32_e32 v125, v125
	v_sub_f32_e32 v143, v93, v143
	v_sub_f32_e32 v142, v90, v142
	v_sub_f32_e32 v141, v87, v141
	v_cndmask_b32_e32 v125, v125, v242, vcc
	v_fma_f32 v125, v147, v125, -v138
	v_cvt_pk_bf16_f32 v150, v125, s0
	s_mov_b32 s0, 0x1ec00000
	v_add_co_u32_e64 v148, s[0:1], s0, v72
	ds_read_u16 v125, v182 offset:30720
	ds_read_u16 v133, v182 offset:47104
	v_addc_co_u32_e64 v149, s[0:1], 0, v73, s[0:1]
	s_or_b32 s1, s62, 9
	s_max_i32 s0, s62, 7
	s_min_i32 s1, s1, s35
	s_sub_i32 s0, s1, s0
	s_add_i32 s0, s0, 7
	global_store_short v[148:149], v150, off offset:2048
	v_add_f32_e32 v148, v147, v146
	v_cvt_f32_i32_e32 v146, s0
	v_add_f32_e32 v145, v148, v145
	v_sub_f32_e32 v140, v85, v140
	v_sub_f32_e32 v139, v84, v139
	v_rcp_iflag_f32_e32 v146, v146
	v_sub_f32_e32 v138, v86, v138
	s_waitcnt lgkmcnt(1)
	v_lshlrev_b32_e32 v125, 16, v125
	v_sub_f32_e32 v127, v127, v94
	v_cndmask_b32_e32 v146, v146, v242, vcc
	v_fma_f32 v146, v148, v146, -v137
	v_cvt_pk_bf16_f32 v149, v146, s0
	s_mov_b32 s0, 0x1ec01000
	v_add_co_u32_e64 v146, s[0:1], s0, v72
	v_sub_f32_e32 v137, v88, v137
	s_nop 0
	v_addc_co_u32_e64 v147, s[0:1], 0, v73, s[0:1]
	s_or_b32 s1, s62, 10
	s_max_i32 s0, s62, 6
	s_min_i32 s1, s1, s35
	s_sub_i32 s0, s1, s0
	s_add_i32 s0, s0, 6
	global_store_short v[146:147], v149, off offset:2048
	v_cvt_f32_i32_e32 v146, s0
	s_waitcnt lgkmcnt(0)
	v_lshlrev_b32_e32 v133, 16, v133
	v_rcp_iflag_f32_e32 v146, v146
	s_nop 0
	v_cndmask_b32_e32 v146, v146, v242, vcc
	v_fma_f32 v146, v145, v146, -v136
	v_cvt_pk_bf16_f32 v148, v146, s0
	s_mov_b32 s0, 0x1ec02000
	v_add_co_u32_e64 v146, s[0:1], s0, v72
	v_sub_f32_e32 v136, v89, v136
	s_nop 0
	v_addc_co_u32_e64 v147, s[0:1], 0, v73, s[0:1]
	s_or_b32 s1, s62, 11
	s_max_i32 s0, s62, 5
	s_min_i32 s1, s1, s35
	s_sub_i32 s0, s1, s0
	s_add_i32 s0, s0, 5
	global_store_short v[146:147], v148, off offset:2048
	v_add_f32_e32 v146, v145, v144
	v_cvt_f32_i32_e32 v144, s0
	v_add_f32_e32 v143, v146, v143
	v_rcp_iflag_f32_e32 v144, v144
	s_nop 0
	v_cndmask_b32_e32 v144, v144, v242, vcc
	v_fma_f32 v144, v146, v144, -v135
	v_cvt_pk_bf16_f32 v147, v144, s0
	s_mov_b32 s0, 0x1ec03000
	v_add_co_u32_e64 v144, s[0:1], s0, v72
	v_sub_f32_e32 v135, v91, v135
	s_nop 0
	v_addc_co_u32_e64 v145, s[0:1], 0, v73, s[0:1]
	s_or_b32 s1, s62, 12
	s_max_i32 s0, s62, 4
	s_min_i32 s1, s1, s35
	s_sub_i32 s0, s1, s0
	s_add_i32 s0, s0, 4
	global_store_short v[144:145], v147, off offset:2048
	v_cvt_f32_i32_e32 v144, s0
	v_rcp_iflag_f32_e32 v144, v144
	s_nop 0
	v_cndmask_b32_e32 v144, v144, v242, vcc
	v_fma_f32 v144, v143, v144, -v134
	v_cvt_pk_bf16_f32 v146, v144, s0
	s_mov_b32 s0, 0x1ec04000
	v_add_co_u32_e64 v144, s[0:1], s0, v72
	v_sub_f32_e32 v134, v92, v134
	s_nop 0
	v_addc_co_u32_e64 v145, s[0:1], 0, v73, s[0:1]
	s_or_b32 s1, s62, 13
	s_max_i32 s0, s62, 3
	s_min_i32 s1, s1, s35
	s_sub_i32 s0, s1, s0
	s_add_i32 s0, s0, 3
	global_store_short v[144:145], v146, off offset:2048
	v_add_f32_e32 v144, v143, v142
	v_cvt_f32_i32_e32 v142, s0
	v_add_f32_e32 v141, v144, v141
	v_rcp_iflag_f32_e32 v142, v142
	s_nop 0
	v_cndmask_b32_e32 v142, v142, v242, vcc
	v_fma_f32 v142, v144, v142, -v132
	v_cvt_pk_bf16_f32 v145, v142, s0
	s_mov_b32 s0, 0x1ec05000
	v_add_co_u32_e64 v142, s[0:1], s0, v72
	v_sub_f32_e32 v132, v94, v132
	s_nop 0
	v_addc_co_u32_e64 v143, s[0:1], 0, v73, s[0:1]
	s_or_b32 s1, s62, 14
	s_max_i32 s0, s62, 2
	s_min_i32 s1, s1, s35
	s_sub_i32 s0, s1, s0
	s_add_i32 s0, s0, 2
	global_store_short v[142:143], v145, off offset:2048
	v_cvt_f32_i32_e32 v142, s0
	v_rcp_iflag_f32_e32 v142, v142
	s_nop 0
	v_cndmask_b32_e32 v142, v142, v242, vcc
	v_fma_f32 v142, v141, v142, -v83
	v_cvt_pk_bf16_f32 v144, v142, s0
	s_mov_b32 s0, 0x1ec06000
	v_add_co_u32_e64 v142, s[0:1], s0, v72
	v_sub_f32_e32 v83, v125, v83
	s_nop 0
	v_addc_co_u32_e64 v143, s[0:1], 0, v73, s[0:1]
	s_or_b32 s1, s62, 15
	s_max_i32 s0, s62, 1
	s_min_i32 s1, s1, s35
	s_sub_i32 s0, s1, s0
	s_add_i32 s0, s0, 1
	global_store_short v[142:143], v144, off offset:2048
	v_add_f32_e32 v142, v141, v140
	v_cvt_f32_i32_e32 v140, s0
	v_add_f32_e32 v139, v142, v139
	v_sub_f32_e32 v144, v69, v84
	v_rcp_iflag_f32_e32 v140, v140
	s_nop 0
	v_cndmask_b32_e32 v140, v140, v242, vcc
	v_fma_f32 v140, v142, v140, -v124
	v_cvt_pk_bf16_f32 v143, v140, s0
	s_mov_b32 s0, 0x1ec07000
	v_add_co_u32_e64 v140, s[0:1], s0, v72
	v_sub_f32_e32 v124, v82, v124
	s_nop 0
	v_addc_co_u32_e64 v141, s[0:1], 0, v73, s[0:1]
	s_or_b32 s1, s62, 16
	s_max_i32 s0, s62, 0
	s_min_i32 s1, s1, s35
	s_sub_i32 s0, s1, s0
	global_store_short v[140:141], v143, off offset:2048
	v_cvt_f32_i32_e32 v140, s0
	v_rcp_iflag_f32_e32 v140, v140
	s_nop 0
	v_cndmask_b32_e32 v140, v140, v242, vcc
	v_fma_f32 v140, v139, v140, -v123
	v_cvt_pk_bf16_f32 v142, v140, s0
	s_mov_b32 s0, 0x1ec08000
	v_add_co_u32_e64 v140, s[0:1], s0, v72
	v_sub_f32_e32 v123, v81, v123
	s_nop 0
	v_addc_co_u32_e64 v141, s[0:1], 0, v73, s[0:1]
	s_or_b32 s0, s62, 17
	s_min_i32 s0, s0, s35
	s_not_b32 s1, s62
	s_cmp_gt_i32 s62, -1
	s_cselect_b32 s1, s1, 0
	s_add_i32 s0, s0, s1
	global_store_short v[140:141], v142, off offset:2048
	v_add_f32_e32 v140, v139, v138
	v_cvt_f32_i32_e32 v138, s0
	v_add_f32_e32 v137, v140, v137
	v_sub_f32_e32 v142, v75, v85
	s_andn2_b64 s[84:85], s[84:85], exec
	v_rcp_iflag_f32_e32 v138, v138
	s_nop 0
	v_cndmask_b32_e32 v138, v138, v242, vcc
	v_fma_f32 v138, v140, v138, -v122
	v_cvt_pk_bf16_f32 v141, v138, s0
	s_mov_b32 s0, 0x1ec09000
	v_add_co_u32_e64 v138, s[0:1], s0, v72
	v_sub_f32_e32 v122, v80, v122
	s_nop 0
	v_addc_co_u32_e64 v139, s[0:1], 0, v73, s[0:1]
	s_or_b32 s1, s62, 18
	s_max_i32 s0, s62, -2
	s_min_i32 s1, s1, s35
	s_sub_i32 s0, s1, s0
	s_add_i32 s0, s0, -2
	global_store_short v[138:139], v141, off offset:2048
	v_cvt_f32_i32_e32 v138, s0
	v_rcp_iflag_f32_e32 v138, v138
	s_nop 0
	v_cndmask_b32_e32 v138, v138, v242, vcc
	v_fma_f32 v138, v137, v138, -v95
	v_cvt_pk_bf16_f32 v140, v138, s0
	s_mov_b32 s0, 0x1ec0a000
	v_add_co_u32_e64 v138, s[0:1], s0, v72
	v_sub_f32_e32 v95, v79, v95
	s_nop 0
	v_addc_co_u32_e64 v139, s[0:1], 0, v73, s[0:1]
	s_or_b32 s1, s62, 19
	s_max_i32 s0, s62, -3
	s_min_i32 s1, s1, s35
	s_sub_i32 s0, s1, s0
	s_add_i32 s0, s0, -3
	global_store_short v[138:139], v140, off offset:2048
	v_add_f32_e32 v138, v137, v136
	v_cvt_f32_i32_e32 v136, s0
	v_add_f32_e32 v135, v138, v135
	v_rcp_iflag_f32_e32 v136, v136
	s_nop 0
	v_cndmask_b32_e32 v136, v136, v242, vcc
	v_fma_f32 v136, v138, v136, -v93
	v_cvt_pk_bf16_f32 v139, v136, s0
	s_mov_b32 s0, 0x1ec0b000
	v_add_co_u32_e64 v136, s[0:1], s0, v72
	v_sub_f32_e32 v93, v78, v93
	s_nop 0
	v_addc_co_u32_e64 v137, s[0:1], 0, v73, s[0:1]
	s_or_b32 s1, s62, 20
	s_max_i32 s0, s62, -4
	s_min_i32 s1, s1, s35
	s_sub_i32 s0, s1, s0
	s_add_i32 s0, s0, -4
	global_store_short v[136:137], v139, off offset:2048
	v_cvt_f32_i32_e32 v136, s0
	v_rcp_iflag_f32_e32 v136, v136
	s_nop 0
	v_cndmask_b32_e32 v136, v136, v242, vcc
	v_fma_f32 v136, v135, v136, -v90
	v_cvt_pk_bf16_f32 v138, v136, s0
	s_mov_b32 s0, 0x1ec0c000
	v_add_co_u32_e64 v136, s[0:1], s0, v72
	v_sub_f32_e32 v90, v77, v90
	s_nop 0
	v_addc_co_u32_e64 v137, s[0:1], 0, v73, s[0:1]
	s_or_b32 s1, s62, 21
	s_max_i32 s0, s62, -5
	s_min_i32 s1, s1, s35
	s_sub_i32 s0, s1, s0
	s_add_i32 s0, s0, -5
	global_store_short v[136:137], v138, off offset:2048
	v_add_f32_e32 v136, v135, v134
	v_cvt_f32_i32_e32 v134, s0
	v_add_f32_e32 v132, v136, v132
	v_add_f32_e32 v83, v132, v83
	v_rcp_iflag_f32_e32 v134, v134
	s_nop 0
	v_cndmask_b32_e32 v134, v134, v242, vcc
	v_fma_f32 v134, v136, v134, -v87
	v_cvt_pk_bf16_f32 v137, v134, s0
	s_mov_b32 s0, 0x1ec0d000
	v_add_co_u32_e64 v134, s[0:1], s0, v72
	v_sub_f32_e32 v87, v76, v87
	s_nop 0
	v_addc_co_u32_e64 v135, s[0:1], 0, v73, s[0:1]
	s_or_b32 s1, s62, 22
	s_max_i32 s0, s62, -6
	s_min_i32 s1, s1, s35
	s_sub_i32 s0, s1, s0
	s_add_i32 s0, s0, -6
	global_store_short v[134:135], v137, off offset:2048
	v_cvt_f32_i32_e32 v134, s0
	v_rcp_iflag_f32_e32 v134, v134
	s_nop 0
	v_cndmask_b32_e32 v134, v134, v242, vcc
	v_fma_f32 v134, v132, v134, -v85
	v_cvt_pk_bf16_f32 v136, v134, s0
	s_mov_b32 s0, 0x1ec0e000
	v_add_co_u32_e64 v134, s[0:1], s0, v72
	s_nop 1
	v_addc_co_u32_e64 v135, s[0:1], 0, v73, s[0:1]
	s_or_b32 s1, s62, 23
	s_max_i32 s0, s62, -7
	s_min_i32 s1, s1, s35
	s_sub_i32 s0, s1, s0
	s_add_i32 s0, s0, -7
	s_or_b32 s1, s62, 24
	global_store_short v[134:135], v136, off offset:2048
	v_cvt_f32_i32_e32 v134, s0
	s_max_i32 s0, s62, -8
	s_min_i32 s1, s1, s35
	s_sub_i32 s0, s1, s0
	s_add_i32 s0, s0, -8
	s_or_b32 s1, s62, 25
	v_cvt_f32_i32_e32 v135, s0
	s_max_i32 s0, s62, -9
	s_min_i32 s1, s1, s35
	s_sub_i32 s0, s1, s0
	s_add_i32 s0, s0, -9
	s_or_b32 s1, s62, 26
	v_cvt_f32_i32_e32 v136, s0
	s_max_i32 s0, s62, -10
	s_min_i32 s1, s1, s35
	s_sub_i32 s0, s1, s0
	s_add_i32 s0, s0, -10
	s_or_b32 s1, s62, 27
	v_cvt_f32_i32_e32 v137, s0
	s_max_i32 s0, s62, -11
	s_min_i32 s1, s1, s35
	s_sub_i32 s0, s1, s0
	s_add_i32 s0, s0, -11
	s_or_b32 s1, s62, 28
	v_cvt_f32_i32_e32 v138, s0
	s_max_i32 s0, s62, -12
	s_min_i32 s1, s1, s35
	s_sub_i32 s0, s1, s0
	s_add_i32 s0, s0, -12
	s_or_b32 s1, s62, 29
	v_cvt_f32_i32_e32 v139, s0
	s_max_i32 s0, s62, -13
	s_min_i32 s1, s1, s35
	s_sub_i32 s0, s1, s0
	s_add_i32 s0, s0, -13
	s_or_b32 s1, s62, 30
	v_cvt_f32_i32_e32 v140, s0
	s_max_i32 s0, s62, -14
	s_min_i32 s1, s1, s35
	s_sub_i32 s0, s1, s0
	s_add_i32 s0, s0, -14
	s_or_b32 s1, s62, 31
	v_cvt_f32_i32_e32 v141, s0
	s_max_i32 s0, s62, -15
	s_min_i32 s1, s1, s35
	s_sub_i32 s0, s1, s0
	s_add_i32 s0, s0, -15
	v_cvt_f32_i32_e32 v85, s0
	s_add_i32 s1, s62, 32
	s_max_i32 s0, s62, -16
	s_min_i32 s1, s1, s35
	v_rcp_iflag_f32_e32 v85, v85
	s_sub_i32 s0, s1, s0
	s_add_i32 s0, s0, -16
	s_add_i32 s1, s62, 33
	v_cndmask_b32_e32 v143, v85, v242, vcc
	v_cvt_f32_i32_e32 v85, s0
	s_max_i32 s0, s62, 0xffffffef
	s_min_i32 s1, s1, s35
	s_sub_i32 s0, s1, s0
	v_rcp_iflag_f32_e32 v85, v85
	s_sub_i32 s0, s0, 17
	s_add_i32 s1, s62, 34
	s_min_i32 s1, s1, s35
	v_cndmask_b32_e32 v145, v85, v242, vcc
	v_cvt_f32_i32_e32 v85, s0
	s_max_i32 s0, s62, 0xffffffee
	s_sub_i32 s0, s1, s0
	s_sub_i32 s0, s0, 18
	v_rcp_iflag_f32_e32 v85, v85
	s_add_i32 s1, s62, 35
	s_min_i32 s1, s1, s35
	v_rcp_iflag_f32_e32 v134, v134
	v_cndmask_b32_e32 v146, v85, v242, vcc
	v_cvt_f32_i32_e32 v85, s0
	s_max_i32 s0, s62, 0xffffffed
	s_sub_i32 s0, s1, s0
	s_sub_i32 s0, s0, 19
	v_rcp_iflag_f32_e32 v85, v85
	s_add_i32 s1, s62, 36
	s_min_i32 s1, s1, s35
	v_rcp_iflag_f32_e32 v135, v135
	v_cndmask_b32_e32 v147, v85, v242, vcc
	v_cvt_f32_i32_e32 v85, s0
	s_max_i32 s0, s62, 0xffffffec
	s_sub_i32 s0, s1, s0
	s_sub_i32 s0, s0, 20
	v_rcp_iflag_f32_e32 v85, v85
	s_add_i32 s1, s62, 37
	s_min_i32 s1, s1, s35
	v_rcp_iflag_f32_e32 v136, v136
	v_cndmask_b32_e32 v148, v85, v242, vcc
	v_cvt_f32_i32_e32 v85, s0
	s_max_i32 s0, s62, 0xffffffeb
	s_sub_i32 s0, s1, s0
	s_sub_i32 s0, s0, 21
	v_rcp_iflag_f32_e32 v85, v85
	s_add_i32 s1, s62, 38
	s_min_i32 s1, s1, s35
	v_rcp_iflag_f32_e32 v137, v137
	v_cndmask_b32_e32 v149, v85, v242, vcc
	v_cvt_f32_i32_e32 v85, s0
	s_max_i32 s0, s62, 0xffffffea
	s_sub_i32 s0, s1, s0
	s_sub_i32 s0, s0, 22
	v_rcp_iflag_f32_e32 v85, v85
	s_min_i32 s1, s63, s35
	v_rcp_iflag_f32_e32 v138, v138
	v_rcp_iflag_f32_e32 v139, v139
	v_cndmask_b32_e32 v150, v85, v242, vcc
	v_cvt_f32_i32_e32 v85, s0
	s_max_i32 s0, s62, 0xffffffe9
	s_sub_i32 s0, s1, s0
	s_sub_i32 s0, s0, 23
	v_rcp_iflag_f32_e32 v85, v85
	v_rcp_iflag_f32_e32 v140, v140
	v_rcp_iflag_f32_e32 v141, v141
	v_cndmask_b32_e32 v134, v134, v242, vcc
	v_cndmask_b32_e32 v151, v85, v242, vcc
	v_cvt_f32_i32_e32 v85, s0
	v_fma_f32 v84, v83, v134, -v84
	v_cvt_pk_bf16_f32 v132, v84, s0
	s_mov_b32 s0, 0x1ec0f000
	v_rcp_iflag_f32_e32 v85, v85
	v_cndmask_b32_e32 v135, v135, v242, vcc
	v_cndmask_b32_e32 v136, v136, v242, vcc
	v_cndmask_b32_e32 v137, v137, v242, vcc
	v_cndmask_b32_e32 v138, v138, v242, vcc
	v_cndmask_b32_e32 v139, v139, v242, vcc
	v_cndmask_b32_e32 v140, v140, v242, vcc
	v_cndmask_b32_e32 v141, v141, v242, vcc
	v_cndmask_b32_e32 v152, v85, v242, vcc
	v_add_co_u32_e32 v84, vcc, s0, v72
	v_add_f32_e32 v83, v83, v124
	s_nop 0
	v_addc_co_u32_e32 v85, vcc, 0, v73, vcc
	global_store_short v[84:85], v132, off offset:2048
	v_fma_f32 v84, v83, v135, -v86
	v_cvt_pk_bf16_f32 v86, v84, s0
	s_mov_b32 s0, 0x1ec10000
	v_add_co_u32_e32 v84, vcc, s0, v72
	v_add_f32_e32 v83, v83, v123
	s_nop 0
	v_addc_co_u32_e32 v85, vcc, 0, v73, vcc
	global_store_short v[84:85], v86, off offset:2048
	v_fma_f32 v84, v83, v136, -v88
	v_cvt_pk_bf16_f32 v86, v84, s0
	s_mov_b32 s0, 0x1ec11000
	v_add_co_u32_e32 v84, vcc, s0, v72
	v_add_f32_e32 v83, v83, v122
	s_nop 0
	v_addc_co_u32_e32 v85, vcc, 0, v73, vcc
	global_store_short v[84:85], v86, off offset:2048
	v_fma_f32 v84, v83, v137, -v89
	v_cvt_pk_bf16_f32 v86, v84, s0
	s_mov_b32 s0, 0x1ec12000
	v_add_co_u32_e32 v84, vcc, s0, v72
	v_add_f32_e32 v83, v83, v95
	s_nop 0
	v_addc_co_u32_e32 v85, vcc, 0, v73, vcc
	global_store_short v[84:85], v86, off offset:2048
	v_fma_f32 v84, v83, v138, -v91
	v_cvt_pk_bf16_f32 v86, v84, s0
	s_mov_b32 s0, 0x1ec13000
	v_add_co_u32_e32 v84, vcc, s0, v72
	v_add_f32_e32 v83, v83, v93
	s_nop 0
	v_addc_co_u32_e32 v85, vcc, 0, v73, vcc
	global_store_short v[84:85], v86, off offset:2048
	v_fma_f32 v84, v83, v139, -v92
	v_cvt_pk_bf16_f32 v86, v84, s0
	s_mov_b32 s0, 0x1ec14000
	v_add_co_u32_e32 v84, vcc, s0, v72
	v_add_f32_e32 v83, v83, v90
	s_nop 0
	v_addc_co_u32_e32 v85, vcc, 0, v73, vcc
	global_store_short v[84:85], v86, off offset:2048
	v_fma_f32 v84, v83, v140, -v94
	v_cvt_pk_bf16_f32 v86, v84, s0
	s_mov_b32 s0, 0x1ec15000
	v_add_co_u32_e32 v84, vcc, s0, v72
	v_add_f32_e32 v83, v83, v87
	s_nop 0
	v_addc_co_u32_e32 v85, vcc, 0, v73, vcc
	global_store_short v[84:85], v86, off offset:2048
	v_fma_f32 v84, v83, v141, -v125
	v_cvt_pk_bf16_f32 v86, v84, s0
	s_mov_b32 s0, 0x1ec16000
	v_add_co_u32_e32 v84, vcc, s0, v72
	s_nop 1
	v_addc_co_u32_e32 v85, vcc, 0, v73, vcc
	global_store_short v[84:85], v86, off offset:2048
	v_add_f32_e32 v84, v83, v142
	v_fma_f32 v82, v84, v143, -v82
	v_cvt_pk_bf16_f32 v85, v82, s0
	s_mov_b32 s0, 0x1ec17000
	v_add_f32_e32 v84, v84, v144
	v_add_co_u32_e32 v82, vcc, s0, v72
	v_fma_f32 v81, v84, v145, -v81
	s_nop 0
	v_addc_co_u32_e32 v83, vcc, 0, v73, vcc
	v_cvt_pk_bf16_f32 v81, v81, s0
	s_mov_b32 s0, 0x1ec18000
	global_store_short v[82:83], v85, off offset:2048
	v_add_co_u32_e32 v82, vcc, s0, v72
	s_nop 1
	v_addc_co_u32_e32 v83, vcc, 0, v73, vcc
	global_store_short v[82:83], v81, off offset:2048
	v_add_f32_e32 v82, v84, v131
	v_fma_f32 v80, v82, v146, -v80
	v_cvt_pk_bf16_f32 v83, v80, s0
	s_mov_b32 s0, 0x1ec19000
	v_add_f32_e32 v82, v82, v130
	v_add_co_u32_e32 v80, vcc, s0, v72
	v_fma_f32 v79, v82, v147, -v79
	s_nop 0
	v_addc_co_u32_e32 v81, vcc, 0, v73, vcc
	v_cvt_pk_bf16_f32 v79, v79, s0
	s_mov_b32 s0, 0x1ec1a000
	global_store_short v[80:81], v83, off offset:2048
	v_add_co_u32_e32 v80, vcc, s0, v72
	s_nop 1
	v_addc_co_u32_e32 v81, vcc, 0, v73, vcc
	global_store_short v[80:81], v79, off offset:2048
	v_add_f32_e32 v80, v82, v128
	v_fma_f32 v78, v80, v148, -v78
	v_cvt_pk_bf16_f32 v81, v78, s0
	s_mov_b32 s0, 0x1ec1b000
	v_add_f32_e32 v80, v80, v129
	v_add_co_u32_e32 v78, vcc, s0, v72
	v_fma_f32 v77, v80, v149, -v77
	s_nop 0
	v_addc_co_u32_e32 v79, vcc, 0, v73, vcc
	v_cvt_pk_bf16_f32 v77, v77, s0
	s_mov_b32 s0, 0x1ec1c000
	global_store_short v[78:79], v81, off offset:2048
	v_add_co_u32_e32 v78, vcc, s0, v72
	s_nop 1
	v_addc_co_u32_e32 v79, vcc, 0, v73, vcc
	global_store_short v[78:79], v77, off offset:2048
	v_add_f32_e32 v78, v80, v126
	v_fma_f32 v76, v78, v150, -v76
	v_cvt_pk_bf16_f32 v79, v76, s0
	s_mov_b32 s0, 0x1ec1d000
	v_add_co_u32_e32 v76, vcc, s0, v72
	s_nop 1
	v_addc_co_u32_e32 v77, vcc, 0, v73, vcc
	global_store_short v[76:77], v79, off offset:2048
	v_add_f32_e32 v76, v78, v127
	v_fma_f32 v75, v76, v151, -v75
	v_add_co_u32_e32 v72, vcc, 0x1ec1e000, v72
	v_cvt_pk_bf16_f32 v75, v75, s0
	s_nop 0
	v_addc_co_u32_e32 v73, vcc, 0, v73, vcc
	global_store_short v[72:73], v75, off offset:2048
	v_sub_f32_e32 v72, v133, v125
	v_add_f32_e32 v72, v76, v72
	v_fma_f32 v69, v72, v152, -v69
.LBB0_402:
	s_or_b64 exec, exec, s[86:87]
	s_and_saveexec_b64 s[0:1], s[84:85]
	s_cbranch_execz .LBB0_404
	ds_read_u16 v134, v182 offset:7168
	ds_read_u16 v131, v182 offset:8192
	ds_read_u16 v130, v182 offset:9216
	ds_read_u16 v129, v182 offset:10240
	ds_read_u16 v128, v182 offset:11264
	ds_read_u16 v127, v182 offset:12288
	ds_read_u16 v126, v182 offset:13312
	ds_read_u16 v125, v182 offset:14336
	ds_read_u16 v124, v182 offset:15360
	ds_read_u16 v123, v182 offset:16384
	ds_read_u16 v122, v182 offset:17408
	ds_read_u16 v95, v182 offset:18432
	ds_read_u16 v94, v182 offset:19456
	ds_read_u16 v93, v182 offset:20480
	ds_read_u16 v92, v182 offset:21504
	ds_read_u16 v91, v182 offset:22528
	ds_read_u16 v90, v182 offset:23552
	ds_read_u16 v89, v182 offset:24576
	ds_read_u16 v88, v182 offset:25600
	ds_read_u16 v87, v182 offset:26624
	ds_read_u16 v86, v182 offset:27648
	ds_read_u16 v85, v182 offset:28672
	ds_read_u16 v83, v182 offset:30720
	ds_read_u16 v84, v182 offset:29696
	ds_read_u16 v82, v182 offset:31744
	ds_read_u16 v81, v182 offset:32768
	ds_read_u16 v78, v182 offset:34816
	ds_read_u16 v80, v182 offset:33792
	ds_read_u16 v77, v182 offset:36864
	ds_read_u16 v75, v182 offset:38912
	s_cmp_gt_i32 s62, 0
	s_cselect_b64 s[12:13], -1, 0
	s_add_i32 s63, s62, 32
	s_cmp_lt_i32 s62, s35
	s_waitcnt lgkmcnt(0)
	v_lshlrev_b32_e32 v134, 16, v134
	s_cselect_b64 s[16:17], -1, 0
	s_ashr_i32 s75, s74, 31
	s_and_b64 s[84:85], s[12:13], s[16:17]
	s_lshl_b64 s[12:13], s[74:75], 12
	s_waitcnt lgkmcnt(0)
	v_lshlrev_b32_e32 v131, 16, v131
	s_add_u32 s12, s94, s12
	s_addc_u32 s13, s95, s13
	v_lshl_add_u64 v[72:73], v[96:97], 1, s[12:13]
	s_mov_b64 s[12:13], 0x1ec00800
	s_waitcnt lgkmcnt(0)
	v_lshlrev_b32_e32 v130, 16, v130
	s_waitcnt lgkmcnt(0)
	v_lshlrev_b32_e32 v129, 16, v129
	s_waitcnt lgkmcnt(0)
	v_lshlrev_b32_e32 v128, 16, v128
	s_waitcnt lgkmcnt(0)
	v_lshlrev_b32_e32 v127, 16, v127
	s_waitcnt lgkmcnt(0)
	v_lshlrev_b32_e32 v126, 16, v126
	s_waitcnt lgkmcnt(0)
	v_lshlrev_b32_e32 v125, 16, v125
	s_waitcnt lgkmcnt(0)
	v_lshlrev_b32_e32 v124, 16, v124
	s_waitcnt lgkmcnt(0)
	v_lshlrev_b32_e32 v123, 16, v123
	s_waitcnt lgkmcnt(0)
	v_lshlrev_b32_e32 v122, 16, v122
	s_waitcnt lgkmcnt(0)
	v_lshlrev_b32_e32 v95, 16, v95
	s_waitcnt lgkmcnt(0)
	v_lshlrev_b32_e32 v94, 16, v94
	s_waitcnt lgkmcnt(0)
	v_lshlrev_b32_e32 v93, 16, v93
	s_waitcnt lgkmcnt(0)
	v_lshlrev_b32_e32 v92, 16, v92
	s_waitcnt lgkmcnt(0)
	v_lshlrev_b32_e32 v91, 16, v91
	s_waitcnt lgkmcnt(0)
	v_lshlrev_b32_e32 v90, 16, v90
	s_waitcnt lgkmcnt(0)
	v_lshlrev_b32_e32 v89, 16, v89
	s_waitcnt lgkmcnt(0)
	v_lshlrev_b32_e32 v88, 16, v88
	s_waitcnt lgkmcnt(0)
	v_lshlrev_b32_e32 v87, 16, v87
	s_waitcnt lgkmcnt(0)
	v_lshlrev_b32_e32 v86, 16, v86
	s_waitcnt lgkmcnt(0)
	v_lshlrev_b32_e32 v85, 16, v85
	s_waitcnt lgkmcnt(0)
	v_lshlrev_b32_e32 v83, 16, v83
	s_waitcnt lgkmcnt(0)
	v_lshlrev_b32_e32 v84, 16, v84
	s_waitcnt lgkmcnt(0)
	v_lshlrev_b32_e32 v82, 16, v82
	s_waitcnt lgkmcnt(0)
	v_lshlrev_b32_e32 v81, 16, v81
	s_waitcnt lgkmcnt(0)
	v_lshlrev_b32_e32 v78, 16, v78
	ds_read_u16 v69, v182 offset:35840
	s_waitcnt lgkmcnt(0)
	v_lshlrev_b32_e32 v80, 16, v80
	s_waitcnt lgkmcnt(0)
	v_lshlrev_b32_e32 v69, 16, v69
	s_waitcnt lgkmcnt(0)
	v_lshlrev_b32_e32 v77, 16, v77
	v_add_f32_e32 v70, 0, v134
	s_waitcnt lgkmcnt(0)
	v_lshlrev_b32_e32 v75, 16, v75
	v_add_f32_e32 v135, v70, v131
	v_lshl_add_u64 v[70:71], v[72:73], 0, s[12:13]
	s_or_b32 s13, s62, 1
	s_max_i32 s12, s62, 1
	s_min_i32 s13, s13, s35
	s_sub_i32 s12, s13, s12
	s_add_i32 s12, s12, 1
	v_cvt_f32_i32_e32 v76, s12
	s_mov_b32 s12, 0x1ec00000
	v_add_co_u32_e32 v132, vcc, s12, v72
	v_rcp_iflag_f32_e32 v76, v76
	s_or_b32 s13, s62, 2
	v_addc_co_u32_e32 v133, vcc, 0, v73, vcc
	v_cndmask_b32_e64 v76, v76, 0.5, s[84:85]
	v_fma_f32 v76, v135, v76, -v131
	v_cvt_pk_bf16_f32 v136, v76, s0
	s_max_i32 s12, s62, 0
	s_min_i32 s13, s13, s35
	ds_read_u16 v76, v182 offset:37888
	ds_read_u16 v79, v182 offset:39936
	global_store_short v[132:133], v136, off offset:2048
	v_sub_f32_e32 v132, v130, v134
	s_sub_i32 s12, s13, s12
	v_add_f32_e32 v134, v135, v132
	v_cvt_f32_i32_e32 v132, s12
	s_mov_b32 s12, 0x1ec01000
	s_not_b32 s13, s62
	v_sub_f32_e32 v131, v129, v131
	v_rcp_iflag_f32_e32 v132, v132
	v_add_f32_e32 v131, v134, v131
	s_waitcnt lgkmcnt(0)
	v_lshlrev_b32_e32 v79, 16, v79
	v_cndmask_b32_e64 v132, v132, 0.5, s[84:85]
	v_fma_f32 v132, v134, v132, -v130
	v_cvt_pk_bf16_f32 v135, v132, s0
	v_add_co_u32_e32 v132, vcc, s12, v72
	s_or_b32 s12, s62, 3
	s_min_i32 s12, s12, s35
	s_cmp_gt_i32 s62, -1
	s_cselect_b32 s13, s13, 0
	v_addc_co_u32_e32 v133, vcc, 0, v73, vcc
	s_add_i32 s12, s12, s13
	global_store_short v[132:133], v135, off offset:2048
	v_cvt_f32_i32_e32 v132, s12
	s_mov_b32 s12, 0x1ec02000
	s_or_b32 s13, s62, 4
	s_min_i32 s13, s13, s35
	v_rcp_iflag_f32_e32 v132, v132
	v_sub_f32_e32 v130, v128, v130
	v_cndmask_b32_e64 v132, v132, 0.5, s[84:85]
	v_fma_f32 v132, v131, v132, -v129
	v_cvt_pk_bf16_f32 v134, v132, s0
	v_add_co_u32_e32 v132, vcc, s12, v72
	s_max_i32 s12, s62, -2
	s_sub_i32 s12, s13, s12
	v_addc_co_u32_e32 v133, vcc, 0, v73, vcc
	s_add_i32 s12, s12, -2
	global_store_short v[132:133], v134, off offset:2048
	v_add_f32_e32 v132, v131, v130
	v_cvt_f32_i32_e32 v130, s12
	s_mov_b32 s12, 0x1ec03000
	s_or_b32 s13, s62, 5
	s_min_i32 s13, s13, s35
	v_rcp_iflag_f32_e32 v130, v130
	v_sub_f32_e32 v129, v127, v129
	v_add_f32_e32 v129, v132, v129
	v_cndmask_b32_e64 v130, v130, 0.5, s[84:85]
	v_fma_f32 v130, v132, v130, -v128
	v_cvt_pk_bf16_f32 v133, v130, s0
	v_add_co_u32_e32 v130, vcc, s12, v72
	s_max_i32 s12, s62, -3
	s_sub_i32 s12, s13, s12
	v_addc_co_u32_e32 v131, vcc, 0, v73, vcc
	s_add_i32 s12, s12, -3
	global_store_short v[130:131], v133, off offset:2048
	v_cvt_f32_i32_e32 v130, s12
	s_mov_b32 s12, 0x1ec04000
	s_or_b32 s13, s62, 6
	s_min_i32 s13, s13, s35
	v_rcp_iflag_f32_e32 v130, v130
	v_sub_f32_e32 v128, v126, v128
	v_cndmask_b32_e64 v130, v130, 0.5, s[84:85]
	v_fma_f32 v130, v129, v130, -v127
	v_cvt_pk_bf16_f32 v132, v130, s0
	v_add_co_u32_e32 v130, vcc, s12, v72
	s_max_i32 s12, s62, -4
	s_sub_i32 s12, s13, s12
	v_addc_co_u32_e32 v131, vcc, 0, v73, vcc
	s_add_i32 s12, s12, -4
	global_store_short v[130:131], v132, off offset:2048
	v_add_f32_e32 v130, v129, v128
	v_cvt_f32_i32_e32 v128, s12
	s_mov_b32 s12, 0x1ec05000
	s_or_b32 s13, s62, 7
	s_min_i32 s13, s13, s35
	v_rcp_iflag_f32_e32 v128, v128
	v_sub_f32_e32 v127, v125, v127
	v_add_f32_e32 v127, v130, v127
	v_cndmask_b32_e64 v128, v128, 0.5, s[84:85]
	v_fma_f32 v128, v130, v128, -v126
	v_cvt_pk_bf16_f32 v131, v128, s0
	v_add_co_u32_e32 v128, vcc, s12, v72
	s_max_i32 s12, s62, -5
	s_sub_i32 s12, s13, s12
	v_addc_co_u32_e32 v129, vcc, 0, v73, vcc
	s_add_i32 s12, s12, -5
	global_store_short v[128:129], v131, off offset:2048
	v_cvt_f32_i32_e32 v128, s12
	s_mov_b32 s12, 0x1ec06000
	s_or_b32 s13, s62, 8
	s_min_i32 s13, s13, s35
	v_rcp_iflag_f32_e32 v128, v128
	v_sub_f32_e32 v126, v124, v126
	v_cndmask_b32_e64 v128, v128, 0.5, s[84:85]
	v_fma_f32 v128, v127, v128, -v125
	v_cvt_pk_bf16_f32 v130, v128, s0
	v_add_co_u32_e32 v128, vcc, s12, v72
	s_max_i32 s12, s62, -6
	s_sub_i32 s12, s13, s12
	v_addc_co_u32_e32 v129, vcc, 0, v73, vcc
	s_add_i32 s12, s12, -6
	global_store_short v[128:129], v130, off offset:2048
	v_add_f32_e32 v128, v127, v126
	v_cvt_f32_i32_e32 v126, s12
	s_mov_b32 s12, 0x1ec07000
	s_or_b32 s13, s62, 9
	s_min_i32 s13, s13, s35
	v_rcp_iflag_f32_e32 v126, v126
	v_sub_f32_e32 v125, v123, v125
	v_add_f32_e32 v125, v128, v125
	v_cndmask_b32_e64 v126, v126, 0.5, s[84:85]
	v_fma_f32 v126, v128, v126, -v124
	v_cvt_pk_bf16_f32 v129, v126, s0
	v_add_co_u32_e32 v126, vcc, s12, v72
	s_max_i32 s12, s62, -7
	s_sub_i32 s12, s13, s12
	v_addc_co_u32_e32 v127, vcc, 0, v73, vcc
	s_add_i32 s12, s12, -7
	global_store_short v[126:127], v129, off offset:2048
	v_cvt_f32_i32_e32 v126, s12
	s_mov_b32 s12, 0x1ec08000
	s_or_b32 s13, s62, 10
	s_min_i32 s13, s13, s35
	v_rcp_iflag_f32_e32 v126, v126
	v_sub_f32_e32 v124, v122, v124
	v_cndmask_b32_e64 v126, v126, 0.5, s[84:85]
	v_fma_f32 v126, v125, v126, -v123
	v_cvt_pk_bf16_f32 v128, v126, s0
	v_add_co_u32_e32 v126, vcc, s12, v72
	s_max_i32 s12, s62, -8
	s_sub_i32 s12, s13, s12
	v_addc_co_u32_e32 v127, vcc, 0, v73, vcc
	s_add_i32 s12, s12, -8
	global_store_short v[126:127], v128, off offset:2048
	v_add_f32_e32 v126, v125, v124
	v_cvt_f32_i32_e32 v124, s12
	s_mov_b32 s12, 0x1ec09000
	s_or_b32 s13, s62, 11
	s_min_i32 s13, s13, s35
	v_rcp_iflag_f32_e32 v124, v124
	v_sub_f32_e32 v123, v95, v123
	v_add_f32_e32 v123, v126, v123
	v_cndmask_b32_e64 v124, v124, 0.5, s[84:85]
	v_fma_f32 v124, v126, v124, -v122
	v_cvt_pk_bf16_f32 v127, v124, s0
	v_add_co_u32_e32 v124, vcc, s12, v72
	s_max_i32 s12, s62, -9
	s_sub_i32 s12, s13, s12
	v_addc_co_u32_e32 v125, vcc, 0, v73, vcc
	s_add_i32 s12, s12, -9
	global_store_short v[124:125], v127, off offset:2048
	v_cvt_f32_i32_e32 v124, s12
	s_mov_b32 s12, 0x1ec0a000
	s_or_b32 s13, s62, 12
	s_min_i32 s13, s13, s35
	v_rcp_iflag_f32_e32 v124, v124
	v_sub_f32_e32 v122, v94, v122
	v_cndmask_b32_e64 v124, v124, 0.5, s[84:85]
	v_fma_f32 v124, v123, v124, -v95
	v_cvt_pk_bf16_f32 v126, v124, s0
	v_add_co_u32_e32 v124, vcc, s12, v72
	s_max_i32 s12, s62, -10
	s_sub_i32 s12, s13, s12
	v_addc_co_u32_e32 v125, vcc, 0, v73, vcc
	s_add_i32 s12, s12, -10
	global_store_short v[124:125], v126, off offset:2048
	v_add_f32_e32 v124, v123, v122
	v_cvt_f32_i32_e32 v122, s12
	s_mov_b32 s12, 0x1ec0b000
	s_or_b32 s13, s62, 13
	s_min_i32 s13, s13, s35
	v_rcp_iflag_f32_e32 v122, v122
	v_sub_f32_e32 v95, v93, v95
	v_add_f32_e32 v95, v124, v95
	v_cndmask_b32_e64 v122, v122, 0.5, s[84:85]
	v_fma_f32 v122, v124, v122, -v94
	v_cvt_pk_bf16_f32 v125, v122, s0
	v_add_co_u32_e32 v122, vcc, s12, v72
	s_max_i32 s12, s62, -11
	s_sub_i32 s12, s13, s12
	v_addc_co_u32_e32 v123, vcc, 0, v73, vcc
	s_add_i32 s12, s12, -11
	global_store_short v[122:123], v125, off offset:2048
	v_cvt_f32_i32_e32 v122, s12
	s_mov_b32 s12, 0x1ec0c000
	s_or_b32 s13, s62, 14
	s_min_i32 s13, s13, s35
	v_rcp_iflag_f32_e32 v122, v122
	v_sub_f32_e32 v94, v92, v94
	v_cndmask_b32_e64 v122, v122, 0.5, s[84:85]
	v_fma_f32 v122, v95, v122, -v93
	v_cvt_pk_bf16_f32 v124, v122, s0
	v_add_co_u32_e32 v122, vcc, s12, v72
	s_max_i32 s12, s62, -12
	s_sub_i32 s12, s13, s12
	v_addc_co_u32_e32 v123, vcc, 0, v73, vcc
	s_add_i32 s12, s12, -12
	global_store_short v[122:123], v124, off offset:2048
	v_add_f32_e32 v122, v95, v94
	v_cvt_f32_i32_e32 v94, s12
	s_mov_b32 s12, 0x1ec0d000
	s_or_b32 s13, s62, 15
	s_min_i32 s13, s13, s35
	v_rcp_iflag_f32_e32 v94, v94
	v_sub_f32_e32 v93, v91, v93
	v_add_f32_e32 v93, v122, v93
	v_cndmask_b32_e64 v94, v94, 0.5, s[84:85]
	v_fma_f32 v94, v122, v94, -v92
	v_cvt_pk_bf16_f32 v123, v94, s0
	v_add_co_u32_e32 v94, vcc, s12, v72
	s_max_i32 s12, s62, -13
	s_sub_i32 s12, s13, s12
	v_addc_co_u32_e32 v95, vcc, 0, v73, vcc
	s_add_i32 s12, s12, -13
	global_store_short v[94:95], v123, off offset:2048
	v_cvt_f32_i32_e32 v94, s12
	s_mov_b32 s12, 0x1ec0e000
	s_or_b32 s13, s62, 16
	s_min_i32 s13, s13, s35
	v_rcp_iflag_f32_e32 v94, v94
	v_sub_f32_e32 v92, v90, v92
	v_cndmask_b32_e64 v94, v94, 0.5, s[84:85]
	v_fma_f32 v94, v93, v94, -v91
	v_cvt_pk_bf16_f32 v122, v94, s0
	v_add_co_u32_e32 v94, vcc, s12, v72
	s_max_i32 s12, s62, -14
	s_sub_i32 s12, s13, s12
	v_addc_co_u32_e32 v95, vcc, 0, v73, vcc
	s_add_i32 s12, s12, -14
	global_store_short v[94:95], v122, off offset:2048
	v_add_f32_e32 v94, v93, v92
	v_cvt_f32_i32_e32 v92, s12
	s_mov_b32 s12, 0x1ec0f000
	s_or_b32 s13, s62, 17
	s_min_i32 s13, s13, s35
	v_rcp_iflag_f32_e32 v92, v92
	v_sub_f32_e32 v91, v89, v91
	v_add_f32_e32 v91, v94, v91
	v_cndmask_b32_e64 v92, v92, 0.5, s[84:85]
	v_fma_f32 v92, v94, v92, -v90
	v_cvt_pk_bf16_f32 v95, v92, s0
	v_add_co_u32_e32 v92, vcc, s12, v72
	s_max_i32 s12, s62, -15
	s_sub_i32 s12, s13, s12
	v_addc_co_u32_e32 v93, vcc, 0, v73, vcc
	s_add_i32 s12, s12, -15
	global_store_short v[92:93], v95, off offset:2048
	v_cvt_f32_i32_e32 v92, s12
	s_mov_b32 s12, 0x1ec10000
	s_or_b32 s13, s62, 18
	s_min_i32 s13, s13, s35
	v_rcp_iflag_f32_e32 v92, v92
	v_sub_f32_e32 v90, v88, v90
	v_cndmask_b32_e64 v92, v92, 0.5, s[84:85]
	v_fma_f32 v92, v91, v92, -v89
	v_cvt_pk_bf16_f32 v94, v92, s0
	v_add_co_u32_e32 v92, vcc, s12, v72
	s_max_i32 s12, s62, -16
	s_sub_i32 s12, s13, s12
	v_addc_co_u32_e32 v93, vcc, 0, v73, vcc
	s_add_i32 s12, s12, -16
	global_store_short v[92:93], v94, off offset:2048
	v_add_f32_e32 v92, v91, v90
	v_cvt_f32_i32_e32 v90, s12
	s_mov_b32 s12, 0x1ec11000
	s_or_b32 s13, s62, 19
	s_min_i32 s13, s13, s35
	v_rcp_iflag_f32_e32 v90, v90
	v_sub_f32_e32 v89, v87, v89
	v_add_f32_e32 v89, v92, v89
	v_cndmask_b32_e64 v90, v90, 0.5, s[84:85]
	v_fma_f32 v90, v92, v90, -v88
	v_cvt_pk_bf16_f32 v93, v90, s0
	v_add_co_u32_e32 v90, vcc, s12, v72
	s_max_i32 s12, s62, 0xffffffef
	s_sub_i32 s12, s13, s12
	v_addc_co_u32_e32 v91, vcc, 0, v73, vcc
	s_sub_i32 s12, s12, 17
	global_store_short v[90:91], v93, off offset:2048
	v_cvt_f32_i32_e32 v90, s12
	s_mov_b32 s12, 0x1ec12000
	s_or_b32 s13, s62, 20
	s_min_i32 s13, s13, s35
	v_rcp_iflag_f32_e32 v90, v90
	v_sub_f32_e32 v88, v86, v88
	v_cndmask_b32_e64 v90, v90, 0.5, s[84:85]
	v_fma_f32 v90, v89, v90, -v87
	v_cvt_pk_bf16_f32 v92, v90, s0
	v_add_co_u32_e32 v90, vcc, s12, v72
	s_max_i32 s12, s62, 0xffffffee
	s_sub_i32 s12, s13, s12
	v_addc_co_u32_e32 v91, vcc, 0, v73, vcc
	s_sub_i32 s12, s12, 18
	global_store_short v[90:91], v92, off offset:2048
	v_add_f32_e32 v90, v89, v88
	v_cvt_f32_i32_e32 v88, s12
	s_mov_b32 s12, 0x1ec13000
	s_or_b32 s13, s62, 21
	s_min_i32 s13, s13, s35
	v_rcp_iflag_f32_e32 v88, v88
	v_sub_f32_e32 v87, v85, v87
	v_add_f32_e32 v87, v90, v87
	v_cndmask_b32_e64 v88, v88, 0.5, s[84:85]
	v_fma_f32 v88, v90, v88, -v86
	v_cvt_pk_bf16_f32 v91, v88, s0
	v_add_co_u32_e32 v88, vcc, s12, v72
	s_max_i32 s12, s62, 0xffffffed
	s_sub_i32 s12, s13, s12
	v_addc_co_u32_e32 v89, vcc, 0, v73, vcc
	s_sub_i32 s12, s12, 19
	global_store_short v[88:89], v91, off offset:2048
	v_cvt_f32_i32_e32 v88, s12
	s_mov_b32 s12, 0x1ec14000
	s_or_b32 s13, s62, 22
	s_min_i32 s13, s13, s35
	v_rcp_iflag_f32_e32 v88, v88
	v_sub_f32_e32 v86, v84, v86
	v_cndmask_b32_e64 v88, v88, 0.5, s[84:85]
	v_fma_f32 v88, v87, v88, -v85
	v_cvt_pk_bf16_f32 v90, v88, s0
	v_add_co_u32_e32 v88, vcc, s12, v72
	s_max_i32 s12, s62, 0xffffffec
	s_sub_i32 s12, s13, s12
	v_addc_co_u32_e32 v89, vcc, 0, v73, vcc
	s_sub_i32 s12, s12, 20
	global_store_short v[88:89], v90, off offset:2048
	v_add_f32_e32 v88, v87, v86
	v_cvt_f32_i32_e32 v86, s12
	s_mov_b32 s12, 0x1ec15000
	s_or_b32 s13, s62, 23
	s_min_i32 s13, s13, s35
	v_rcp_iflag_f32_e32 v86, v86
	v_sub_f32_e32 v85, v83, v85
	v_add_f32_e32 v85, v88, v85
	v_cndmask_b32_e64 v86, v86, 0.5, s[84:85]
	v_fma_f32 v86, v88, v86, -v84
	v_cvt_pk_bf16_f32 v89, v86, s0
	v_add_co_u32_e32 v86, vcc, s12, v72
	s_max_i32 s12, s62, 0xffffffeb
	s_sub_i32 s12, s13, s12
	v_addc_co_u32_e32 v87, vcc, 0, v73, vcc
	s_sub_i32 s12, s12, 21
	global_store_short v[86:87], v89, off offset:2048
	v_cvt_f32_i32_e32 v86, s12
	s_mov_b32 s12, 0x1ec16000
	s_or_b32 s13, s62, 24
	s_min_i32 s13, s13, s35
	v_rcp_iflag_f32_e32 v86, v86
	v_sub_f32_e32 v84, v82, v84
	v_cndmask_b32_e64 v86, v86, 0.5, s[84:85]
	v_fma_f32 v86, v85, v86, -v83
	v_cvt_pk_bf16_f32 v88, v86, s0
	v_add_co_u32_e32 v86, vcc, s12, v72
	s_max_i32 s12, s62, 0xffffffea
	s_sub_i32 s12, s13, s12
	v_addc_co_u32_e32 v87, vcc, 0, v73, vcc
	s_sub_i32 s12, s12, 22
	global_store_short v[86:87], v88, off offset:2048
	v_add_f32_e32 v86, v85, v84
	v_cvt_f32_i32_e32 v84, s12
	s_mov_b32 s12, 0x1ec17000
	s_or_b32 s13, s62, 25
	s_min_i32 s13, s13, s35
	v_rcp_iflag_f32_e32 v84, v84
	v_sub_f32_e32 v83, v81, v83
	v_add_f32_e32 v83, v86, v83
	v_cndmask_b32_e64 v84, v84, 0.5, s[84:85]
	v_fma_f32 v84, v86, v84, -v82
	v_cvt_pk_bf16_f32 v87, v84, s0
	v_add_co_u32_e32 v84, vcc, s12, v72
	s_max_i32 s12, s62, 0xffffffe9
	s_sub_i32 s12, s13, s12
	v_addc_co_u32_e32 v85, vcc, 0, v73, vcc
	s_sub_i32 s12, s12, 23
	global_store_short v[84:85], v87, off offset:2048
	v_cvt_f32_i32_e32 v84, s12
	s_mov_b32 s12, 0x1ec18000
	s_or_b32 s13, s62, 26
	s_min_i32 s13, s13, s35
	v_rcp_iflag_f32_e32 v84, v84
	v_sub_f32_e32 v82, v80, v82
	v_cndmask_b32_e64 v84, v84, 0.5, s[84:85]
	v_fma_f32 v84, v83, v84, -v81
	v_cvt_pk_bf16_f32 v86, v84, s0
	v_add_co_u32_e32 v84, vcc, s12, v72
	s_max_i32 s12, s62, 0xffffffe8
	s_sub_i32 s12, s13, s12
	v_addc_co_u32_e32 v85, vcc, 0, v73, vcc
	s_sub_i32 s12, s12, 24
	global_store_short v[84:85], v86, off offset:2048
	v_add_f32_e32 v84, v83, v82
	v_cvt_f32_i32_e32 v82, s12
	s_mov_b32 s12, 0x1ec19000
	s_or_b32 s13, s62, 27
	s_min_i32 s13, s13, s35
	v_rcp_iflag_f32_e32 v82, v82
	v_sub_f32_e32 v81, v78, v81
	v_add_f32_e32 v81, v84, v81
	v_cndmask_b32_e64 v82, v82, 0.5, s[84:85]
	v_fma_f32 v82, v84, v82, -v80
	v_cvt_pk_bf16_f32 v85, v82, s0
	v_add_co_u32_e32 v82, vcc, s12, v72
	s_max_i32 s12, s62, 0xffffffe7
	s_sub_i32 s12, s13, s12
	v_addc_co_u32_e32 v83, vcc, 0, v73, vcc
	s_sub_i32 s12, s12, 25
	global_store_short v[82:83], v85, off offset:2048
	v_cvt_f32_i32_e32 v82, s12
	s_mov_b32 s12, 0x1ec1a000
	s_or_b32 s13, s62, 28
	s_min_i32 s13, s13, s35
	v_rcp_iflag_f32_e32 v82, v82
	v_sub_f32_e32 v80, v69, v80
	v_cndmask_b32_e64 v82, v82, 0.5, s[84:85]
	v_fma_f32 v82, v81, v82, -v78
	v_cvt_pk_bf16_f32 v84, v82, s0
	v_add_co_u32_e32 v82, vcc, s12, v72
	s_max_i32 s12, s62, 0xffffffe6
	s_sub_i32 s12, s13, s12
	v_addc_co_u32_e32 v83, vcc, 0, v73, vcc
	s_sub_i32 s12, s12, 26
	global_store_short v[82:83], v84, off offset:2048
	v_add_f32_e32 v82, v81, v80
	v_cvt_f32_i32_e32 v80, s12
	s_mov_b32 s12, 0x1ec1b000
	s_or_b32 s13, s62, 29
	s_min_i32 s13, s13, s35
	v_rcp_iflag_f32_e32 v80, v80
	v_sub_f32_e32 v78, v77, v78
	v_add_f32_e32 v78, v82, v78
	v_lshlrev_b32_e32 v84, 16, v76
	v_cndmask_b32_e64 v80, v80, 0.5, s[84:85]
	v_fma_f32 v80, v82, v80, -v69
	v_cvt_pk_bf16_f32 v83, v80, s0
	v_add_co_u32_e32 v80, vcc, s12, v72
	s_max_i32 s12, s62, 0xffffffe5
	s_sub_i32 s12, s13, s12
	v_addc_co_u32_e32 v81, vcc, 0, v73, vcc
	s_sub_i32 s12, s12, 27
	global_store_short v[80:81], v83, off offset:2048
	v_cvt_f32_i32_e32 v80, s12
	s_mov_b32 s12, 0x1ec1c000
	s_or_b32 s13, s62, 30
	s_min_i32 s13, s13, s35
	v_rcp_iflag_f32_e32 v80, v80
	v_sub_f32_e32 v69, v84, v69
	v_add_f32_e32 v69, v78, v69
	v_cndmask_b32_e64 v80, v80, 0.5, s[84:85]
	v_fma_f32 v80, v78, v80, -v77
	v_cvt_pk_bf16_f32 v82, v80, s0
	v_add_co_u32_e32 v80, vcc, s12, v72
	s_max_i32 s12, s62, 0xffffffe4
	s_sub_i32 s12, s13, s12
	v_addc_co_u32_e32 v81, vcc, 0, v73, vcc
	s_sub_i32 s12, s12, 28
	s_or_b32 s13, s62, 31
	global_store_short v[80:81], v82, off offset:2048
	v_cvt_f32_i32_e32 v80, s12
	s_max_i32 s12, s62, 0xffffffe3
	s_min_i32 s13, s13, s35
	s_sub_i32 s12, s13, s12
	s_sub_i32 s12, s12, 29
	v_sub_f32_e32 v81, v75, v77
	v_cvt_f32_i32_e32 v77, s12
	s_max_i32 s12, s62, 0xffffffe2
	s_min_i32 s13, s63, s35
	s_sub_i32 s12, s13, s12
	v_rcp_iflag_f32_e32 v77, v77
	s_sub_i32 s12, s12, 30
	v_rcp_iflag_f32_e32 v80, v80
	v_cndmask_b32_e64 v82, v77, 0.5, s[84:85]
	v_cvt_f32_i32_e32 v77, s12
	v_cndmask_b32_e64 v80, v80, 0.5, s[84:85]
	v_fma_f32 v76, v69, v80, -v84
	v_cvt_pk_bf16_f32 v78, v76, s0
	v_rcp_iflag_f32_e32 v77, v77
	v_add_co_u32_e32 v76, vcc, 0x1ec1d000, v72
	v_add_f32_e32 v69, v69, v81
	v_cndmask_b32_e64 v83, v77, 0.5, s[84:85]
	v_addc_co_u32_e32 v77, vcc, 0, v73, vcc
	v_fma_f32 v75, v69, v82, -v75
	v_add_co_u32_e32 v72, vcc, 0x1ec1e000, v72
	v_cvt_pk_bf16_f32 v75, v75, s0
	s_nop 0
	v_addc_co_u32_e32 v73, vcc, 0, v73, vcc
	global_store_short v[72:73], v75, off offset:2048
	v_sub_f32_e32 v72, v79, v84
	v_add_f32_e32 v69, v69, v72
	v_fma_f32 v69, v69, v83, -v79
	global_store_short v[76:77], v78, off offset:2048

.LBB0_513:
	v_readlane_b32 s74, v252, 10
	s_add_u32 s0, s84, 0x80080
	v_mov_b32_e32 v133, v3
	v_readlane_b32 s75, v252, 11
	s_addc_u32 s1, s85, 0
	s_add_i32 m0, s17, 0x18000
	v_lshl_add_u64 v[6:7], v[6:7], 0, s[66:67]
	v_lshl_add_u64 v[16:17], s[74:75], 0, v[132:133]
	v_mov_b32_e32 v135, v3
	s_waitcnt vmcnt(2)
	s_barrier
	global_load_lds_dwordx4 v[6:7], off
	v_lshl_add_u64 v[4:5], v[4:5], 0, s[66:67]
	s_add_i32 m0, s17, 0x1a000
	s_add_i32 s62, s17, 0x8000
	v_lshl_add_u64 v[18:19], s[74:75], 0, v[134:135]
	global_load_lds_dwordx4 v[4:5], off
	v_lshl_add_u64 v[4:5], v[16:17], 0, s[66:67]
	s_mov_b32 m0, s62
	s_add_i32 s63, s17, 0xa000
	global_load_lds_dwordx4 v[4:5], off
	v_lshl_add_u64 v[4:5], v[18:19], 0, s[66:67]
	s_mov_b32 m0, s63
	v_lshrrev_b32_e32 v20, 1, v14
	global_load_lds_dwordx4 v[4:5], off
	s_add_i32 m0, s17, 0x1c000
	v_lshl_add_u64 v[4:5], s[0:1], 0, v[2:3]
	global_load_lds_dwordx4 v[4:5], off
	v_lshl_add_u64 v[4:5], s[0:1], 0, v[136:137]
	s_add_i32 m0, s17, 0x1e000
	v_and_b32_e32 v20, 24, v20
	global_load_lds_dwordx4 v[4:5], off
	v_lshlrev_b32_e32 v4, 15, v8
	v_and_b32_e32 v4, 0xffff0000, v4
	v_lshl_add_u32 v4, v9, 12, v4
	v_and_b32_e32 v5, 1, v8
	v_lshl_or_b32 v4, v5, 6, v4
	s_lshl_b32 s23, s23, 5
	v_lshl_add_u32 v138, v10, 1, v4
	v_lshlrev_b32_e32 v4, 15, v11
	v_and_b32_e32 v15, 15, v14
	v_lshlrev_b32_e32 v21, 1, v20
	v_lshlrev_b32_e32 v14, 2, v14
	s_and_b32 s23, s23, 0x60
	v_and_b32_e32 v4, 0xffff0000, v4
	v_bfe_u32 v1, v0, 2, 4
	v_lshl_or_b32 v1, s35, 6, v1
	v_bfe_u32 v231, v0, 2, 4
	v_and_b32_e32 v230, 3, v0
	v_lshl_or_b32 v231, v230, 4, v231
	v_lshlrev_b32_e32 v231, 2, v231
	v_lshl_or_b32 v15, v15, 6, v21
	v_and_b32_e32 v14, 32, v14
	s_lshl_b32 s35, s35, 13
	s_lshl_b32 s50, s23, 7
	s_waitcnt vmcnt(6)
	v_lshl_add_u32 v4, v12, 12, v4
	v_and_b32_e32 v5, 1, v11
	v_bitop3_b32 v142, v15, s50, v14 bitop3:0xde
	v_bitop3_b32 v14, v15, s35, v14 bitop3:0xde
	s_cmpk_lt_u32 s9, 0x100
	v_lshl_or_b32 v4, v5, 6, v4
	v_readlane_b32 s0, v252, 17
	s_mov_b32 s64, 32
	s_cselect_b64 s[58:59], -1, 0
	v_and_b32_e32 v143, 3, v0
	v_lshl_or_b32 v143, v143, 3, s23
	v_mov_b32_e32 v139, v3
	v_lshl_add_u32 v140, v13, 1, v4
	v_mov_b32_e32 v141, v3
	s_mov_b64 s[86:87], -1
	s_mov_b32 s50, 0
	v_add_u32_e32 v144, 0, v14
	s_mov_b32 s51, s0
	s_barrier
	v_readlane_b32 s1, v252, 18
	s_branch .LBB0_516

.LBB0_524:
	s_lshl_b32 s9, s51, 8
	s_add_i32 s23, s9, 0xffffe000
	s_cmp_eq_u32 s50, 0
	s_cselect_b32 s9, s9, s23
	s_mov_b32 s23, 0x21c00000
	s_cselect_b32 s23, s23, 0x33c00000
	s_add_u32 s50, s94, s23
	v_lshl_or_b32 v146, s22, 8, v143
	v_add_u32_e32 v148, s9, v1
	s_addc_u32 s51, s95, 0
	v_ashrrev_i32_e32 v147, 31, v146
	v_ashrrev_i32_e32 v149, 31, v148
	v_lshl_add_u64 v[146:147], v[146:147], 1, s[50:51]
	v_lshlrev_b64 v[150:151], 12, v[148:149]
	v_lshl_add_u64 v[150:151], v[146:147], 0, v[150:151]
	s_mov_b32 s9, 0x80000
	s_mov_b64 s[50:51], 0x80000
	v_cvt_pk_bf16_f32 v64, v64, v65
	v_cvt_pk_bf16_f32 v65, v66, v67
	v_cvt_pk_bf16_f32 v66, v60, v61
	v_add_co_u32_e32 v60, vcc, s9, v150
	v_cvt_pk_bf16_f32 v72, v72, v73
	v_cvt_pk_bf16_f32 v73, v74, v75
	v_cvt_pk_bf16_f32 v74, v68, v69
	v_lshl_add_u64 v[68:69], v[150:151], 0, s[50:51]
	v_addc_co_u32_e32 v61, vcc, 0, v151, vcc
	v_cvt_pk_bf16_f32 v48, v48, v49
	v_cvt_pk_bf16_f32 v49, v50, v51
	v_cvt_pk_bf16_f32 v50, v44, v45
	v_cvt_pk_bf16_f32 v51, v46, v47
	s_mov_b32 s9, 0x90000
	ds_bpermute_b32 v48, v231, v48
	ds_bpermute_b32 v49, v231, v49
	ds_bpermute_b32 v50, v231, v50
	ds_bpermute_b32 v51, v231, v51
	s_waitcnt lgkmcnt(0)
	global_store_dwordx4 v[68:69], v[48:51], off offset:256
	s_mov_b64 s[50:51], 0x90000
	v_cvt_pk_bf16_f32 v112, v112, v113
	v_add_co_u32_e32 v50, vcc, s9, v150
	v_cvt_pk_bf16_f32 v113, v114, v115
	v_cvt_pk_bf16_f32 v114, v108, v109
	v_or_b32_e32 v108, 16, v148
	v_lshl_add_u64 v[48:49], v[150:151], 0, s[50:51]
	v_addc_co_u32_e32 v51, vcc, 0, v151, vcc
	v_cvt_pk_bf16_f32 v32, v32, v33
	v_cvt_pk_bf16_f32 v33, v34, v35
	v_cvt_pk_bf16_f32 v34, v28, v29
	v_cvt_pk_bf16_f32 v35, v30, v31
	s_mov_b32 s9, 0xa0000
	v_ashrrev_i32_e32 v109, 31, v108
	v_cvt_pk_bf16_f32 v96, v96, v97
	v_cvt_pk_bf16_f32 v97, v98, v99
	v_cvt_pk_bf16_f32 v98, v92, v93
	v_or_b32_e32 v92, 32, v148
	ds_bpermute_b32 v32, v231, v32
	ds_bpermute_b32 v33, v231, v33
	ds_bpermute_b32 v34, v231, v34
	ds_bpermute_b32 v35, v231, v35
	s_waitcnt lgkmcnt(0)
	global_store_dwordx4 v[48:49], v[32:35], off offset:256
	s_mov_b64 s[50:51], 0xa0000
	v_cvt_pk_bf16_f32 v115, v110, v111
	v_add_co_u32_e32 v34, vcc, s9, v150
	v_lshlrev_b64 v[108:109], 12, v[108:109]
	v_ashrrev_i32_e32 v93, 31, v92
	v_cvt_pk_bf16_f32 v80, v80, v81
	v_cvt_pk_bf16_f32 v81, v82, v83
	v_cvt_pk_bf16_f32 v82, v76, v77
	v_or_b32_e32 v76, 48, v148
	v_lshl_add_u64 v[32:33], v[150:151], 0, s[50:51]
	v_addc_co_u32_e32 v35, vcc, 0, v151, vcc
	v_cvt_pk_bf16_f32 v16, v16, v17
	v_cvt_pk_bf16_f32 v17, v18, v19
	v_cvt_pk_bf16_f32 v18, v12, v13
	v_cvt_pk_bf16_f32 v19, v14, v15
	s_mov_b32 s9, 0xb0000
	ds_bpermute_b32 v112, v231, v112
	ds_bpermute_b32 v113, v231, v113
	ds_bpermute_b32 v114, v231, v114
	ds_bpermute_b32 v115, v231, v115
	s_waitcnt lgkmcnt(0)
	global_store_dwordx4 v[150:151], v[112:115], off offset:256
	v_cvt_pk_bf16_f32 v99, v94, v95
	v_lshlrev_b64 v[92:93], 12, v[92:93]
	v_lshl_add_u64 v[112:113], v[146:147], 0, v[108:109]
	v_ashrrev_i32_e32 v77, 31, v76
	ds_bpermute_b32 v16, v231, v16
	ds_bpermute_b32 v17, v231, v17
	ds_bpermute_b32 v18, v231, v18
	ds_bpermute_b32 v19, v231, v19
	s_waitcnt lgkmcnt(0)
	global_store_dwordx4 v[32:33], v[16:19], off offset:256
	ds_bpermute_b32 v96, v231, v96
	ds_bpermute_b32 v97, v231, v97
	ds_bpermute_b32 v98, v231, v98
	ds_bpermute_b32 v99, v231, v99
	s_waitcnt lgkmcnt(0)
	global_store_dwordx4 v[112:113], v[96:99], off offset:256
	v_cvt_pk_bf16_f32 v83, v78, v79
	v_add_co_u32_e32 v18, vcc, s9, v150
	v_lshl_add_u64 v[96:97], v[146:147], 0, v[92:93]
	v_lshlrev_b64 v[76:77], 12, v[76:77]
	s_mov_b64 s[50:51], 0xb0000
	v_addc_co_u32_e32 v19, vcc, 0, v151, vcc
	v_cvt_pk_bf16_f32 v128, v128, v129
	v_cvt_pk_bf16_f32 v129, v130, v131
	v_cvt_pk_bf16_f32 v130, v124, v125
	v_cvt_pk_bf16_f32 v131, v126, v127
	v_cvt_pk_bf16_f32 v108, v120, v121
	v_cvt_pk_bf16_f32 v109, v122, v123
	v_cvt_pk_bf16_f32 v110, v116, v117
	v_cvt_pk_bf16_f32 v111, v118, v119
	v_cvt_pk_bf16_f32 v92, v104, v105
	v_cvt_pk_bf16_f32 v93, v106, v107
	v_cvt_pk_bf16_f32 v94, v100, v101
	v_cvt_pk_bf16_f32 v95, v102, v103
	ds_bpermute_b32 v80, v231, v80
	ds_bpermute_b32 v81, v231, v81
	ds_bpermute_b32 v82, v231, v82
	ds_bpermute_b32 v83, v231, v83
	s_waitcnt lgkmcnt(0)
	global_store_dwordx4 v[96:97], v[80:83], off offset:256
	v_cvt_pk_bf16_f32 v78, v84, v85
	v_cvt_pk_bf16_f32 v79, v86, v87
	v_lshl_add_u64 v[80:81], v[146:147], 0, v[76:77]
	v_cvt_pk_bf16_f32 v76, v88, v89
	v_cvt_pk_bf16_f32 v77, v90, v91
	v_cvt_pk_bf16_f32 v75, v70, v71
	v_cvt_pk_bf16_f32 v67, v62, v63
	v_cvt_pk_bf16_f32 v44, v56, v57
	v_cvt_pk_bf16_f32 v45, v58, v59
	v_cvt_pk_bf16_f32 v46, v52, v53
	v_cvt_pk_bf16_f32 v47, v54, v55
	v_cvt_pk_bf16_f32 v28, v40, v41
	v_cvt_pk_bf16_f32 v29, v42, v43
	v_cvt_pk_bf16_f32 v30, v36, v37
	v_cvt_pk_bf16_f32 v31, v38, v39
	v_lshl_add_u64 v[16:17], v[150:151], 0, s[50:51]
	v_cvt_pk_bf16_f32 v12, v24, v25
	v_cvt_pk_bf16_f32 v13, v26, v27
	v_cvt_pk_bf16_f32 v14, v20, v21
	v_cvt_pk_bf16_f32 v15, v22, v23
	v_cvt_pk_bf16_f32 v8, v8, v9
	v_cvt_pk_bf16_f32 v9, v10, v11
	v_cvt_pk_bf16_f32 v10, v4, v5
	v_cvt_pk_bf16_f32 v11, v6, v7
	s_and_b64 vcc, exec, s[0:1]
	s_mov_b64 s[0:1], -1
	ds_bpermute_b32 v128, v231, v128
	ds_bpermute_b32 v129, v231, v129
	ds_bpermute_b32 v130, v231, v130
	ds_bpermute_b32 v131, v231, v131
	s_waitcnt lgkmcnt(0)
	global_store_dwordx4 v[150:151], v[128:131], off
	ds_bpermute_b32 v108, v231, v108
	ds_bpermute_b32 v109, v231, v109
	ds_bpermute_b32 v110, v231, v110
	ds_bpermute_b32 v111, v231, v111
	s_waitcnt lgkmcnt(0)
	global_store_dwordx4 v[112:113], v[108:111], off
	ds_bpermute_b32 v92, v231, v92
	ds_bpermute_b32 v93, v231, v93
	ds_bpermute_b32 v94, v231, v94
	ds_bpermute_b32 v95, v231, v95
	s_waitcnt lgkmcnt(0)
	global_store_dwordx4 v[96:97], v[92:95], off
	ds_bpermute_b32 v76, v231, v76
	ds_bpermute_b32 v77, v231, v77
	ds_bpermute_b32 v78, v231, v78
	ds_bpermute_b32 v79, v231, v79
	s_waitcnt lgkmcnt(0)
	global_store_dwordx4 v[80:81], v[76:79], off
	ds_bpermute_b32 v72, v231, v72
	ds_bpermute_b32 v73, v231, v73
	ds_bpermute_b32 v74, v231, v74
	ds_bpermute_b32 v75, v231, v75
	s_waitcnt lgkmcnt(0)
	global_store_dwordx4 v[80:81], v[72:75], off offset:256
	ds_bpermute_b32 v64, v231, v64
	ds_bpermute_b32 v65, v231, v65
	ds_bpermute_b32 v66, v231, v66
	ds_bpermute_b32 v67, v231, v67
	s_waitcnt lgkmcnt(0)
	global_store_dwordx4 v[60:61], v[64:67], off
	ds_bpermute_b32 v44, v231, v44
	ds_bpermute_b32 v45, v231, v45
	ds_bpermute_b32 v46, v231, v46
	ds_bpermute_b32 v47, v231, v47
	s_waitcnt lgkmcnt(0)
	global_store_dwordx4 v[50:51], v[44:47], off
	ds_bpermute_b32 v28, v231, v28
	ds_bpermute_b32 v29, v231, v29
	ds_bpermute_b32 v30, v231, v30
	ds_bpermute_b32 v31, v231, v31
	s_waitcnt lgkmcnt(0)
	global_store_dwordx4 v[34:35], v[28:31], off
	ds_bpermute_b32 v12, v231, v12
	ds_bpermute_b32 v13, v231, v13
	ds_bpermute_b32 v14, v231, v14
	ds_bpermute_b32 v15, v231, v15
	s_waitcnt lgkmcnt(0)
	global_store_dwordx4 v[18:19], v[12:15], off
	ds_bpermute_b32 v8, v231, v8
	ds_bpermute_b32 v9, v231, v9
	ds_bpermute_b32 v10, v231, v10
	ds_bpermute_b32 v11, v231, v11
	s_waitcnt lgkmcnt(0)
	global_store_dwordx4 v[16:17], v[8:11], off offset:256
	s_cbranch_vccnz .LBB0_515
	s_andn2_b64 vcc, exec, s[36:37]
	s_cbranch_vccnz .LBB0_514
	s_barrier
	s_branch .LBB0_514

.LBB0_688:
	v_lshrrev_b32_e32 v20, 1, v10
	v_and_b32_e32 v20, 24, v20
	v_and_b32_e32 v11, 15, v10
	v_lshlrev_b32_e32 v21, 1, v20
	v_lshlrev_b32_e32 v10, 2, v10
	s_lshl_b32 s13, s13, 5
	v_bfe_u32 v1, v0, 2, 4
	v_lshl_or_b32 v1, s16, 6, v1
	v_bfe_u32 v231, v0, 2, 4
	v_and_b32_e32 v230, 3, v0
	v_lshl_or_b32 v231, v230, 4, v231
	v_lshlrev_b32_e32 v231, 2, v231
	v_lshl_or_b32 v11, v11, 6, v21
	s_lshl_b32 s16, s16, 13
	v_and_b32_e32 v10, 32, v10
	s_and_b32 s13, s13, 0x60
	v_lshl_add_u64 v[12:13], s[90:91], 0, v[2:3]
	v_mov_b32_e32 v133, v3
	v_readlane_b32 s88, v252, 37
	v_bitop3_b32 v21, v11, s16, v10 bitop3:0xde
	s_lshl_b32 s16, s13, 7
	v_lshl_add_u64 v[14:15], s[90:91], 0, v[132:133]
	v_mov_b32_e32 v137, v3
	v_readlane_b32 s89, v252, 38
	v_bitop3_b32 v144, v11, s16, v10 bitop3:0xde
	s_add_i32 m0, s60, 0x18000
	v_lshl_add_u64 v[10:11], v[12:13], 0, s[66:67]
	v_lshl_add_u64 v[16:17], s[88:89], 0, v[136:137]
	v_mov_b32_e32 v135, v3
	s_waitcnt vmcnt(2)
	s_barrier
	global_load_lds_dwordx4 v[10:11], off
	v_lshl_add_u64 v[10:11], v[14:15], 0, s[66:67]
	s_add_i32 m0, s60, 0x1a000
	s_add_i32 s64, s60, 0x8000
	s_add_i32 s58, s60, 0xa000
	v_lshl_add_u64 v[18:19], s[88:89], 0, v[134:135]
	global_load_lds_dwordx4 v[10:11], off
	v_lshl_add_u64 v[10:11], v[16:17], 0, s[66:67]
	s_mov_b32 m0, s64
	s_add_u32 s16, s90, 0x80080
	global_load_lds_dwordx4 v[10:11], off
	v_lshl_add_u64 v[10:11], v[18:19], 0, s[66:67]
	s_mov_b32 m0, s58
	s_addc_u32 s17, s91, 0
	global_load_lds_dwordx4 v[10:11], off
	s_add_i32 m0, s60, 0x1c000
	v_lshl_add_u64 v[10:11], s[16:17], 0, v[2:3]
	global_load_lds_dwordx4 v[10:11], off
	v_lshl_add_u64 v[10:11], s[16:17], 0, v[132:133]
	s_add_i32 m0, s60, 0x1e000
	s_cmpk_lt_u32 s12, 0x100
	global_load_lds_dwordx4 v[10:11], off
	v_lshlrev_b32_e32 v10, 15, v8
	v_and_b32_e32 v10, 0xffff0000, v10
	v_lshl_add_u32 v7, v7, 12, v10
	v_and_b32_e32 v8, 1, v8
	v_lshl_or_b32 v7, v8, 6, v7
	v_lshl_add_u32 v138, v9, 1, v7
	v_lshlrev_b32_e32 v7, 15, v4
	v_and_b32_e32 v7, 0xffff0000, v7
	s_waitcnt vmcnt(6)
	v_lshl_add_u32 v5, v5, 12, v7
	v_and_b32_e32 v4, 1, v4
	v_lshl_or_b32 v4, v4, 6, v5
	v_readlane_b32 s16, v252, 33
	s_cselect_b64 s[68:69], -1, 0
	v_and_b32_e32 v145, 3, v0
	v_lshl_or_b32 v145, v145, 3, s13
	v_mov_b32_e32 v139, v3
	v_lshl_add_u32 v140, v6, 1, v4
	v_mov_b32_e32 v141, v3
	s_mov_b32 s59, 0
	v_add_u32_e32 v146, 0, v21
	v_readlane_b32 s12, v252, 32
	s_mov_b32 s13, s16
	s_barrier
	v_readlane_b32 s17, v252, 34
	s_branch .LBB0_691

.LBB0_697:
	v_max_f32_e32 v124, v124, v124
	v_max_f32_e32 v125, v125, v125
	v_max_f32_e32 v124, 0, v124
	v_max_f32_e32 v125, 0, v125
	v_pk_mul_f32 v[152:153], v[124:125], v[124:125]
	v_max_f32_e32 v125, v126, v126
	v_lshl_or_b32 v142, s12, 8, v145
	v_lshl_add_u32 v148, s13, 8, v1
	v_max_f32_e32 v128, v128, v128
	v_max_f32_e32 v129, v129, v129
	v_max_f32_e32 v124, v130, v130
	v_max_f32_e32 v126, 0, v125
	v_max_f32_e32 v125, v131, v131
	v_max_f32_e32 v127, v127, v127
	v_ashrrev_i32_e32 v143, 31, v142
	v_ashrrev_i32_e32 v149, 31, v148
	v_max_f32_e32 v128, 0, v128
	v_max_f32_e32 v129, 0, v129
	v_max_f32_e32 v124, 0, v124
	v_max_f32_e32 v125, 0, v125
	v_max_f32_e32 v127, 0, v127
	v_lshl_add_u64 v[150:151], v[142:143], 1, s[38:39]
	v_lshlrev_b64 v[142:143], 14, v[148:149]
	v_pk_mul_f32 v[128:129], v[128:129], v[128:129]
	v_pk_mul_f32 v[130:131], v[124:125], v[124:125]
	v_pk_mul_f32 v[154:155], v[126:127], v[126:127]
	v_max_f32_e32 v116, v116, v116
	v_max_f32_e32 v117, v117, v117
	v_lshl_add_u64 v[142:143], v[150:151], 0, v[142:143]
	v_cvt_pk_bf16_f32 v124, v128, v129
	v_cvt_pk_bf16_f32 v125, v130, v131
	v_cvt_pk_bf16_f32 v126, v152, v153
	v_cvt_pk_bf16_f32 v127, v154, v155
	v_max_f32_e32 v116, 0, v116
	v_max_f32_e32 v117, 0, v117
	ds_bpermute_b32 v124, v231, v124
	ds_bpermute_b32 v125, v231, v125
	ds_bpermute_b32 v126, v231, v126
	ds_bpermute_b32 v127, v231, v127
	s_waitcnt lgkmcnt(0)
	global_store_dwordx4 v[142:143], v[124:127], off
	v_max_f32_e32 v120, v120, v120
	v_max_f32_e32 v121, v121, v121
	v_pk_mul_f32 v[124:125], v[116:117], v[116:117]
	v_max_f32_e32 v117, v118, v118
	v_max_f32_e32 v116, v122, v122
	v_max_f32_e32 v118, 0, v117
	v_max_f32_e32 v117, v123, v123
	v_max_f32_e32 v119, v119, v119
	v_max_f32_e32 v120, 0, v120
	v_max_f32_e32 v121, 0, v121
	v_max_f32_e32 v116, 0, v116
	v_max_f32_e32 v117, 0, v117
	v_max_f32_e32 v119, 0, v119
	v_pk_mul_f32 v[120:121], v[120:121], v[120:121]
	v_pk_mul_f32 v[122:123], v[116:117], v[116:117]
	v_pk_mul_f32 v[126:127], v[118:119], v[118:119]
	v_max_f32_e32 v108, v108, v108
	v_max_f32_e32 v109, v109, v109
	v_cvt_pk_bf16_f32 v116, v120, v121
	v_cvt_pk_bf16_f32 v117, v122, v123
	v_cvt_pk_bf16_f32 v118, v124, v125
	v_cvt_pk_bf16_f32 v119, v126, v127
	v_max_f32_e32 v108, 0, v108
	v_max_f32_e32 v109, 0, v109
	ds_bpermute_b32 v116, v231, v116
	ds_bpermute_b32 v117, v231, v117
	ds_bpermute_b32 v118, v231, v118
	ds_bpermute_b32 v119, v231, v119
	s_waitcnt lgkmcnt(0)
	global_store_dwordx4 v[142:143], v[116:119], off offset:256
	v_max_f32_e32 v112, v112, v112
	v_max_f32_e32 v113, v113, v113
	v_pk_mul_f32 v[118:119], v[108:109], v[108:109]
	v_max_f32_e32 v109, v110, v110
	v_or_b32_e32 v116, 16, v148
	v_max_f32_e32 v108, v114, v114
	v_max_f32_e32 v110, 0, v109
	v_max_f32_e32 v109, v115, v115
	v_max_f32_e32 v111, v111, v111
	v_ashrrev_i32_e32 v117, 31, v116
	v_max_f32_e32 v112, 0, v112
	v_max_f32_e32 v113, 0, v113
	v_max_f32_e32 v108, 0, v108
	v_max_f32_e32 v109, 0, v109
	v_max_f32_e32 v111, 0, v111
	v_lshlrev_b64 v[116:117], 14, v[116:117]
	v_pk_mul_f32 v[112:113], v[112:113], v[112:113]
	v_pk_mul_f32 v[114:115], v[108:109], v[108:109]
	v_pk_mul_f32 v[120:121], v[110:111], v[110:111]
	v_max_f32_e32 v100, v100, v100
	v_max_f32_e32 v101, v101, v101
	v_lshl_add_u64 v[116:117], v[150:151], 0, v[116:117]
	v_cvt_pk_bf16_f32 v108, v112, v113
	v_cvt_pk_bf16_f32 v109, v114, v115
	v_cvt_pk_bf16_f32 v110, v118, v119
	v_cvt_pk_bf16_f32 v111, v120, v121
	v_max_f32_e32 v100, 0, v100
	v_max_f32_e32 v101, 0, v101
	ds_bpermute_b32 v108, v231, v108
	ds_bpermute_b32 v109, v231, v109
	ds_bpermute_b32 v110, v231, v110
	ds_bpermute_b32 v111, v231, v111
	s_waitcnt lgkmcnt(0)
	global_store_dwordx4 v[116:117], v[108:111], off
	v_max_f32_e32 v104, v104, v104
	v_max_f32_e32 v105, v105, v105
	v_pk_mul_f32 v[108:109], v[100:101], v[100:101]
	v_max_f32_e32 v101, v102, v102
	v_max_f32_e32 v100, v106, v106
	v_max_f32_e32 v102, 0, v101
	v_max_f32_e32 v101, v107, v107
	v_max_f32_e32 v103, v103, v103
	v_max_f32_e32 v104, 0, v104
	v_max_f32_e32 v105, 0, v105
	v_max_f32_e32 v100, 0, v100
	v_max_f32_e32 v101, 0, v101
	v_max_f32_e32 v103, 0, v103
	v_pk_mul_f32 v[104:105], v[104:105], v[104:105]
	v_pk_mul_f32 v[106:107], v[100:101], v[100:101]
	v_pk_mul_f32 v[110:111], v[102:103], v[102:103]
	v_max_f32_e32 v92, v92, v92
	v_max_f32_e32 v93, v93, v93
	v_cvt_pk_bf16_f32 v100, v104, v105
	v_cvt_pk_bf16_f32 v101, v106, v107
	v_cvt_pk_bf16_f32 v102, v108, v109
	v_cvt_pk_bf16_f32 v103, v110, v111
	v_max_f32_e32 v92, 0, v92
	v_max_f32_e32 v93, 0, v93
	ds_bpermute_b32 v100, v231, v100
	ds_bpermute_b32 v101, v231, v101
	ds_bpermute_b32 v102, v231, v102
	ds_bpermute_b32 v103, v231, v103
	s_waitcnt lgkmcnt(0)
	global_store_dwordx4 v[116:117], v[100:103], off offset:256
	v_max_f32_e32 v96, v96, v96
	v_max_f32_e32 v97, v97, v97
	v_pk_mul_f32 v[102:103], v[92:93], v[92:93]
	v_max_f32_e32 v93, v94, v94
	v_or_b32_e32 v100, 32, v148
	v_max_f32_e32 v92, v98, v98
	v_max_f32_e32 v94, 0, v93
	v_max_f32_e32 v93, v99, v99
	v_max_f32_e32 v95, v95, v95
	v_ashrrev_i32_e32 v101, 31, v100
	v_max_f32_e32 v96, 0, v96
	v_max_f32_e32 v97, 0, v97
	v_max_f32_e32 v92, 0, v92
	v_max_f32_e32 v93, 0, v93
	v_max_f32_e32 v95, 0, v95
	v_lshlrev_b64 v[100:101], 14, v[100:101]
	v_pk_mul_f32 v[96:97], v[96:97], v[96:97]
	v_pk_mul_f32 v[98:99], v[92:93], v[92:93]
	v_pk_mul_f32 v[104:105], v[94:95], v[94:95]
	v_max_f32_e32 v84, v84, v84
	v_max_f32_e32 v85, v85, v85
	v_lshl_add_u64 v[100:101], v[150:151], 0, v[100:101]
	v_cvt_pk_bf16_f32 v92, v96, v97
	v_cvt_pk_bf16_f32 v93, v98, v99
	v_cvt_pk_bf16_f32 v94, v102, v103
	v_cvt_pk_bf16_f32 v95, v104, v105
	v_max_f32_e32 v84, 0, v84
	v_max_f32_e32 v85, 0, v85
	ds_bpermute_b32 v92, v231, v92
	ds_bpermute_b32 v93, v231, v93
	ds_bpermute_b32 v94, v231, v94
	ds_bpermute_b32 v95, v231, v95
	s_waitcnt lgkmcnt(0)
	global_store_dwordx4 v[100:101], v[92:95], off
	v_max_f32_e32 v88, v88, v88
	v_max_f32_e32 v89, v89, v89
	v_pk_mul_f32 v[92:93], v[84:85], v[84:85]
	v_max_f32_e32 v85, v86, v86
	v_max_f32_e32 v84, v90, v90
	v_max_f32_e32 v86, 0, v85
	v_max_f32_e32 v85, v91, v91
	v_max_f32_e32 v87, v87, v87
	v_max_f32_e32 v88, 0, v88
	v_max_f32_e32 v89, 0, v89
	v_max_f32_e32 v84, 0, v84
	v_max_f32_e32 v85, 0, v85
	v_max_f32_e32 v87, 0, v87
	v_pk_mul_f32 v[88:89], v[88:89], v[88:89]
	v_pk_mul_f32 v[90:91], v[84:85], v[84:85]
	v_pk_mul_f32 v[94:95], v[86:87], v[86:87]
	v_max_f32_e32 v76, v76, v76
	v_max_f32_e32 v77, v77, v77
	v_cvt_pk_bf16_f32 v84, v88, v89
	v_cvt_pk_bf16_f32 v85, v90, v91
	v_cvt_pk_bf16_f32 v86, v92, v93
	v_cvt_pk_bf16_f32 v87, v94, v95
	v_max_f32_e32 v76, 0, v76
	v_max_f32_e32 v77, 0, v77
	ds_bpermute_b32 v84, v231, v84
	ds_bpermute_b32 v85, v231, v85
	ds_bpermute_b32 v86, v231, v86
	ds_bpermute_b32 v87, v231, v87
	s_waitcnt lgkmcnt(0)
	global_store_dwordx4 v[100:101], v[84:87], off offset:256
	v_max_f32_e32 v80, v80, v80
	v_max_f32_e32 v81, v81, v81
	v_pk_mul_f32 v[86:87], v[76:77], v[76:77]
	v_max_f32_e32 v77, v78, v78
	v_or_b32_e32 v84, 48, v148
	v_max_f32_e32 v76, v82, v82
	v_max_f32_e32 v78, 0, v77
	v_max_f32_e32 v77, v83, v83
	v_max_f32_e32 v79, v79, v79
	v_ashrrev_i32_e32 v85, 31, v84
	v_max_f32_e32 v80, 0, v80
	v_max_f32_e32 v81, 0, v81
	v_max_f32_e32 v76, 0, v76
	v_max_f32_e32 v77, 0, v77
	v_max_f32_e32 v79, 0, v79
	v_lshlrev_b64 v[84:85], 14, v[84:85]
	v_pk_mul_f32 v[80:81], v[80:81], v[80:81]
	v_pk_mul_f32 v[82:83], v[76:77], v[76:77]
	v_pk_mul_f32 v[88:89], v[78:79], v[78:79]
	v_max_f32_e32 v68, v68, v68
	v_max_f32_e32 v69, v69, v69
	v_lshl_add_u64 v[84:85], v[150:151], 0, v[84:85]
	v_cvt_pk_bf16_f32 v76, v80, v81
	v_cvt_pk_bf16_f32 v77, v82, v83
	v_cvt_pk_bf16_f32 v78, v86, v87
	v_cvt_pk_bf16_f32 v79, v88, v89
	v_max_f32_e32 v68, 0, v68
	v_max_f32_e32 v69, 0, v69
	ds_bpermute_b32 v76, v231, v76
	ds_bpermute_b32 v77, v231, v77
	ds_bpermute_b32 v78, v231, v78
	ds_bpermute_b32 v79, v231, v79
	s_waitcnt lgkmcnt(0)
	global_store_dwordx4 v[84:85], v[76:79], off
	v_max_f32_e32 v72, v72, v72
	v_max_f32_e32 v73, v73, v73
	v_pk_mul_f32 v[76:77], v[68:69], v[68:69]
	v_max_f32_e32 v69, v70, v70
	v_max_f32_e32 v68, v74, v74
	v_max_f32_e32 v70, 0, v69
	v_max_f32_e32 v69, v75, v75
	v_max_f32_e32 v71, v71, v71
	v_max_f32_e32 v72, 0, v72
	v_max_f32_e32 v73, 0, v73
	v_max_f32_e32 v68, 0, v68
	v_max_f32_e32 v69, 0, v69
	v_max_f32_e32 v71, 0, v71
	v_pk_mul_f32 v[72:73], v[72:73], v[72:73]
	v_pk_mul_f32 v[74:75], v[68:69], v[68:69]
	v_pk_mul_f32 v[78:79], v[70:71], v[70:71]
	v_max_f32_e32 v60, v60, v60
	v_max_f32_e32 v61, v61, v61
	v_cvt_pk_bf16_f32 v68, v72, v73
	v_cvt_pk_bf16_f32 v69, v74, v75
	v_cvt_pk_bf16_f32 v70, v76, v77
	v_cvt_pk_bf16_f32 v71, v78, v79
	v_max_f32_e32 v60, 0, v60
	v_max_f32_e32 v61, 0, v61
	ds_bpermute_b32 v68, v231, v68
	ds_bpermute_b32 v69, v231, v69
	ds_bpermute_b32 v70, v231, v70
	ds_bpermute_b32 v71, v231, v71
	s_waitcnt lgkmcnt(0)
	global_store_dwordx4 v[84:85], v[68:71], off offset:256
	v_max_f32_e32 v64, v64, v64
	v_max_f32_e32 v65, v65, v65
	v_pk_mul_f32 v[70:71], v[60:61], v[60:61]
	v_max_f32_e32 v61, v62, v62
	s_mov_b64 s[12:13], 0x200000
	v_max_f32_e32 v64, 0, v64
	v_max_f32_e32 v65, 0, v65
	v_max_f32_e32 v60, v66, v66
	v_max_f32_e32 v62, 0, v61
	v_max_f32_e32 v61, v67, v67
	v_max_f32_e32 v63, v63, v63
	v_lshl_add_u64 v[68:69], v[142:143], 0, s[12:13]
	v_pk_mul_f32 v[64:65], v[64:65], v[64:65]
	v_max_f32_e32 v60, 0, v60
	v_max_f32_e32 v61, 0, v61
	v_max_f32_e32 v63, 0, v63
	s_mov_b32 s12, 0x200000
	v_pk_mul_f32 v[66:67], v[60:61], v[60:61]
	v_pk_mul_f32 v[72:73], v[62:63], v[62:63]
	v_cvt_pk_bf16_f32 v60, v64, v65
	v_add_co_u32_e32 v64, vcc, s12, v142
	v_max_f32_e32 v52, v52, v52
	v_max_f32_e32 v53, v53, v53
	v_cvt_pk_bf16_f32 v61, v66, v67
	v_cvt_pk_bf16_f32 v62, v70, v71
	v_cvt_pk_bf16_f32 v63, v72, v73
	v_addc_co_u32_e32 v65, vcc, 0, v143, vcc
	v_max_f32_e32 v52, 0, v52
	v_max_f32_e32 v53, 0, v53
	ds_bpermute_b32 v60, v231, v60
	ds_bpermute_b32 v61, v231, v61
	ds_bpermute_b32 v62, v231, v62
	ds_bpermute_b32 v63, v231, v63
	s_waitcnt lgkmcnt(0)
	global_store_dwordx4 v[64:65], v[60:63], off
	v_max_f32_e32 v56, v56, v56
	v_max_f32_e32 v57, v57, v57
	v_pk_mul_f32 v[60:61], v[52:53], v[52:53]
	v_max_f32_e32 v53, v54, v54
	v_max_f32_e32 v52, v58, v58
	v_max_f32_e32 v54, 0, v53
	v_max_f32_e32 v53, v59, v59
	v_max_f32_e32 v55, v55, v55
	v_max_f32_e32 v56, 0, v56
	v_max_f32_e32 v57, 0, v57
	v_max_f32_e32 v52, 0, v52
	v_max_f32_e32 v53, 0, v53
	v_max_f32_e32 v55, 0, v55
	v_pk_mul_f32 v[56:57], v[56:57], v[56:57]
	v_pk_mul_f32 v[58:59], v[52:53], v[52:53]
	v_pk_mul_f32 v[62:63], v[54:55], v[54:55]
	v_max_f32_e32 v44, v44, v44
	v_max_f32_e32 v45, v45, v45
	v_cvt_pk_bf16_f32 v52, v56, v57
	v_cvt_pk_bf16_f32 v53, v58, v59
	v_cvt_pk_bf16_f32 v54, v60, v61
	v_cvt_pk_bf16_f32 v55, v62, v63
	v_max_f32_e32 v44, 0, v44
	v_max_f32_e32 v45, 0, v45
	ds_bpermute_b32 v52, v231, v52
	ds_bpermute_b32 v53, v231, v53
	ds_bpermute_b32 v54, v231, v54
	ds_bpermute_b32 v55, v231, v55
	s_waitcnt lgkmcnt(0)
	global_store_dwordx4 v[68:69], v[52:55], off offset:256
	v_max_f32_e32 v48, v48, v48
	v_max_f32_e32 v49, v49, v49
	v_pk_mul_f32 v[54:55], v[44:45], v[44:45]
	v_max_f32_e32 v45, v46, v46
	s_mov_b64 s[12:13], 0x240000
	v_max_f32_e32 v48, 0, v48
	v_max_f32_e32 v49, 0, v49
	v_max_f32_e32 v44, v50, v50
	v_max_f32_e32 v46, 0, v45
	v_max_f32_e32 v45, v51, v51
	v_max_f32_e32 v47, v47, v47
	v_lshl_add_u64 v[52:53], v[142:143], 0, s[12:13]
	v_pk_mul_f32 v[48:49], v[48:49], v[48:49]
	v_max_f32_e32 v44, 0, v44
	v_max_f32_e32 v45, 0, v45
	v_max_f32_e32 v47, 0, v47
	s_mov_b32 s12, 0x240000
	v_pk_mul_f32 v[50:51], v[44:45], v[44:45]
	v_pk_mul_f32 v[56:57], v[46:47], v[46:47]
	v_cvt_pk_bf16_f32 v44, v48, v49
	v_add_co_u32_e32 v48, vcc, s12, v142
	v_max_f32_e32 v36, v36, v36
	v_max_f32_e32 v37, v37, v37
	v_cvt_pk_bf16_f32 v45, v50, v51
	v_cvt_pk_bf16_f32 v46, v54, v55
	v_cvt_pk_bf16_f32 v47, v56, v57
	v_addc_co_u32_e32 v49, vcc, 0, v143, vcc
	v_max_f32_e32 v36, 0, v36
	v_max_f32_e32 v37, 0, v37
	ds_bpermute_b32 v44, v231, v44
	ds_bpermute_b32 v45, v231, v45
	ds_bpermute_b32 v46, v231, v46
	ds_bpermute_b32 v47, v231, v47
	s_waitcnt lgkmcnt(0)
	global_store_dwordx4 v[48:49], v[44:47], off
	v_max_f32_e32 v40, v40, v40
	v_max_f32_e32 v41, v41, v41
	v_pk_mul_f32 v[44:45], v[36:37], v[36:37]
	v_max_f32_e32 v37, v38, v38
	v_max_f32_e32 v36, v42, v42
	v_max_f32_e32 v38, 0, v37
	v_max_f32_e32 v37, v43, v43
	v_max_f32_e32 v39, v39, v39
	v_max_f32_e32 v40, 0, v40
	v_max_f32_e32 v41, 0, v41
	v_max_f32_e32 v36, 0, v36
	v_max_f32_e32 v37, 0, v37
	v_max_f32_e32 v39, 0, v39
	v_pk_mul_f32 v[40:41], v[40:41], v[40:41]
	v_pk_mul_f32 v[42:43], v[36:37], v[36:37]
	v_pk_mul_f32 v[46:47], v[38:39], v[38:39]
	v_max_f32_e32 v28, v28, v28
	v_max_f32_e32 v29, v29, v29
	v_cvt_pk_bf16_f32 v36, v40, v41
	v_cvt_pk_bf16_f32 v37, v42, v43
	v_cvt_pk_bf16_f32 v38, v44, v45
	v_cvt_pk_bf16_f32 v39, v46, v47
	v_max_f32_e32 v28, 0, v28
	v_max_f32_e32 v29, 0, v29
	ds_bpermute_b32 v36, v231, v36
	ds_bpermute_b32 v37, v231, v37
	ds_bpermute_b32 v38, v231, v38
	ds_bpermute_b32 v39, v231, v39
	s_waitcnt lgkmcnt(0)
	global_store_dwordx4 v[52:53], v[36:39], off offset:256
	v_max_f32_e32 v32, v32, v32
	v_max_f32_e32 v33, v33, v33
	v_pk_mul_f32 v[38:39], v[28:29], v[28:29]
	v_max_f32_e32 v29, v30, v30
	s_mov_b64 s[12:13], 0x280000
	v_max_f32_e32 v32, 0, v32
	v_max_f32_e32 v33, 0, v33
	v_max_f32_e32 v28, v34, v34
	v_max_f32_e32 v30, 0, v29
	v_max_f32_e32 v29, v35, v35
	v_max_f32_e32 v31, v31, v31
	v_lshl_add_u64 v[36:37], v[142:143], 0, s[12:13]
	v_pk_mul_f32 v[32:33], v[32:33], v[32:33]
	v_max_f32_e32 v28, 0, v28
	v_max_f32_e32 v29, 0, v29
	v_max_f32_e32 v31, 0, v31
	s_mov_b32 s12, 0x280000
	v_pk_mul_f32 v[34:35], v[28:29], v[28:29]
	v_pk_mul_f32 v[40:41], v[30:31], v[30:31]
	v_cvt_pk_bf16_f32 v28, v32, v33
	v_add_co_u32_e32 v32, vcc, s12, v142
	v_max_f32_e32 v20, v20, v20
	v_max_f32_e32 v21, v21, v21
	v_cvt_pk_bf16_f32 v29, v34, v35
	v_cvt_pk_bf16_f32 v30, v38, v39
	v_cvt_pk_bf16_f32 v31, v40, v41
	v_addc_co_u32_e32 v33, vcc, 0, v143, vcc
	v_max_f32_e32 v20, 0, v20
	v_max_f32_e32 v21, 0, v21
	ds_bpermute_b32 v28, v231, v28
	ds_bpermute_b32 v29, v231, v29
	ds_bpermute_b32 v30, v231, v30
	ds_bpermute_b32 v31, v231, v31
	s_waitcnt lgkmcnt(0)
	global_store_dwordx4 v[32:33], v[28:31], off
	v_max_f32_e32 v24, v24, v24
	v_max_f32_e32 v25, v25, v25
	v_pk_mul_f32 v[28:29], v[20:21], v[20:21]
	v_max_f32_e32 v21, v22, v22
	v_max_f32_e32 v20, v26, v26
	v_max_f32_e32 v22, 0, v21
	v_max_f32_e32 v21, v27, v27
	v_max_f32_e32 v23, v23, v23
	v_max_f32_e32 v24, 0, v24
	v_max_f32_e32 v25, 0, v25
	v_max_f32_e32 v20, 0, v20
	v_max_f32_e32 v21, 0, v21
	v_max_f32_e32 v23, 0, v23
	v_pk_mul_f32 v[24:25], v[24:25], v[24:25]
	v_pk_mul_f32 v[26:27], v[20:21], v[20:21]
	v_pk_mul_f32 v[30:31], v[22:23], v[22:23]
	v_max_f32_e32 v12, v12, v12
	v_max_f32_e32 v13, v13, v13
	v_cvt_pk_bf16_f32 v20, v24, v25
	v_cvt_pk_bf16_f32 v21, v26, v27
	v_cvt_pk_bf16_f32 v22, v28, v29
	v_cvt_pk_bf16_f32 v23, v30, v31
	v_max_f32_e32 v12, 0, v12
	v_max_f32_e32 v13, 0, v13
	ds_bpermute_b32 v20, v231, v20
	ds_bpermute_b32 v21, v231, v21
	ds_bpermute_b32 v22, v231, v22
	ds_bpermute_b32 v23, v231, v23
	s_waitcnt lgkmcnt(0)
	global_store_dwordx4 v[36:37], v[20:23], off offset:256
	v_max_f32_e32 v16, v16, v16
	v_max_f32_e32 v17, v17, v17
	v_pk_mul_f32 v[22:23], v[12:13], v[12:13]
	v_max_f32_e32 v13, v14, v14
	s_mov_b64 s[12:13], 0x2c0000
	v_max_f32_e32 v16, 0, v16
	v_max_f32_e32 v17, 0, v17
	v_max_f32_e32 v12, v18, v18
	v_max_f32_e32 v14, 0, v13
	v_max_f32_e32 v13, v19, v19
	v_max_f32_e32 v15, v15, v15
	v_lshl_add_u64 v[20:21], v[142:143], 0, s[12:13]
	v_pk_mul_f32 v[16:17], v[16:17], v[16:17]
	v_max_f32_e32 v12, 0, v12
	v_max_f32_e32 v13, 0, v13
	v_max_f32_e32 v15, 0, v15
	s_mov_b32 s12, 0x2c0000
	v_pk_mul_f32 v[18:19], v[12:13], v[12:13]
	v_pk_mul_f32 v[24:25], v[14:15], v[14:15]
	v_cvt_pk_bf16_f32 v12, v16, v17
	v_add_co_u32_e32 v16, vcc, s12, v142
	v_max_f32_e32 v4, v4, v4
	v_max_f32_e32 v5, v5, v5
	v_cvt_pk_bf16_f32 v13, v18, v19
	v_cvt_pk_bf16_f32 v14, v22, v23
	v_cvt_pk_bf16_f32 v15, v24, v25
	v_addc_co_u32_e32 v17, vcc, 0, v143, vcc
	v_max_f32_e32 v4, 0, v4
	v_max_f32_e32 v5, 0, v5
	ds_bpermute_b32 v12, v231, v12
	ds_bpermute_b32 v13, v231, v13
	ds_bpermute_b32 v14, v231, v14
	ds_bpermute_b32 v15, v231, v15
	s_waitcnt lgkmcnt(0)
	global_store_dwordx4 v[16:17], v[12:15], off
	v_max_f32_e32 v8, v8, v8
	v_max_f32_e32 v9, v9, v9
	v_pk_mul_f32 v[12:13], v[4:5], v[4:5]
	v_max_f32_e32 v5, v6, v6
	v_max_f32_e32 v4, v10, v10
	v_max_f32_e32 v6, 0, v5
	v_max_f32_e32 v5, v11, v11
	v_max_f32_e32 v7, v7, v7
	v_max_f32_e32 v8, 0, v8
	v_max_f32_e32 v9, 0, v9
	v_max_f32_e32 v4, 0, v4
	v_max_f32_e32 v5, 0, v5
	v_max_f32_e32 v7, 0, v7
	v_pk_mul_f32 v[8:9], v[8:9], v[8:9]
	v_pk_mul_f32 v[10:11], v[4:5], v[4:5]
	v_pk_mul_f32 v[14:15], v[6:7], v[6:7]
	v_cvt_pk_bf16_f32 v4, v8, v9
	v_cvt_pk_bf16_f32 v5, v10, v11
	v_cvt_pk_bf16_f32 v6, v12, v13
	v_cvt_pk_bf16_f32 v7, v14, v15
	s_andn2_b64 vcc, exec, s[36:37]
	s_mov_b64 s[36:37], -1
	ds_bpermute_b32 v4, v231, v4
	ds_bpermute_b32 v5, v231, v5
	ds_bpermute_b32 v6, v231, v6
	ds_bpermute_b32 v7, v231, v7
	s_waitcnt lgkmcnt(0)
	global_store_dwordx4 v[20:21], v[4:7], off offset:256
	s_cbranch_vccnz .LBB0_690
	s_andn2_b64 vcc, exec, s[0:1]
	s_cbranch_vccnz .LBB0_689
	s_barrier
	s_branch .LBB0_689

.LBB0_755:
	v_readlane_b32 s84, v252, 20
	s_add_u32 s50, s86, 0x200080
	v_mov_b32_e32 v133, v3
	v_readlane_b32 s85, v252, 21
	s_addc_u32 s51, s87, 0
	s_add_i32 m0, s16, 0x18000
	v_lshl_add_u64 v[4:5], v[4:5], 0, s[66:67]
	v_lshl_add_u64 v[16:17], s[84:85], 0, v[132:133]
	v_mov_b32_e32 v135, v3
	s_waitcnt vmcnt(2)
	s_barrier
	global_load_lds_dwordx4 v[4:5], off
	v_lshl_add_u64 v[4:5], v[6:7], 0, s[66:67]
	s_add_i32 m0, s16, 0x1a000
	s_add_i32 s60, s16, 0x8000
	v_lshl_add_u64 v[18:19], s[84:85], 0, v[134:135]
	global_load_lds_dwordx4 v[4:5], off
	v_lshl_add_u64 v[4:5], v[16:17], 0, s[66:67]
	s_mov_b32 m0, s60
	s_add_i32 s61, s16, 0xa000
	global_load_lds_dwordx4 v[4:5], off
	v_lshl_add_u64 v[4:5], v[18:19], 0, s[66:67]
	s_mov_b32 m0, s61
	v_lshrrev_b32_e32 v20, 1, v14
	global_load_lds_dwordx4 v[4:5], off
	s_add_i32 m0, s16, 0x1c000
	v_lshl_add_u64 v[4:5], s[50:51], 0, v[2:3]
	global_load_lds_dwordx4 v[4:5], off
	v_lshl_add_u64 v[4:5], s[50:51], 0, v[136:137]
	s_add_i32 m0, s16, 0x1e000
	v_and_b32_e32 v20, 24, v20
	global_load_lds_dwordx4 v[4:5], off
	v_lshlrev_b32_e32 v4, 17, v8
	v_and_b32_e32 v4, 0xfffc0000, v4
	v_lshl_add_u32 v4, v9, 14, v4
	v_and_b32_e32 v5, 1, v8
	v_lshl_or_b32 v4, v5, 6, v4
	s_lshl_b32 s1, s1, 5
	v_lshl_add_u32 v138, v10, 1, v4
	v_lshlrev_b32_e32 v4, 17, v11
	v_and_b32_e32 v15, 15, v14
	v_lshlrev_b32_e32 v21, 1, v20
	v_lshlrev_b32_e32 v14, 2, v14
	s_and_b32 s1, s1, 0x60
	v_and_b32_e32 v4, 0xfffc0000, v4
	v_bfe_u32 v1, v0, 2, 4
	v_lshl_or_b32 v1, s23, 6, v1
	v_bfe_u32 v231, v0, 2, 4
	v_and_b32_e32 v230, 3, v0
	v_lshl_or_b32 v231, v230, 4, v231
	v_lshlrev_b32_e32 v231, 2, v231
	v_lshl_or_b32 v15, v15, 6, v21
	v_and_b32_e32 v14, 32, v14
	s_lshl_b32 s23, s23, 13
	s_lshl_b32 s29, s1, 7
	s_waitcnt vmcnt(6)
	v_lshl_add_u32 v4, v12, 14, v4
	v_and_b32_e32 v5, 1, v11
	v_bitop3_b32 v142, v15, s29, v14 bitop3:0xde
	v_bitop3_b32 v14, v15, s23, v14 bitop3:0xde
	s_cmpk_lt_u32 s0, 0x100
	v_and_b32_e32 v143, 3, v0
	v_lshl_or_b32 v143, v143, 3, s1
	v_lshl_or_b32 v4, v5, 6, v4
	v_readlane_b32 s0, v252, 17
	s_cselect_b64 s[68:69], -1, 0
	v_mov_b32_e32 v139, v3
	v_lshl_add_u32 v140, v13, 1, v4
	v_mov_b32_e32 v141, v3
	s_mov_b64 s[88:89], -1
	s_movk_i32 s51, 0x80
	s_mov_b32 s50, 0
	v_add_u32_e32 v144, 0, v14
	s_mov_b32 s54, s0
	s_barrier
	v_readlane_b32 s1, v252, 18
	s_branch .LBB0_758

.LBB0_766:
	s_lshl_b32 s23, s54, 8
	s_add_i32 s29, s23, 0xffffe000
	s_cmp_eq_u32 s50, 0
	s_cselect_b32 s23, s23, s29
	s_cselect_b32 s29, s31, s27
	s_cselect_b32 s35, s30, s26
	v_lshl_or_b32 v148, s22, 8, v143
	v_add_u32_e32 v150, s23, v1
	v_mov_b32_e32 v146, s35
	v_mov_b32_e32 v147, s29
	v_ashrrev_i32_e32 v149, 31, v148
	v_ashrrev_i32_e32 v151, 31, v150
	v_lshl_add_u64 v[146:147], v[148:149], 1, v[146:147]
	v_lshlrev_b64 v[148:149], 12, v[150:151]
	v_lshl_add_u64 v[148:149], v[146:147], 0, v[148:149]
	s_mov_b32 s23, 0x80000
	s_mov_b64 s[50:51], 0x80000
	v_cvt_pk_bf16_f32 v64, v64, v65
	v_cvt_pk_bf16_f32 v65, v66, v67
	v_cvt_pk_bf16_f32 v66, v60, v61
	v_add_co_u32_e32 v60, vcc, s23, v148
	v_cvt_pk_bf16_f32 v72, v72, v73
	v_cvt_pk_bf16_f32 v73, v74, v75
	v_cvt_pk_bf16_f32 v74, v68, v69
	v_lshl_add_u64 v[68:69], v[148:149], 0, s[50:51]
	v_addc_co_u32_e32 v61, vcc, 0, v149, vcc
	v_cvt_pk_bf16_f32 v48, v48, v49
	v_cvt_pk_bf16_f32 v49, v50, v51
	v_cvt_pk_bf16_f32 v50, v44, v45
	v_cvt_pk_bf16_f32 v51, v46, v47
	s_mov_b32 s23, 0x90000
	ds_bpermute_b32 v48, v231, v48
	ds_bpermute_b32 v49, v231, v49
	ds_bpermute_b32 v50, v231, v50
	ds_bpermute_b32 v51, v231, v51
	s_waitcnt lgkmcnt(0)
	global_store_dwordx4 v[68:69], v[48:51], off offset:256
	s_mov_b64 s[50:51], 0x90000
	v_cvt_pk_bf16_f32 v112, v112, v113
	v_add_co_u32_e32 v50, vcc, s23, v148
	v_cvt_pk_bf16_f32 v113, v114, v115
	v_cvt_pk_bf16_f32 v114, v108, v109
	v_or_b32_e32 v108, 16, v150
	v_lshl_add_u64 v[48:49], v[148:149], 0, s[50:51]
	v_addc_co_u32_e32 v51, vcc, 0, v149, vcc
	v_cvt_pk_bf16_f32 v32, v32, v33
	v_cvt_pk_bf16_f32 v33, v34, v35
	v_cvt_pk_bf16_f32 v34, v28, v29
	v_cvt_pk_bf16_f32 v35, v30, v31
	s_mov_b32 s23, 0xa0000
	v_ashrrev_i32_e32 v109, 31, v108
	v_cvt_pk_bf16_f32 v96, v96, v97
	v_cvt_pk_bf16_f32 v97, v98, v99
	v_cvt_pk_bf16_f32 v98, v92, v93
	v_or_b32_e32 v92, 32, v150
	ds_bpermute_b32 v32, v231, v32
	ds_bpermute_b32 v33, v231, v33
	ds_bpermute_b32 v34, v231, v34
	ds_bpermute_b32 v35, v231, v35
	s_waitcnt lgkmcnt(0)
	global_store_dwordx4 v[48:49], v[32:35], off offset:256
	s_mov_b64 s[50:51], 0xa0000
	v_cvt_pk_bf16_f32 v115, v110, v111
	v_add_co_u32_e32 v34, vcc, s23, v148
	v_lshlrev_b64 v[108:109], 12, v[108:109]
	v_ashrrev_i32_e32 v93, 31, v92
	v_cvt_pk_bf16_f32 v80, v80, v81
	v_cvt_pk_bf16_f32 v81, v82, v83
	v_cvt_pk_bf16_f32 v82, v76, v77
	v_or_b32_e32 v76, 48, v150
	v_lshl_add_u64 v[32:33], v[148:149], 0, s[50:51]
	v_addc_co_u32_e32 v35, vcc, 0, v149, vcc
	v_cvt_pk_bf16_f32 v16, v16, v17
	v_cvt_pk_bf16_f32 v17, v18, v19
	v_cvt_pk_bf16_f32 v18, v12, v13
	v_cvt_pk_bf16_f32 v19, v14, v15
	s_mov_b32 s23, 0xb0000
	ds_bpermute_b32 v112, v231, v112
	ds_bpermute_b32 v113, v231, v113
	ds_bpermute_b32 v114, v231, v114
	ds_bpermute_b32 v115, v231, v115
	s_waitcnt lgkmcnt(0)
	global_store_dwordx4 v[148:149], v[112:115], off offset:256
	v_cvt_pk_bf16_f32 v99, v94, v95
	v_lshlrev_b64 v[92:93], 12, v[92:93]
	v_lshl_add_u64 v[112:113], v[146:147], 0, v[108:109]
	v_ashrrev_i32_e32 v77, 31, v76
	ds_bpermute_b32 v16, v231, v16
	ds_bpermute_b32 v17, v231, v17
	ds_bpermute_b32 v18, v231, v18
	ds_bpermute_b32 v19, v231, v19
	s_waitcnt lgkmcnt(0)
	global_store_dwordx4 v[32:33], v[16:19], off offset:256
	ds_bpermute_b32 v96, v231, v96
	ds_bpermute_b32 v97, v231, v97
	ds_bpermute_b32 v98, v231, v98
	ds_bpermute_b32 v99, v231, v99
	s_waitcnt lgkmcnt(0)
	global_store_dwordx4 v[112:113], v[96:99], off offset:256
	v_cvt_pk_bf16_f32 v83, v78, v79
	v_add_co_u32_e32 v18, vcc, s23, v148
	v_lshl_add_u64 v[96:97], v[146:147], 0, v[92:93]
	v_lshlrev_b64 v[76:77], 12, v[76:77]
	s_mov_b64 s[50:51], 0xb0000
	v_addc_co_u32_e32 v19, vcc, 0, v149, vcc
	v_cvt_pk_bf16_f32 v128, v128, v129
	v_cvt_pk_bf16_f32 v129, v130, v131
	v_cvt_pk_bf16_f32 v130, v124, v125
	v_cvt_pk_bf16_f32 v131, v126, v127
	v_cvt_pk_bf16_f32 v108, v120, v121
	v_cvt_pk_bf16_f32 v109, v122, v123
	v_cvt_pk_bf16_f32 v110, v116, v117
	v_cvt_pk_bf16_f32 v111, v118, v119
	v_cvt_pk_bf16_f32 v92, v104, v105
	v_cvt_pk_bf16_f32 v93, v106, v107
	v_cvt_pk_bf16_f32 v94, v100, v101
	v_cvt_pk_bf16_f32 v95, v102, v103
	ds_bpermute_b32 v80, v231, v80
	ds_bpermute_b32 v81, v231, v81
	ds_bpermute_b32 v82, v231, v82
	ds_bpermute_b32 v83, v231, v83
	s_waitcnt lgkmcnt(0)
	global_store_dwordx4 v[96:97], v[80:83], off offset:256
	v_cvt_pk_bf16_f32 v78, v84, v85
	v_cvt_pk_bf16_f32 v79, v86, v87
	v_lshl_add_u64 v[80:81], v[146:147], 0, v[76:77]
	v_cvt_pk_bf16_f32 v76, v88, v89
	v_cvt_pk_bf16_f32 v77, v90, v91
	v_cvt_pk_bf16_f32 v75, v70, v71
	v_cvt_pk_bf16_f32 v67, v62, v63
	v_cvt_pk_bf16_f32 v44, v56, v57
	v_cvt_pk_bf16_f32 v45, v58, v59
	v_cvt_pk_bf16_f32 v46, v52, v53
	v_cvt_pk_bf16_f32 v47, v54, v55
	v_cvt_pk_bf16_f32 v28, v40, v41
	v_cvt_pk_bf16_f32 v29, v42, v43
	v_cvt_pk_bf16_f32 v30, v36, v37
	v_cvt_pk_bf16_f32 v31, v38, v39
	v_lshl_add_u64 v[16:17], v[148:149], 0, s[50:51]
	v_cvt_pk_bf16_f32 v12, v24, v25
	v_cvt_pk_bf16_f32 v13, v26, v27
	v_cvt_pk_bf16_f32 v14, v20, v21
	v_cvt_pk_bf16_f32 v15, v22, v23
	v_cvt_pk_bf16_f32 v8, v8, v9
	v_cvt_pk_bf16_f32 v9, v10, v11
	v_cvt_pk_bf16_f32 v10, v4, v5
	v_cvt_pk_bf16_f32 v11, v6, v7
	s_and_b64 vcc, exec, s[0:1]
	s_mov_b64 s[0:1], -1
	ds_bpermute_b32 v128, v231, v128
	ds_bpermute_b32 v129, v231, v129
	ds_bpermute_b32 v130, v231, v130
	ds_bpermute_b32 v131, v231, v131
	s_waitcnt lgkmcnt(0)
	global_store_dwordx4 v[148:149], v[128:131], off
	ds_bpermute_b32 v108, v231, v108
	ds_bpermute_b32 v109, v231, v109
	ds_bpermute_b32 v110, v231, v110
	ds_bpermute_b32 v111, v231, v111
	s_waitcnt lgkmcnt(0)
	global_store_dwordx4 v[112:113], v[108:111], off
	ds_bpermute_b32 v92, v231, v92
	ds_bpermute_b32 v93, v231, v93
	ds_bpermute_b32 v94, v231, v94
	ds_bpermute_b32 v95, v231, v95
	s_waitcnt lgkmcnt(0)
	global_store_dwordx4 v[96:97], v[92:95], off
	ds_bpermute_b32 v76, v231, v76
	ds_bpermute_b32 v77, v231, v77
	ds_bpermute_b32 v78, v231, v78
	ds_bpermute_b32 v79, v231, v79
	s_waitcnt lgkmcnt(0)
	global_store_dwordx4 v[80:81], v[76:79], off
	ds_bpermute_b32 v72, v231, v72
	ds_bpermute_b32 v73, v231, v73
	ds_bpermute_b32 v74, v231, v74
	ds_bpermute_b32 v75, v231, v75
	s_waitcnt lgkmcnt(0)
	global_store_dwordx4 v[80:81], v[72:75], off offset:256
	ds_bpermute_b32 v64, v231, v64
	ds_bpermute_b32 v65, v231, v65
	ds_bpermute_b32 v66, v231, v66
	ds_bpermute_b32 v67, v231, v67
	s_waitcnt lgkmcnt(0)
	global_store_dwordx4 v[60:61], v[64:67], off
	ds_bpermute_b32 v44, v231, v44
	ds_bpermute_b32 v45, v231, v45
	ds_bpermute_b32 v46, v231, v46
	ds_bpermute_b32 v47, v231, v47
	s_waitcnt lgkmcnt(0)
	global_store_dwordx4 v[50:51], v[44:47], off
	ds_bpermute_b32 v28, v231, v28
	ds_bpermute_b32 v29, v231, v29
	ds_bpermute_b32 v30, v231, v30
	ds_bpermute_b32 v31, v231, v31
	s_waitcnt lgkmcnt(0)
	global_store_dwordx4 v[34:35], v[28:31], off
	ds_bpermute_b32 v12, v231, v12
	ds_bpermute_b32 v13, v231, v13
	ds_bpermute_b32 v14, v231, v14
	ds_bpermute_b32 v15, v231, v15
	s_waitcnt lgkmcnt(0)
	global_store_dwordx4 v[18:19], v[12:15], off
	ds_bpermute_b32 v8, v231, v8
	ds_bpermute_b32 v9, v231, v9
	ds_bpermute_b32 v10, v231, v10
	ds_bpermute_b32 v11, v231, v11
	s_waitcnt lgkmcnt(0)
	global_store_dwordx4 v[16:17], v[8:11], off offset:256
	s_cbranch_vccnz .LBB0_757
	s_andn2_b64 vcc, exec, s[36:37]
	s_cbranch_vccnz .LBB0_756
	s_barrier
	s_branch .LBB0_756
